# phase 6 gate-A/branch-A GEMMs executed inside phase 5 (second resident block runs them before its phase-5 rows, the first after), stash moved to R4/R7, phase 6 runs only sites c,d
# speedup vs baseline: 1.0021x; 1.0021x over previous
.LBB0_391:
	s_cmp_gt_i32 s54, 5
	s_cselect_b64 s[6:7], -1, 0
	s_cmp_lt_i32 s55, 6
	s_cselect_b64 s[8:9], -1, 0
	s_or_b64 s[6:7], s[6:7], s[8:9]
	s_and_b64 vcc, exec, s[6:7]
	s_cbranch_vccnz .LBB0_449
	s_cmp_lt_u32 s2, 0x100
	s_cbranch_scc1 .Lp5_body
	s_branch .Lp5_gemm
.Lp5_body:
	v_lshl_add_u32 v30, s2, 2, v169
	s_movk_i32 s3, 0x4000
	v_cmp_gt_i32_e32 vcc, s3, v30
	s_and_saveexec_b64 s[20:21], vcc
	s_cbranch_execz .LBB0_395
	s_load_dwordx2 s[6:7], s[0:1], 0x50
	v_lshlrev_b32_e32 v0, 3, v168
	v_and_b32_e32 v32, 0x1f8, v0
	v_lshlrev_b32_e32 v16, 2, v32
	s_lshl_b32 s3, s52, 2
	s_waitcnt lgkmcnt(0)
	global_load_dwordx4 v[0:3], v16, s[6:7]
	global_load_dwordx4 v[4:7], v16, s[6:7] offset:16
	global_load_dwordx4 v[8:11], v16, s[6:7] offset:2048
	global_load_dwordx4 v[12:15], v16, s[6:7] offset:2064
	v_mbcnt_lo_u32_b32 v16, -1, 0
	v_mbcnt_hi_u32_b32 v16, -1, v16
	v_and_b32_e32 v18, 64, v16
	v_xor_b32_e32 v17, 1, v16
	v_add_u32_e32 v18, 64, v18
	v_xor_b32_e32 v19, 2, v16
	v_cmp_lt_i32_e32 vcc, v17, v18
	v_xor_b32_e32 v20, 4, v16
	s_load_dwordx4 s[12:15], s[0:1], 0xd8
	s_load_dwordx4 s[16:19], s[0:1], 0xf8
	v_cndmask_b32_e32 v17, v16, v17, vcc
	v_cmp_lt_i32_e32 vcc, v19, v18
	v_xor_b32_e32 v21, 8, v16
	v_xor_b32_e32 v22, 16, v16
	v_cndmask_b32_e32 v19, v16, v19, vcc
	v_cmp_lt_i32_e32 vcc, v20, v18
	s_mov_b64 s[22:23], 0
	s_mov_b32 s24, 0x3b800000
	v_cndmask_b32_e32 v20, v16, v20, vcc
	v_cmp_lt_i32_e32 vcc, v21, v18
	v_mov_b32_e32 v34, 0x358637bd
	s_mov_b32 s25, 0x800000
	v_cndmask_b32_e32 v21, v16, v21, vcc
	v_cmp_lt_i32_e32 vcc, v22, v18
	s_movk_i32 s26, 0x7fff
	s_movk_i32 s27, 0x3fff
	v_cndmask_b32_e32 v16, v16, v22, vcc
	v_lshlrev_b32_e32 v33, 2, v17
	v_lshlrev_b32_e32 v35, 2, v19
	v_lshlrev_b32_e32 v58, 2, v20
	v_lshlrev_b32_e32 v59, 2, v21
	v_lshlrev_b32_e32 v60, 2, v16
	v_mov_b32_e32 v61, 1
	s_waitcnt vmcnt(0)
	v_mov_b32_e32 v36, v1
	v_mov_b32_e32 v37, v3
	v_mov_b32_e32 v1, v2
	v_mov_b32_e32 v2, v5
	v_mov_b32_e32 v3, v7
	v_mov_b32_e32 v5, v6
	v_mov_b32_e32 v6, v9
	v_mov_b32_e32 v7, v11
	v_mov_b32_e32 v9, v10
	v_mov_b32_e32 v10, v13
	v_mov_b32_e32 v11, v15
	v_mov_b32_e32 v13, v14

.LBB0_395:
	s_or_b64 exec, exec, s[20:21]
	s_cmp_lt_u32 s2, 0x100
	s_cbranch_scc0 .Lp5_done
.Lp5_gemm:
	s_cmp_eq_u32 s52, 0x200
	s_cbranch_scc0 .Lp5_gemm_end
	s_lshr_b32 s81, s2, 3
	s_mov_b32 s80, 64
	s_movk_i32 s82, 0x80
	s_and_b32 s79, s2, 7
	s_lshl_b32 s79, s79, 4
	s_mov_b64 s[36:37], 0
	s_cmp_lg_u64 s[36:37], 0
	s_cbranch_scc1 .Lp5g_lin
	s_lshr_b32 s71, s81, 6
	s_and_b32 s72, s81, 63
	s_lshr_b32 s74, s72, 3
	s_and_b32 s72, s72, 7
	s_lshl_b32 s70, s71, 3
	s_add_u32 s70, s70, s79
	s_add_u32 s70, s70, s72
	s_branch .Lp5g_dec

.Lp5g_dec:
	s_load_dwordx2 s[22:23], s[0:1], 0x60
	s_load_dwordx2 s[24:25], s[0:1], 0xf0
	s_load_dwordx2 s[34:35], s[0:1], 0x108
	s_load_dwordx2 s[26:27], s[0:1], 0xd8
	s_mov_b32 s3, 0x7fff
	v_mov_b32_e32 v242, 1
	v_lshlrev_b32_e32 v243, 4, v168
	v_bfe_u32 v249, v168, 6, 1
	v_bfe_u32 v250, v168, 4, 2
	v_lshlrev_b32_e32 v250, 4, v250
	v_lshl_or_b32 v244, v249, 8, v250
	s_lshl_b32 s71, s74, 9
	s_and_b32 s72, s2, 7
	s_lshl_b32 s72, s72, 22
	s_lshr_b32 s73, s2, 3
	s_lshl_b32 s73, s73, 16
	s_add_u32 s72, s72, s73
	s_lshl_b32 s73, s2, 16
	s_waitcnt lgkmcnt(0)
	s_add_u32 s22, s22, s71
	s_addc_u32 s23, s23, 0
	s_add_u32 s24, s24, s72
	s_addc_u32 s25, s25, 0
	s_add_u32 s34, s34, s73
	s_addc_u32 s35, s35, 0
.Lp5g_site_a:
	v_and_b32_e32 v236, 15, v168
	v_lshrrev_b32_e32 v237, 1, v236
	v_bfe_u32 v238, v168, 4, 2
	v_xor_b32_e32 v237, v237, v238
	v_lshlrev_b32_e32 v237, 4, v237
	v_lshl_or_b32 v236, v236, 7, v237
	v_xor_b32_e32 v237, 64, v236
	v_add_u32_e32 v236, 16, v236
	v_add_u32_e32 v237, 16, v237
	v_bfe_u32 v238, v168, 7, 1
	v_lshl_add_u32 v240, v238, 13, v237
	v_lshl_add_u32 v238, v238, 13, v236
	v_bfe_u32 v239, v168, 6, 1
	v_lshl_add_u32 v241, v239, 13, v237
	v_lshl_add_u32 v239, v239, 13, v236
	v_lshrrev_b32_e32 v236, 3, v168
	v_lshrrev_b32_e32 v237, 4, v168
	v_xor_b32_e32 v237, v237, v168
	v_and_b32_e32 v237, 7, v237
	v_lshlrev_b32_e32 v237, 4, v237
	v_lshl_or_b32 v232, v236, 11, v237
	v_add_u32_e32 v233, 0x10000, v232
	v_add_u32_e32 v234, 0x20000, v232
	v_add_u32_e32 v235, 0x30000, v232
	s_load_dwordx2 s[90:91], s[0:1], 0xa0
	s_load_dwordx2 s[92:93], s[0:1], 0xa8
	v_lshrrev_b32_e32 v237, 6, v168
	s_nop 1
	v_readfirstlane_b32 s97, v237
	s_nop 3
	s_lshl_b32 s96, s97, 10
	s_add_u32 s96, s96, 16
	s_add_u32 s94, s81, s80
	s_cmp_lt_i32 s94, s82
	s_cselect_b32 s95, 1, 0
	s_cmp_lg_u64 s[36:37], 0
	s_cselect_b32 s95, 0, s95
	s_cmp_ge_u32 s94, 0x40
	s_cselect_b32 s97, 1, 0
	s_mul_i32 s100, s97, 0x40
	s_sub_u32 s100, s94, s100
	s_lshr_b32 s101, s100, 3
	s_and_b32 s100, s100, 7
	s_lshl_b32 s97, s97, 3
	s_add_u32 s100, s100, s97
	s_add_u32 s100, s100, s79
	s_cmp_lg_u32 s101, s74
	s_cselect_b32 s95, 0, s95
	s_cmp_eq_u32 s95, 1
	s_cselect_b32 s101, s100, s70
	s_mov_b32 s97, s101
	s_waitcnt lgkmcnt(0)
	s_lshl_b32 s94, s74, 18
	s_add_u32 s94, s94, 0xc40000
	s_add_u32 s98, s92, s94
	s_addc_u32 s99, s93, 0
	s_lshl_b32 s101, s101, 18
	s_add_u32 s92, s90, s101
	s_addc_u32 s93, s91, 0
	s_lshl_b32 s94, s70, 18
	s_add_u32 s90, s90, s94
	s_addc_u32 s91, s91, 0
	s_mov_b64 s[100:101], s[90:91]
	s_mov_b64 s[90:91], s[98:99]
	s_mov_b64 s[98:99], s[92:93]
	s_mov_b64 s[92:93], s[100:101]
	s_waitcnt vmcnt(0)
	s_barrier
	s_add_u32 m0, s96, 0x0
	s_nop 0
	global_load_lds_dwordx4 v232, s[90:91]
	s_add_u32 m0, s96, 0x1000
	s_nop 0
	global_load_lds_dwordx4 v233, s[90:91]
	s_add_u32 m0, s96, 0x2000
	s_nop 0
	global_load_lds_dwordx4 v234, s[90:91]
	s_add_u32 m0, s96, 0x3000
	s_nop 0
	global_load_lds_dwordx4 v235, s[90:91]
	s_add_u32 m0, s96, 0x8000
	s_nop 0
	global_load_lds_dwordx4 v232, s[92:93]
	s_add_u32 m0, s96, 0x9000
	s_nop 0
	global_load_lds_dwordx4 v233, s[92:93]
	s_add_u32 m0, s96, 0xa000
	s_nop 0
	global_load_lds_dwordx4 v234, s[92:93]
	s_add_u32 m0, s96, 0xb000
	s_nop 0
	global_load_lds_dwordx4 v235, s[92:93]
	s_add_u32 m0, s96, 0xc000
	s_nop 0
	global_load_lds_dwordx4 v232, s[98:99]
	s_add_u32 m0, s96, 0xd000
	s_nop 0
	global_load_lds_dwordx4 v233, s[98:99]
	s_add_u32 m0, s96, 0xe000
	s_nop 0
	global_load_lds_dwordx4 v234, s[98:99]
	s_add_u32 m0, s96, 0xf000
	s_nop 0
	global_load_lds_dwordx4 v235, s[98:99]
	s_add_u32 s90, s90, 0x80
	s_addc_u32 s91, s91, 0
	s_add_u32 s92, s92, 0x80
	s_addc_u32 s93, s93, 0
	s_add_u32 s98, s98, 0x80
	s_addc_u32 s99, s99, 0
	v_mov_b32_e32 v0, 0
	v_mov_b32_e32 v1, v0
	v_mov_b32_e32 v2, v0
	v_mov_b32_e32 v3, v0
	v_mov_b32_e32 v4, v0
	v_mov_b32_e32 v5, v0
	v_mov_b32_e32 v6, v0
	v_mov_b32_e32 v7, v0
	v_mov_b32_e32 v8, v0
	v_mov_b32_e32 v9, v0
	v_mov_b32_e32 v10, v0
	v_mov_b32_e32 v11, v0
	v_mov_b32_e32 v12, v0
	v_mov_b32_e32 v13, v0
	v_mov_b32_e32 v14, v0
	v_mov_b32_e32 v15, v0
	v_mov_b32_e32 v16, v0
	v_mov_b32_e32 v17, v0
	v_mov_b32_e32 v18, v0
	v_mov_b32_e32 v19, v0
	v_mov_b32_e32 v20, v0
	v_mov_b32_e32 v21, v0
	v_mov_b32_e32 v22, v0
	v_mov_b32_e32 v23, v0
	v_mov_b32_e32 v24, v0
	v_mov_b32_e32 v25, v0
	v_mov_b32_e32 v26, v0
	v_mov_b32_e32 v27, v0
	v_mov_b32_e32 v28, v0
	v_mov_b32_e32 v29, v0
	v_mov_b32_e32 v30, v0
	v_mov_b32_e32 v31, v0
	v_mov_b32_e32 v32, v0
	v_mov_b32_e32 v33, v0
	v_mov_b32_e32 v34, v0
	v_mov_b32_e32 v35, v0
	v_mov_b32_e32 v36, v0
	v_mov_b32_e32 v37, v0
	v_mov_b32_e32 v38, v0
	v_mov_b32_e32 v39, v0
	v_mov_b32_e32 v40, v0
	v_mov_b32_e32 v41, v0
	v_mov_b32_e32 v42, v0
	v_mov_b32_e32 v43, v0
	v_mov_b32_e32 v44, v0
	v_mov_b32_e32 v45, v0
	v_mov_b32_e32 v46, v0
	v_mov_b32_e32 v47, v0
	v_mov_b32_e32 v48, v0
	v_mov_b32_e32 v49, v0
	v_mov_b32_e32 v50, v0
	v_mov_b32_e32 v51, v0
	v_mov_b32_e32 v52, v0
	v_mov_b32_e32 v53, v0
	v_mov_b32_e32 v54, v0
	v_mov_b32_e32 v55, v0
	v_mov_b32_e32 v56, v0
	v_mov_b32_e32 v57, v0
	v_mov_b32_e32 v58, v0
	v_mov_b32_e32 v59, v0
	v_mov_b32_e32 v60, v0
	v_mov_b32_e32 v61, v0
	v_mov_b32_e32 v62, v0
	v_mov_b32_e32 v63, v0
	v_mov_b32_e32 v64, v0
	v_mov_b32_e32 v65, v0
	v_mov_b32_e32 v66, v0
	v_mov_b32_e32 v67, v0
	v_mov_b32_e32 v68, v0
	v_mov_b32_e32 v69, v0
	v_mov_b32_e32 v70, v0
	v_mov_b32_e32 v71, v0
	v_mov_b32_e32 v72, v0
	v_mov_b32_e32 v73, v0
	v_mov_b32_e32 v74, v0
	v_mov_b32_e32 v75, v0
	v_mov_b32_e32 v76, v0
	v_mov_b32_e32 v77, v0
	v_mov_b32_e32 v78, v0
	v_mov_b32_e32 v79, v0
	v_mov_b32_e32 v80, v0
	v_mov_b32_e32 v81, v0
	v_mov_b32_e32 v82, v0
	v_mov_b32_e32 v83, v0
	v_mov_b32_e32 v84, v0
	v_mov_b32_e32 v85, v0
	v_mov_b32_e32 v86, v0
	v_mov_b32_e32 v87, v0
	v_mov_b32_e32 v88, v0
	v_mov_b32_e32 v89, v0
	v_mov_b32_e32 v90, v0
	v_mov_b32_e32 v91, v0
	v_mov_b32_e32 v92, v0
	v_mov_b32_e32 v93, v0
	v_mov_b32_e32 v94, v0
	v_mov_b32_e32 v95, v0
	v_mov_b32_e32 v96, v0
	v_mov_b32_e32 v97, v0
	v_mov_b32_e32 v98, v0
	v_mov_b32_e32 v99, v0
	v_mov_b32_e32 v100, v0
	v_mov_b32_e32 v101, v0
	v_mov_b32_e32 v102, v0
	v_mov_b32_e32 v103, v0
	v_mov_b32_e32 v104, v0
	v_mov_b32_e32 v105, v0
	v_mov_b32_e32 v106, v0
	v_mov_b32_e32 v107, v0
	v_mov_b32_e32 v108, v0
	v_mov_b32_e32 v109, v0
	v_mov_b32_e32 v110, v0
	v_mov_b32_e32 v111, v0
	v_mov_b32_e32 v112, v0
	v_mov_b32_e32 v113, v0
	v_mov_b32_e32 v114, v0
	v_mov_b32_e32 v115, v0
	v_mov_b32_e32 v116, v0
	v_mov_b32_e32 v117, v0
	v_mov_b32_e32 v118, v0
	v_mov_b32_e32 v119, v0
	v_mov_b32_e32 v120, v0
	v_mov_b32_e32 v121, v0
	v_mov_b32_e32 v122, v0
	v_mov_b32_e32 v123, v0
	v_mov_b32_e32 v124, v0
	v_mov_b32_e32 v125, v0
	v_mov_b32_e32 v126, v0
	v_mov_b32_e32 v127, v0
	s_mov_b32 s94, 0

.Lp5ga_ep:
	global_load_dwordx4 v[128:131], v244, s[22:23]
	global_load_dwordx4 v[132:135], v244, s[22:23] offset:64
	global_load_dwordx4 v[136:139], v244, s[22:23] offset:128
	global_load_dwordx4 v[140:143], v244, s[22:23] offset:192
	s_cmp_eq_u32 s83, 1
	s_cselect_b32 s84, s34, s24
	s_cselect_b32 s85, s35, s25
	s_waitcnt vmcnt(0)
	v_add_f32_e32 v148, v0, v128
	v_add_f32_e32 v149, v1, v129
	v_add_f32_e32 v150, v2, v130
	v_add_f32_e32 v151, v3, v131
	v_add_f32_e32 v152, v4, v132
	v_add_f32_e32 v153, v5, v133
	v_add_f32_e32 v154, v6, v134
	v_add_f32_e32 v155, v7, v135
	v_mul_f32_e32 v148, 0xbfb8aa3b, v148
	v_mul_f32_e32 v149, 0xbfb8aa3b, v149
	v_mul_f32_e32 v150, 0xbfb8aa3b, v150
	v_mul_f32_e32 v151, 0xbfb8aa3b, v151
	v_mul_f32_e32 v152, 0xbfb8aa3b, v152
	v_mul_f32_e32 v153, 0xbfb8aa3b, v153
	v_mul_f32_e32 v154, 0xbfb8aa3b, v154
	v_mul_f32_e32 v155, 0xbfb8aa3b, v155
	v_exp_f32_e32 v156, v148
	v_exp_f32_e32 v157, v149
	v_exp_f32_e32 v158, v150
	v_exp_f32_e32 v159, v151
	v_exp_f32_e32 v160, v152
	v_exp_f32_e32 v161, v153
	v_exp_f32_e32 v162, v154
	v_exp_f32_e32 v163, v155
	v_add_f32_e32 v156, 1.0, v156
	v_add_f32_e32 v157, 1.0, v157
	v_add_f32_e32 v158, 1.0, v158
	v_add_f32_e32 v159, 1.0, v159
	v_add_f32_e32 v160, 1.0, v160
	v_add_f32_e32 v161, 1.0, v161
	v_add_f32_e32 v162, 1.0, v162
	v_add_f32_e32 v163, 1.0, v163
	v_div_scale_f32 v164, s[76:77], v156, v156, 1.0
	v_div_scale_f32 v165, s[76:77], v157, v157, 1.0
	v_div_scale_f32 v166, s[76:77], v158, v158, 1.0
	v_div_scale_f32 v167, s[76:77], v159, v159, 1.0
	v_div_scale_f32 v172, s[76:77], v160, v160, 1.0
	v_div_scale_f32 v173, s[76:77], v161, v161, 1.0
	v_div_scale_f32 v174, s[76:77], v162, v162, 1.0
	v_div_scale_f32 v175, s[76:77], v163, v163, 1.0
	v_rcp_f32_e32 v176, v164
	v_rcp_f32_e32 v177, v165
	v_rcp_f32_e32 v178, v166
	v_rcp_f32_e32 v179, v167
	v_rcp_f32_e32 v180, v172
	v_rcp_f32_e32 v181, v173
	v_rcp_f32_e32 v182, v174
	v_rcp_f32_e32 v183, v175
	v_fma_f32 v148, -v164, v176, 1.0
	v_fma_f32 v149, -v165, v177, 1.0
	v_fma_f32 v150, -v166, v178, 1.0
	v_fma_f32 v151, -v167, v179, 1.0
	v_fma_f32 v152, -v172, v180, 1.0
	v_fma_f32 v153, -v173, v181, 1.0
	v_fma_f32 v154, -v174, v182, 1.0
	v_fma_f32 v155, -v175, v183, 1.0
	v_fmac_f32_e32 v176, v148, v176
	v_fmac_f32_e32 v177, v149, v177
	v_fmac_f32_e32 v178, v150, v178
	v_fmac_f32_e32 v179, v151, v179
	v_fmac_f32_e32 v180, v152, v180
	v_fmac_f32_e32 v181, v153, v181
	v_fmac_f32_e32 v182, v154, v182
	v_fmac_f32_e32 v183, v155, v183
	v_div_scale_f32 v184, vcc, 1.0, v156, 1.0
	v_mul_f32_e32 v192, v184, v176
	v_fma_f32 v148, -v164, v192, v184
	v_fmac_f32_e32 v192, v148, v176
	v_fma_f32 v184, -v164, v192, v184
	v_div_fmas_f32 v184, v184, v176, v192
	v_div_fixup_f32 v148, v184, v156, 1.0
	v_div_scale_f32 v185, vcc, 1.0, v157, 1.0
	v_mul_f32_e32 v193, v185, v177
	v_fma_f32 v149, -v165, v193, v185
	v_fmac_f32_e32 v193, v149, v177
	v_fma_f32 v185, -v165, v193, v185
	v_div_fmas_f32 v185, v185, v177, v193
	v_div_fixup_f32 v149, v185, v157, 1.0
	v_div_scale_f32 v186, vcc, 1.0, v158, 1.0
	v_mul_f32_e32 v194, v186, v178
	v_fma_f32 v150, -v166, v194, v186
	v_fmac_f32_e32 v194, v150, v178
	v_fma_f32 v186, -v166, v194, v186
	v_div_fmas_f32 v186, v186, v178, v194
	v_div_fixup_f32 v150, v186, v158, 1.0
	v_div_scale_f32 v187, vcc, 1.0, v159, 1.0
	v_mul_f32_e32 v195, v187, v179
	v_fma_f32 v151, -v167, v195, v187
	v_fmac_f32_e32 v195, v151, v179
	v_fma_f32 v187, -v167, v195, v187
	v_div_fmas_f32 v187, v187, v179, v195
	v_div_fixup_f32 v151, v187, v159, 1.0
	v_div_scale_f32 v188, vcc, 1.0, v160, 1.0
	v_mul_f32_e32 v196, v188, v180
	v_fma_f32 v152, -v172, v196, v188
	v_fmac_f32_e32 v196, v152, v180
	v_fma_f32 v188, -v172, v196, v188
	v_div_fmas_f32 v188, v188, v180, v196
	v_div_fixup_f32 v152, v188, v160, 1.0
	v_div_scale_f32 v189, vcc, 1.0, v161, 1.0
	v_mul_f32_e32 v197, v189, v181
	v_fma_f32 v153, -v173, v197, v189
	v_fmac_f32_e32 v197, v153, v181
	v_fma_f32 v189, -v173, v197, v189
	v_div_fmas_f32 v189, v189, v181, v197
	v_div_fixup_f32 v153, v189, v161, 1.0
	v_div_scale_f32 v190, vcc, 1.0, v162, 1.0
	v_mul_f32_e32 v198, v190, v182
	v_fma_f32 v154, -v174, v198, v190
	v_fmac_f32_e32 v198, v154, v182
	v_fma_f32 v190, -v174, v198, v190
	v_div_fmas_f32 v190, v190, v182, v198
	v_div_fixup_f32 v154, v190, v162, 1.0
	v_div_scale_f32 v191, vcc, 1.0, v163, 1.0
	v_mul_f32_e32 v199, v191, v183
	v_fma_f32 v155, -v175, v199, v191
	v_fmac_f32_e32 v199, v155, v183
	v_fma_f32 v191, -v175, v199, v191
	v_div_fmas_f32 v191, v191, v183, v199
	v_div_fixup_f32 v155, v191, v163, 1.0
	v_cvt_pk_bf16_f32 v200, v148, v149
	v_cvt_pk_bf16_f32 v201, v150, v151
	v_cvt_pk_bf16_f32 v202, v152, v153
	v_cvt_pk_bf16_f32 v203, v154, v155
	global_store_dwordx4 v243, v[200:203], s[84:85]
	s_add_u32 s84, s84, 0x1000
	s_addc_u32 s85, s85, 0
	v_add_f32_e32 v148, v8, v136
	v_add_f32_e32 v149, v9, v137
	v_add_f32_e32 v150, v10, v138
	v_add_f32_e32 v151, v11, v139
	v_add_f32_e32 v152, v12, v140
	v_add_f32_e32 v153, v13, v141
	v_add_f32_e32 v154, v14, v142
	v_add_f32_e32 v155, v15, v143
	v_mul_f32_e32 v148, 0xbfb8aa3b, v148
	v_mul_f32_e32 v149, 0xbfb8aa3b, v149
	v_mul_f32_e32 v150, 0xbfb8aa3b, v150
	v_mul_f32_e32 v151, 0xbfb8aa3b, v151
	v_mul_f32_e32 v152, 0xbfb8aa3b, v152
	v_mul_f32_e32 v153, 0xbfb8aa3b, v153
	v_mul_f32_e32 v154, 0xbfb8aa3b, v154
	v_mul_f32_e32 v155, 0xbfb8aa3b, v155
	v_exp_f32_e32 v156, v148
	v_exp_f32_e32 v157, v149
	v_exp_f32_e32 v158, v150
	v_exp_f32_e32 v159, v151
	v_exp_f32_e32 v160, v152
	v_exp_f32_e32 v161, v153
	v_exp_f32_e32 v162, v154
	v_exp_f32_e32 v163, v155
	v_add_f32_e32 v156, 1.0, v156
	v_add_f32_e32 v157, 1.0, v157
	v_add_f32_e32 v158, 1.0, v158
	v_add_f32_e32 v159, 1.0, v159
	v_add_f32_e32 v160, 1.0, v160
	v_add_f32_e32 v161, 1.0, v161
	v_add_f32_e32 v162, 1.0, v162
	v_add_f32_e32 v163, 1.0, v163
	v_div_scale_f32 v164, s[76:77], v156, v156, 1.0
	v_div_scale_f32 v165, s[76:77], v157, v157, 1.0
	v_div_scale_f32 v166, s[76:77], v158, v158, 1.0
	v_div_scale_f32 v167, s[76:77], v159, v159, 1.0
	v_div_scale_f32 v172, s[76:77], v160, v160, 1.0
	v_div_scale_f32 v173, s[76:77], v161, v161, 1.0
	v_div_scale_f32 v174, s[76:77], v162, v162, 1.0
	v_div_scale_f32 v175, s[76:77], v163, v163, 1.0
	v_rcp_f32_e32 v176, v164
	v_rcp_f32_e32 v177, v165
	v_rcp_f32_e32 v178, v166
	v_rcp_f32_e32 v179, v167
	v_rcp_f32_e32 v180, v172
	v_rcp_f32_e32 v181, v173
	v_rcp_f32_e32 v182, v174
	v_rcp_f32_e32 v183, v175
	v_fma_f32 v148, -v164, v176, 1.0
	v_fma_f32 v149, -v165, v177, 1.0
	v_fma_f32 v150, -v166, v178, 1.0
	v_fma_f32 v151, -v167, v179, 1.0
	v_fma_f32 v152, -v172, v180, 1.0
	v_fma_f32 v153, -v173, v181, 1.0
	v_fma_f32 v154, -v174, v182, 1.0
	v_fma_f32 v155, -v175, v183, 1.0
	v_fmac_f32_e32 v176, v148, v176
	v_fmac_f32_e32 v177, v149, v177
	v_fmac_f32_e32 v178, v150, v178
	v_fmac_f32_e32 v179, v151, v179
	v_fmac_f32_e32 v180, v152, v180
	v_fmac_f32_e32 v181, v153, v181
	v_fmac_f32_e32 v182, v154, v182
	v_fmac_f32_e32 v183, v155, v183
	v_div_scale_f32 v184, vcc, 1.0, v156, 1.0
	v_mul_f32_e32 v192, v184, v176
	v_fma_f32 v148, -v164, v192, v184
	v_fmac_f32_e32 v192, v148, v176
	v_fma_f32 v184, -v164, v192, v184
	v_div_fmas_f32 v184, v184, v176, v192
	v_div_fixup_f32 v148, v184, v156, 1.0
	v_div_scale_f32 v185, vcc, 1.0, v157, 1.0
	v_mul_f32_e32 v193, v185, v177
	v_fma_f32 v149, -v165, v193, v185
	v_fmac_f32_e32 v193, v149, v177
	v_fma_f32 v185, -v165, v193, v185
	v_div_fmas_f32 v185, v185, v177, v193
	v_div_fixup_f32 v149, v185, v157, 1.0
	v_div_scale_f32 v186, vcc, 1.0, v158, 1.0
	v_mul_f32_e32 v194, v186, v178
	v_fma_f32 v150, -v166, v194, v186
	v_fmac_f32_e32 v194, v150, v178
	v_fma_f32 v186, -v166, v194, v186
	v_div_fmas_f32 v186, v186, v178, v194
	v_div_fixup_f32 v150, v186, v158, 1.0
	v_div_scale_f32 v187, vcc, 1.0, v159, 1.0
	v_mul_f32_e32 v195, v187, v179
	v_fma_f32 v151, -v167, v195, v187
	v_fmac_f32_e32 v195, v151, v179
	v_fma_f32 v187, -v167, v195, v187
	v_div_fmas_f32 v187, v187, v179, v195
	v_div_fixup_f32 v151, v187, v159, 1.0
	v_div_scale_f32 v188, vcc, 1.0, v160, 1.0
	v_mul_f32_e32 v196, v188, v180
	v_fma_f32 v152, -v172, v196, v188
	v_fmac_f32_e32 v196, v152, v180
	v_fma_f32 v188, -v172, v196, v188
	v_div_fmas_f32 v188, v188, v180, v196
	v_div_fixup_f32 v152, v188, v160, 1.0
	v_div_scale_f32 v189, vcc, 1.0, v161, 1.0
	v_mul_f32_e32 v197, v189, v181
	v_fma_f32 v153, -v173, v197, v189
	v_fmac_f32_e32 v197, v153, v181
	v_fma_f32 v189, -v173, v197, v189
	v_div_fmas_f32 v189, v189, v181, v197
	v_div_fixup_f32 v153, v189, v161, 1.0
	v_div_scale_f32 v190, vcc, 1.0, v162, 1.0
	v_mul_f32_e32 v198, v190, v182
	v_fma_f32 v154, -v174, v198, v190
	v_fmac_f32_e32 v198, v154, v182
	v_fma_f32 v190, -v174, v198, v190
	v_div_fmas_f32 v190, v190, v182, v198
	v_div_fixup_f32 v154, v190, v162, 1.0
	v_div_scale_f32 v191, vcc, 1.0, v163, 1.0
	v_mul_f32_e32 v199, v191, v183
	v_fma_f32 v155, -v175, v199, v191
	v_fmac_f32_e32 v199, v155, v183
	v_fma_f32 v191, -v175, v199, v191
	v_div_fmas_f32 v191, v191, v183, v199
	v_div_fixup_f32 v155, v191, v163, 1.0
	v_cvt_pk_bf16_f32 v204, v148, v149
	v_cvt_pk_bf16_f32 v205, v150, v151
	v_cvt_pk_bf16_f32 v206, v152, v153
	v_cvt_pk_bf16_f32 v207, v154, v155
	global_store_dwordx4 v243, v[204:207], s[84:85]
	s_add_u32 s84, s84, 0x1000
	s_addc_u32 s85, s85, 0
	v_add_f32_e32 v148, v16, v128
	v_add_f32_e32 v149, v17, v129
	v_add_f32_e32 v150, v18, v130
	v_add_f32_e32 v151, v19, v131
	v_add_f32_e32 v152, v20, v132
	v_add_f32_e32 v153, v21, v133
	v_add_f32_e32 v154, v22, v134
	v_add_f32_e32 v155, v23, v135
	v_mul_f32_e32 v148, 0xbfb8aa3b, v148
	v_mul_f32_e32 v149, 0xbfb8aa3b, v149
	v_mul_f32_e32 v150, 0xbfb8aa3b, v150
	v_mul_f32_e32 v151, 0xbfb8aa3b, v151
	v_mul_f32_e32 v152, 0xbfb8aa3b, v152
	v_mul_f32_e32 v153, 0xbfb8aa3b, v153
	v_mul_f32_e32 v154, 0xbfb8aa3b, v154
	v_mul_f32_e32 v155, 0xbfb8aa3b, v155
	v_exp_f32_e32 v156, v148
	v_exp_f32_e32 v157, v149
	v_exp_f32_e32 v158, v150
	v_exp_f32_e32 v159, v151
	v_exp_f32_e32 v160, v152
	v_exp_f32_e32 v161, v153
	v_exp_f32_e32 v162, v154
	v_exp_f32_e32 v163, v155
	v_add_f32_e32 v156, 1.0, v156
	v_add_f32_e32 v157, 1.0, v157
	v_add_f32_e32 v158, 1.0, v158
	v_add_f32_e32 v159, 1.0, v159
	v_add_f32_e32 v160, 1.0, v160
	v_add_f32_e32 v161, 1.0, v161
	v_add_f32_e32 v162, 1.0, v162
	v_add_f32_e32 v163, 1.0, v163
	v_div_scale_f32 v164, s[76:77], v156, v156, 1.0
	v_div_scale_f32 v165, s[76:77], v157, v157, 1.0
	v_div_scale_f32 v166, s[76:77], v158, v158, 1.0
	v_div_scale_f32 v167, s[76:77], v159, v159, 1.0
	v_div_scale_f32 v172, s[76:77], v160, v160, 1.0
	v_div_scale_f32 v173, s[76:77], v161, v161, 1.0
	v_div_scale_f32 v174, s[76:77], v162, v162, 1.0
	v_div_scale_f32 v175, s[76:77], v163, v163, 1.0
	v_rcp_f32_e32 v176, v164
	v_rcp_f32_e32 v177, v165
	v_rcp_f32_e32 v178, v166
	v_rcp_f32_e32 v179, v167
	v_rcp_f32_e32 v180, v172
	v_rcp_f32_e32 v181, v173
	v_rcp_f32_e32 v182, v174
	v_rcp_f32_e32 v183, v175
	v_fma_f32 v148, -v164, v176, 1.0
	v_fma_f32 v149, -v165, v177, 1.0
	v_fma_f32 v150, -v166, v178, 1.0
	v_fma_f32 v151, -v167, v179, 1.0
	v_fma_f32 v152, -v172, v180, 1.0
	v_fma_f32 v153, -v173, v181, 1.0
	v_fma_f32 v154, -v174, v182, 1.0
	v_fma_f32 v155, -v175, v183, 1.0
	v_fmac_f32_e32 v176, v148, v176
	v_fmac_f32_e32 v177, v149, v177
	v_fmac_f32_e32 v178, v150, v178
	v_fmac_f32_e32 v179, v151, v179
	v_fmac_f32_e32 v180, v152, v180
	v_fmac_f32_e32 v181, v153, v181
	v_fmac_f32_e32 v182, v154, v182
	v_fmac_f32_e32 v183, v155, v183
	v_div_scale_f32 v184, vcc, 1.0, v156, 1.0
	v_mul_f32_e32 v192, v184, v176
	v_fma_f32 v148, -v164, v192, v184
	v_fmac_f32_e32 v192, v148, v176
	v_fma_f32 v184, -v164, v192, v184
	v_div_fmas_f32 v184, v184, v176, v192
	v_div_fixup_f32 v148, v184, v156, 1.0
	v_div_scale_f32 v185, vcc, 1.0, v157, 1.0
	v_mul_f32_e32 v193, v185, v177
	v_fma_f32 v149, -v165, v193, v185
	v_fmac_f32_e32 v193, v149, v177
	v_fma_f32 v185, -v165, v193, v185
	v_div_fmas_f32 v185, v185, v177, v193
	v_div_fixup_f32 v149, v185, v157, 1.0
	v_div_scale_f32 v186, vcc, 1.0, v158, 1.0
	v_mul_f32_e32 v194, v186, v178
	v_fma_f32 v150, -v166, v194, v186
	v_fmac_f32_e32 v194, v150, v178
	v_fma_f32 v186, -v166, v194, v186
	v_div_fmas_f32 v186, v186, v178, v194
	v_div_fixup_f32 v150, v186, v158, 1.0
	v_div_scale_f32 v187, vcc, 1.0, v159, 1.0
	v_mul_f32_e32 v195, v187, v179
	v_fma_f32 v151, -v167, v195, v187
	v_fmac_f32_e32 v195, v151, v179
	v_fma_f32 v187, -v167, v195, v187
	v_div_fmas_f32 v187, v187, v179, v195
	v_div_fixup_f32 v151, v187, v159, 1.0
	v_div_scale_f32 v188, vcc, 1.0, v160, 1.0
	v_mul_f32_e32 v196, v188, v180
	v_fma_f32 v152, -v172, v196, v188
	v_fmac_f32_e32 v196, v152, v180
	v_fma_f32 v188, -v172, v196, v188
	v_div_fmas_f32 v188, v188, v180, v196
	v_div_fixup_f32 v152, v188, v160, 1.0
	v_div_scale_f32 v189, vcc, 1.0, v161, 1.0
	v_mul_f32_e32 v197, v189, v181
	v_fma_f32 v153, -v173, v197, v189
	v_fmac_f32_e32 v197, v153, v181
	v_fma_f32 v189, -v173, v197, v189
	v_div_fmas_f32 v189, v189, v181, v197
	v_div_fixup_f32 v153, v189, v161, 1.0
	v_div_scale_f32 v190, vcc, 1.0, v162, 1.0
	v_mul_f32_e32 v198, v190, v182
	v_fma_f32 v154, -v174, v198, v190
	v_fmac_f32_e32 v198, v154, v182
	v_fma_f32 v190, -v174, v198, v190
	v_div_fmas_f32 v190, v190, v182, v198
	v_div_fixup_f32 v154, v190, v162, 1.0
	v_div_scale_f32 v191, vcc, 1.0, v163, 1.0
	v_mul_f32_e32 v199, v191, v183
	v_fma_f32 v155, -v175, v199, v191
	v_fmac_f32_e32 v199, v155, v183
	v_fma_f32 v191, -v175, v199, v191
	v_div_fmas_f32 v191, v191, v183, v199
	v_div_fixup_f32 v155, v191, v163, 1.0
	v_cvt_pk_bf16_f32 v200, v148, v149
	v_cvt_pk_bf16_f32 v201, v150, v151
	v_cvt_pk_bf16_f32 v202, v152, v153
	v_cvt_pk_bf16_f32 v203, v154, v155
	global_store_dwordx4 v243, v[200:203], s[84:85]
	s_add_u32 s84, s84, 0x1000
	s_addc_u32 s85, s85, 0
	v_add_f32_e32 v148, v24, v136
	v_add_f32_e32 v149, v25, v137
	v_add_f32_e32 v150, v26, v138
	v_add_f32_e32 v151, v27, v139
	v_add_f32_e32 v152, v28, v140
	v_add_f32_e32 v153, v29, v141
	v_add_f32_e32 v154, v30, v142
	v_add_f32_e32 v155, v31, v143
	v_mul_f32_e32 v148, 0xbfb8aa3b, v148
	v_mul_f32_e32 v149, 0xbfb8aa3b, v149
	v_mul_f32_e32 v150, 0xbfb8aa3b, v150
	v_mul_f32_e32 v151, 0xbfb8aa3b, v151
	v_mul_f32_e32 v152, 0xbfb8aa3b, v152
	v_mul_f32_e32 v153, 0xbfb8aa3b, v153
	v_mul_f32_e32 v154, 0xbfb8aa3b, v154
	v_mul_f32_e32 v155, 0xbfb8aa3b, v155
	v_exp_f32_e32 v156, v148
	v_exp_f32_e32 v157, v149
	v_exp_f32_e32 v158, v150
	v_exp_f32_e32 v159, v151
	v_exp_f32_e32 v160, v152
	v_exp_f32_e32 v161, v153
	v_exp_f32_e32 v162, v154
	v_exp_f32_e32 v163, v155
	v_add_f32_e32 v156, 1.0, v156
	v_add_f32_e32 v157, 1.0, v157
	v_add_f32_e32 v158, 1.0, v158
	v_add_f32_e32 v159, 1.0, v159
	v_add_f32_e32 v160, 1.0, v160
	v_add_f32_e32 v161, 1.0, v161
	v_add_f32_e32 v162, 1.0, v162
	v_add_f32_e32 v163, 1.0, v163
	v_div_scale_f32 v164, s[76:77], v156, v156, 1.0
	v_div_scale_f32 v165, s[76:77], v157, v157, 1.0
	v_div_scale_f32 v166, s[76:77], v158, v158, 1.0
	v_div_scale_f32 v167, s[76:77], v159, v159, 1.0
	v_div_scale_f32 v172, s[76:77], v160, v160, 1.0
	v_div_scale_f32 v173, s[76:77], v161, v161, 1.0
	v_div_scale_f32 v174, s[76:77], v162, v162, 1.0
	v_div_scale_f32 v175, s[76:77], v163, v163, 1.0
	v_rcp_f32_e32 v176, v164
	v_rcp_f32_e32 v177, v165
	v_rcp_f32_e32 v178, v166
	v_rcp_f32_e32 v179, v167
	v_rcp_f32_e32 v180, v172
	v_rcp_f32_e32 v181, v173
	v_rcp_f32_e32 v182, v174
	v_rcp_f32_e32 v183, v175
	v_fma_f32 v148, -v164, v176, 1.0
	v_fma_f32 v149, -v165, v177, 1.0
	v_fma_f32 v150, -v166, v178, 1.0
	v_fma_f32 v151, -v167, v179, 1.0
	v_fma_f32 v152, -v172, v180, 1.0
	v_fma_f32 v153, -v173, v181, 1.0
	v_fma_f32 v154, -v174, v182, 1.0
	v_fma_f32 v155, -v175, v183, 1.0
	v_fmac_f32_e32 v176, v148, v176
	v_fmac_f32_e32 v177, v149, v177
	v_fmac_f32_e32 v178, v150, v178
	v_fmac_f32_e32 v179, v151, v179
	v_fmac_f32_e32 v180, v152, v180
	v_fmac_f32_e32 v181, v153, v181
	v_fmac_f32_e32 v182, v154, v182
	v_fmac_f32_e32 v183, v155, v183
	v_div_scale_f32 v184, vcc, 1.0, v156, 1.0
	v_mul_f32_e32 v192, v184, v176
	v_fma_f32 v148, -v164, v192, v184
	v_fmac_f32_e32 v192, v148, v176
	v_fma_f32 v184, -v164, v192, v184
	v_div_fmas_f32 v184, v184, v176, v192
	v_div_fixup_f32 v148, v184, v156, 1.0
	v_div_scale_f32 v185, vcc, 1.0, v157, 1.0
	v_mul_f32_e32 v193, v185, v177
	v_fma_f32 v149, -v165, v193, v185
	v_fmac_f32_e32 v193, v149, v177
	v_fma_f32 v185, -v165, v193, v185
	v_div_fmas_f32 v185, v185, v177, v193
	v_div_fixup_f32 v149, v185, v157, 1.0
	v_div_scale_f32 v186, vcc, 1.0, v158, 1.0
	v_mul_f32_e32 v194, v186, v178
	v_fma_f32 v150, -v166, v194, v186
	v_fmac_f32_e32 v194, v150, v178
	v_fma_f32 v186, -v166, v194, v186
	v_div_fmas_f32 v186, v186, v178, v194
	v_div_fixup_f32 v150, v186, v158, 1.0
	v_div_scale_f32 v187, vcc, 1.0, v159, 1.0
	v_mul_f32_e32 v195, v187, v179
	v_fma_f32 v151, -v167, v195, v187
	v_fmac_f32_e32 v195, v151, v179
	v_fma_f32 v187, -v167, v195, v187
	v_div_fmas_f32 v187, v187, v179, v195
	v_div_fixup_f32 v151, v187, v159, 1.0
	v_div_scale_f32 v188, vcc, 1.0, v160, 1.0
	v_mul_f32_e32 v196, v188, v180
	v_fma_f32 v152, -v172, v196, v188
	v_fmac_f32_e32 v196, v152, v180
	v_fma_f32 v188, -v172, v196, v188
	v_div_fmas_f32 v188, v188, v180, v196
	v_div_fixup_f32 v152, v188, v160, 1.0
	v_div_scale_f32 v189, vcc, 1.0, v161, 1.0
	v_mul_f32_e32 v197, v189, v181
	v_fma_f32 v153, -v173, v197, v189
	v_fmac_f32_e32 v197, v153, v181
	v_fma_f32 v189, -v173, v197, v189
	v_div_fmas_f32 v189, v189, v181, v197
	v_div_fixup_f32 v153, v189, v161, 1.0
	v_div_scale_f32 v190, vcc, 1.0, v162, 1.0
	v_mul_f32_e32 v198, v190, v182
	v_fma_f32 v154, -v174, v198, v190
	v_fmac_f32_e32 v198, v154, v182
	v_fma_f32 v190, -v174, v198, v190
	v_div_fmas_f32 v190, v190, v182, v198
	v_div_fixup_f32 v154, v190, v162, 1.0
	v_div_scale_f32 v191, vcc, 1.0, v163, 1.0
	v_mul_f32_e32 v199, v191, v183
	v_fma_f32 v155, -v175, v199, v191
	v_fmac_f32_e32 v199, v155, v183
	v_fma_f32 v191, -v175, v199, v191
	v_div_fmas_f32 v191, v191, v183, v199
	v_div_fixup_f32 v155, v191, v163, 1.0
	v_cvt_pk_bf16_f32 v204, v148, v149
	v_cvt_pk_bf16_f32 v205, v150, v151
	v_cvt_pk_bf16_f32 v206, v152, v153
	v_cvt_pk_bf16_f32 v207, v154, v155
	global_store_dwordx4 v243, v[204:207], s[84:85]
	s_add_u32 s84, s84, 0x1000
	s_addc_u32 s85, s85, 0
	v_add_f32_e32 v148, v32, v128
	v_add_f32_e32 v149, v33, v129
	v_add_f32_e32 v150, v34, v130
	v_add_f32_e32 v151, v35, v131
	v_add_f32_e32 v152, v36, v132
	v_add_f32_e32 v153, v37, v133
	v_add_f32_e32 v154, v38, v134
	v_add_f32_e32 v155, v39, v135
	v_mul_f32_e32 v148, 0xbfb8aa3b, v148
	v_mul_f32_e32 v149, 0xbfb8aa3b, v149
	v_mul_f32_e32 v150, 0xbfb8aa3b, v150
	v_mul_f32_e32 v151, 0xbfb8aa3b, v151
	v_mul_f32_e32 v152, 0xbfb8aa3b, v152
	v_mul_f32_e32 v153, 0xbfb8aa3b, v153
	v_mul_f32_e32 v154, 0xbfb8aa3b, v154
	v_mul_f32_e32 v155, 0xbfb8aa3b, v155
	v_exp_f32_e32 v156, v148
	v_exp_f32_e32 v157, v149
	v_exp_f32_e32 v158, v150
	v_exp_f32_e32 v159, v151
	v_exp_f32_e32 v160, v152
	v_exp_f32_e32 v161, v153
	v_exp_f32_e32 v162, v154
	v_exp_f32_e32 v163, v155
	v_add_f32_e32 v156, 1.0, v156
	v_add_f32_e32 v157, 1.0, v157
	v_add_f32_e32 v158, 1.0, v158
	v_add_f32_e32 v159, 1.0, v159
	v_add_f32_e32 v160, 1.0, v160
	v_add_f32_e32 v161, 1.0, v161
	v_add_f32_e32 v162, 1.0, v162
	v_add_f32_e32 v163, 1.0, v163
	v_div_scale_f32 v164, s[76:77], v156, v156, 1.0
	v_div_scale_f32 v165, s[76:77], v157, v157, 1.0
	v_div_scale_f32 v166, s[76:77], v158, v158, 1.0
	v_div_scale_f32 v167, s[76:77], v159, v159, 1.0
	v_div_scale_f32 v172, s[76:77], v160, v160, 1.0
	v_div_scale_f32 v173, s[76:77], v161, v161, 1.0
	v_div_scale_f32 v174, s[76:77], v162, v162, 1.0
	v_div_scale_f32 v175, s[76:77], v163, v163, 1.0
	v_rcp_f32_e32 v176, v164
	v_rcp_f32_e32 v177, v165
	v_rcp_f32_e32 v178, v166
	v_rcp_f32_e32 v179, v167
	v_rcp_f32_e32 v180, v172
	v_rcp_f32_e32 v181, v173
	v_rcp_f32_e32 v182, v174
	v_rcp_f32_e32 v183, v175
	v_fma_f32 v148, -v164, v176, 1.0
	v_fma_f32 v149, -v165, v177, 1.0
	v_fma_f32 v150, -v166, v178, 1.0
	v_fma_f32 v151, -v167, v179, 1.0
	v_fma_f32 v152, -v172, v180, 1.0
	v_fma_f32 v153, -v173, v181, 1.0
	v_fma_f32 v154, -v174, v182, 1.0
	v_fma_f32 v155, -v175, v183, 1.0
	v_fmac_f32_e32 v176, v148, v176
	v_fmac_f32_e32 v177, v149, v177
	v_fmac_f32_e32 v178, v150, v178
	v_fmac_f32_e32 v179, v151, v179
	v_fmac_f32_e32 v180, v152, v180
	v_fmac_f32_e32 v181, v153, v181
	v_fmac_f32_e32 v182, v154, v182
	v_fmac_f32_e32 v183, v155, v183
	v_div_scale_f32 v184, vcc, 1.0, v156, 1.0
	v_mul_f32_e32 v192, v184, v176
	v_fma_f32 v148, -v164, v192, v184
	v_fmac_f32_e32 v192, v148, v176
	v_fma_f32 v184, -v164, v192, v184
	v_div_fmas_f32 v184, v184, v176, v192
	v_div_fixup_f32 v148, v184, v156, 1.0
	v_div_scale_f32 v185, vcc, 1.0, v157, 1.0
	v_mul_f32_e32 v193, v185, v177
	v_fma_f32 v149, -v165, v193, v185
	v_fmac_f32_e32 v193, v149, v177
	v_fma_f32 v185, -v165, v193, v185
	v_div_fmas_f32 v185, v185, v177, v193
	v_div_fixup_f32 v149, v185, v157, 1.0
	v_div_scale_f32 v186, vcc, 1.0, v158, 1.0
	v_mul_f32_e32 v194, v186, v178
	v_fma_f32 v150, -v166, v194, v186
	v_fmac_f32_e32 v194, v150, v178
	v_fma_f32 v186, -v166, v194, v186
	v_div_fmas_f32 v186, v186, v178, v194
	v_div_fixup_f32 v150, v186, v158, 1.0
	v_div_scale_f32 v187, vcc, 1.0, v159, 1.0
	v_mul_f32_e32 v195, v187, v179
	v_fma_f32 v151, -v167, v195, v187
	v_fmac_f32_e32 v195, v151, v179
	v_fma_f32 v187, -v167, v195, v187
	v_div_fmas_f32 v187, v187, v179, v195
	v_div_fixup_f32 v151, v187, v159, 1.0
	v_div_scale_f32 v188, vcc, 1.0, v160, 1.0
	v_mul_f32_e32 v196, v188, v180
	v_fma_f32 v152, -v172, v196, v188
	v_fmac_f32_e32 v196, v152, v180
	v_fma_f32 v188, -v172, v196, v188
	v_div_fmas_f32 v188, v188, v180, v196
	v_div_fixup_f32 v152, v188, v160, 1.0
	v_div_scale_f32 v189, vcc, 1.0, v161, 1.0
	v_mul_f32_e32 v197, v189, v181
	v_fma_f32 v153, -v173, v197, v189
	v_fmac_f32_e32 v197, v153, v181
	v_fma_f32 v189, -v173, v197, v189
	v_div_fmas_f32 v189, v189, v181, v197
	v_div_fixup_f32 v153, v189, v161, 1.0
	v_div_scale_f32 v190, vcc, 1.0, v162, 1.0
	v_mul_f32_e32 v198, v190, v182
	v_fma_f32 v154, -v174, v198, v190
	v_fmac_f32_e32 v198, v154, v182
	v_fma_f32 v190, -v174, v198, v190
	v_div_fmas_f32 v190, v190, v182, v198
	v_div_fixup_f32 v154, v190, v162, 1.0
	v_div_scale_f32 v191, vcc, 1.0, v163, 1.0
	v_mul_f32_e32 v199, v191, v183
	v_fma_f32 v155, -v175, v199, v191
	v_fmac_f32_e32 v199, v155, v183
	v_fma_f32 v191, -v175, v199, v191
	v_div_fmas_f32 v191, v191, v183, v199
	v_div_fixup_f32 v155, v191, v163, 1.0
	v_cvt_pk_bf16_f32 v200, v148, v149
	v_cvt_pk_bf16_f32 v201, v150, v151
	v_cvt_pk_bf16_f32 v202, v152, v153
	v_cvt_pk_bf16_f32 v203, v154, v155
	global_store_dwordx4 v243, v[200:203], s[84:85]
	s_add_u32 s84, s84, 0x1000
	s_addc_u32 s85, s85, 0
	v_add_f32_e32 v148, v40, v136
	v_add_f32_e32 v149, v41, v137
	v_add_f32_e32 v150, v42, v138
	v_add_f32_e32 v151, v43, v139
	v_add_f32_e32 v152, v44, v140
	v_add_f32_e32 v153, v45, v141
	v_add_f32_e32 v154, v46, v142
	v_add_f32_e32 v155, v47, v143
	v_mul_f32_e32 v148, 0xbfb8aa3b, v148
	v_mul_f32_e32 v149, 0xbfb8aa3b, v149
	v_mul_f32_e32 v150, 0xbfb8aa3b, v150
	v_mul_f32_e32 v151, 0xbfb8aa3b, v151
	v_mul_f32_e32 v152, 0xbfb8aa3b, v152
	v_mul_f32_e32 v153, 0xbfb8aa3b, v153
	v_mul_f32_e32 v154, 0xbfb8aa3b, v154
	v_mul_f32_e32 v155, 0xbfb8aa3b, v155
	v_exp_f32_e32 v156, v148
	v_exp_f32_e32 v157, v149
	v_exp_f32_e32 v158, v150
	v_exp_f32_e32 v159, v151
	v_exp_f32_e32 v160, v152
	v_exp_f32_e32 v161, v153
	v_exp_f32_e32 v162, v154
	v_exp_f32_e32 v163, v155
	v_add_f32_e32 v156, 1.0, v156
	v_add_f32_e32 v157, 1.0, v157
	v_add_f32_e32 v158, 1.0, v158
	v_add_f32_e32 v159, 1.0, v159
	v_add_f32_e32 v160, 1.0, v160
	v_add_f32_e32 v161, 1.0, v161
	v_add_f32_e32 v162, 1.0, v162
	v_add_f32_e32 v163, 1.0, v163
	v_div_scale_f32 v164, s[76:77], v156, v156, 1.0
	v_div_scale_f32 v165, s[76:77], v157, v157, 1.0
	v_div_scale_f32 v166, s[76:77], v158, v158, 1.0
	v_div_scale_f32 v167, s[76:77], v159, v159, 1.0
	v_div_scale_f32 v172, s[76:77], v160, v160, 1.0
	v_div_scale_f32 v173, s[76:77], v161, v161, 1.0
	v_div_scale_f32 v174, s[76:77], v162, v162, 1.0
	v_div_scale_f32 v175, s[76:77], v163, v163, 1.0
	v_rcp_f32_e32 v176, v164
	v_rcp_f32_e32 v177, v165
	v_rcp_f32_e32 v178, v166
	v_rcp_f32_e32 v179, v167
	v_rcp_f32_e32 v180, v172
	v_rcp_f32_e32 v181, v173
	v_rcp_f32_e32 v182, v174
	v_rcp_f32_e32 v183, v175
	v_fma_f32 v148, -v164, v176, 1.0
	v_fma_f32 v149, -v165, v177, 1.0
	v_fma_f32 v150, -v166, v178, 1.0
	v_fma_f32 v151, -v167, v179, 1.0
	v_fma_f32 v152, -v172, v180, 1.0
	v_fma_f32 v153, -v173, v181, 1.0
	v_fma_f32 v154, -v174, v182, 1.0
	v_fma_f32 v155, -v175, v183, 1.0
	v_fmac_f32_e32 v176, v148, v176
	v_fmac_f32_e32 v177, v149, v177
	v_fmac_f32_e32 v178, v150, v178
	v_fmac_f32_e32 v179, v151, v179
	v_fmac_f32_e32 v180, v152, v180
	v_fmac_f32_e32 v181, v153, v181
	v_fmac_f32_e32 v182, v154, v182
	v_fmac_f32_e32 v183, v155, v183
	v_div_scale_f32 v184, vcc, 1.0, v156, 1.0
	v_mul_f32_e32 v192, v184, v176
	v_fma_f32 v148, -v164, v192, v184
	v_fmac_f32_e32 v192, v148, v176
	v_fma_f32 v184, -v164, v192, v184
	v_div_fmas_f32 v184, v184, v176, v192
	v_div_fixup_f32 v148, v184, v156, 1.0
	v_div_scale_f32 v185, vcc, 1.0, v157, 1.0
	v_mul_f32_e32 v193, v185, v177
	v_fma_f32 v149, -v165, v193, v185
	v_fmac_f32_e32 v193, v149, v177
	v_fma_f32 v185, -v165, v193, v185
	v_div_fmas_f32 v185, v185, v177, v193
	v_div_fixup_f32 v149, v185, v157, 1.0
	v_div_scale_f32 v186, vcc, 1.0, v158, 1.0
	v_mul_f32_e32 v194, v186, v178
	v_fma_f32 v150, -v166, v194, v186
	v_fmac_f32_e32 v194, v150, v178
	v_fma_f32 v186, -v166, v194, v186
	v_div_fmas_f32 v186, v186, v178, v194
	v_div_fixup_f32 v150, v186, v158, 1.0
	v_div_scale_f32 v187, vcc, 1.0, v159, 1.0
	v_mul_f32_e32 v195, v187, v179
	v_fma_f32 v151, -v167, v195, v187
	v_fmac_f32_e32 v195, v151, v179
	v_fma_f32 v187, -v167, v195, v187
	v_div_fmas_f32 v187, v187, v179, v195
	v_div_fixup_f32 v151, v187, v159, 1.0
	v_div_scale_f32 v188, vcc, 1.0, v160, 1.0
	v_mul_f32_e32 v196, v188, v180
	v_fma_f32 v152, -v172, v196, v188
	v_fmac_f32_e32 v196, v152, v180
	v_fma_f32 v188, -v172, v196, v188
	v_div_fmas_f32 v188, v188, v180, v196
	v_div_fixup_f32 v152, v188, v160, 1.0
	v_div_scale_f32 v189, vcc, 1.0, v161, 1.0
	v_mul_f32_e32 v197, v189, v181
	v_fma_f32 v153, -v173, v197, v189
	v_fmac_f32_e32 v197, v153, v181
	v_fma_f32 v189, -v173, v197, v189
	v_div_fmas_f32 v189, v189, v181, v197
	v_div_fixup_f32 v153, v189, v161, 1.0
	v_div_scale_f32 v190, vcc, 1.0, v162, 1.0
	v_mul_f32_e32 v198, v190, v182
	v_fma_f32 v154, -v174, v198, v190
	v_fmac_f32_e32 v198, v154, v182
	v_fma_f32 v190, -v174, v198, v190
	v_div_fmas_f32 v190, v190, v182, v198
	v_div_fixup_f32 v154, v190, v162, 1.0
	v_div_scale_f32 v191, vcc, 1.0, v163, 1.0
	v_mul_f32_e32 v199, v191, v183
	v_fma_f32 v155, -v175, v199, v191
	v_fmac_f32_e32 v199, v155, v183
	v_fma_f32 v191, -v175, v199, v191
	v_div_fmas_f32 v191, v191, v183, v199
	v_div_fixup_f32 v155, v191, v163, 1.0
	v_cvt_pk_bf16_f32 v204, v148, v149
	v_cvt_pk_bf16_f32 v205, v150, v151
	v_cvt_pk_bf16_f32 v206, v152, v153
	v_cvt_pk_bf16_f32 v207, v154, v155
	global_store_dwordx4 v243, v[204:207], s[84:85]
	s_add_u32 s84, s84, 0x1000
	s_addc_u32 s85, s85, 0
	v_add_f32_e32 v148, v48, v128
	v_add_f32_e32 v149, v49, v129
	v_add_f32_e32 v150, v50, v130
	v_add_f32_e32 v151, v51, v131
	v_add_f32_e32 v152, v52, v132
	v_add_f32_e32 v153, v53, v133
	v_add_f32_e32 v154, v54, v134
	v_add_f32_e32 v155, v55, v135
	v_mul_f32_e32 v148, 0xbfb8aa3b, v148
	v_mul_f32_e32 v149, 0xbfb8aa3b, v149
	v_mul_f32_e32 v150, 0xbfb8aa3b, v150
	v_mul_f32_e32 v151, 0xbfb8aa3b, v151
	v_mul_f32_e32 v152, 0xbfb8aa3b, v152
	v_mul_f32_e32 v153, 0xbfb8aa3b, v153
	v_mul_f32_e32 v154, 0xbfb8aa3b, v154
	v_mul_f32_e32 v155, 0xbfb8aa3b, v155
	v_exp_f32_e32 v156, v148
	v_exp_f32_e32 v157, v149
	v_exp_f32_e32 v158, v150
	v_exp_f32_e32 v159, v151
	v_exp_f32_e32 v160, v152
	v_exp_f32_e32 v161, v153
	v_exp_f32_e32 v162, v154
	v_exp_f32_e32 v163, v155
	v_add_f32_e32 v156, 1.0, v156
	v_add_f32_e32 v157, 1.0, v157
	v_add_f32_e32 v158, 1.0, v158
	v_add_f32_e32 v159, 1.0, v159
	v_add_f32_e32 v160, 1.0, v160
	v_add_f32_e32 v161, 1.0, v161
	v_add_f32_e32 v162, 1.0, v162
	v_add_f32_e32 v163, 1.0, v163
	v_div_scale_f32 v164, s[76:77], v156, v156, 1.0
	v_div_scale_f32 v165, s[76:77], v157, v157, 1.0
	v_div_scale_f32 v166, s[76:77], v158, v158, 1.0
	v_div_scale_f32 v167, s[76:77], v159, v159, 1.0
	v_div_scale_f32 v172, s[76:77], v160, v160, 1.0
	v_div_scale_f32 v173, s[76:77], v161, v161, 1.0
	v_div_scale_f32 v174, s[76:77], v162, v162, 1.0
	v_div_scale_f32 v175, s[76:77], v163, v163, 1.0
	v_rcp_f32_e32 v176, v164
	v_rcp_f32_e32 v177, v165
	v_rcp_f32_e32 v178, v166
	v_rcp_f32_e32 v179, v167
	v_rcp_f32_e32 v180, v172
	v_rcp_f32_e32 v181, v173
	v_rcp_f32_e32 v182, v174
	v_rcp_f32_e32 v183, v175
	v_fma_f32 v148, -v164, v176, 1.0
	v_fma_f32 v149, -v165, v177, 1.0
	v_fma_f32 v150, -v166, v178, 1.0
	v_fma_f32 v151, -v167, v179, 1.0
	v_fma_f32 v152, -v172, v180, 1.0
	v_fma_f32 v153, -v173, v181, 1.0
	v_fma_f32 v154, -v174, v182, 1.0
	v_fma_f32 v155, -v175, v183, 1.0
	v_fmac_f32_e32 v176, v148, v176
	v_fmac_f32_e32 v177, v149, v177
	v_fmac_f32_e32 v178, v150, v178
	v_fmac_f32_e32 v179, v151, v179
	v_fmac_f32_e32 v180, v152, v180
	v_fmac_f32_e32 v181, v153, v181
	v_fmac_f32_e32 v182, v154, v182
	v_fmac_f32_e32 v183, v155, v183
	v_div_scale_f32 v184, vcc, 1.0, v156, 1.0
	v_mul_f32_e32 v192, v184, v176
	v_fma_f32 v148, -v164, v192, v184
	v_fmac_f32_e32 v192, v148, v176
	v_fma_f32 v184, -v164, v192, v184
	v_div_fmas_f32 v184, v184, v176, v192
	v_div_fixup_f32 v148, v184, v156, 1.0
	v_div_scale_f32 v185, vcc, 1.0, v157, 1.0
	v_mul_f32_e32 v193, v185, v177
	v_fma_f32 v149, -v165, v193, v185
	v_fmac_f32_e32 v193, v149, v177
	v_fma_f32 v185, -v165, v193, v185
	v_div_fmas_f32 v185, v185, v177, v193
	v_div_fixup_f32 v149, v185, v157, 1.0
	v_div_scale_f32 v186, vcc, 1.0, v158, 1.0
	v_mul_f32_e32 v194, v186, v178
	v_fma_f32 v150, -v166, v194, v186
	v_fmac_f32_e32 v194, v150, v178
	v_fma_f32 v186, -v166, v194, v186
	v_div_fmas_f32 v186, v186, v178, v194
	v_div_fixup_f32 v150, v186, v158, 1.0
	v_div_scale_f32 v187, vcc, 1.0, v159, 1.0
	v_mul_f32_e32 v195, v187, v179
	v_fma_f32 v151, -v167, v195, v187
	v_fmac_f32_e32 v195, v151, v179
	v_fma_f32 v187, -v167, v195, v187
	v_div_fmas_f32 v187, v187, v179, v195
	v_div_fixup_f32 v151, v187, v159, 1.0
	v_div_scale_f32 v188, vcc, 1.0, v160, 1.0
	v_mul_f32_e32 v196, v188, v180
	v_fma_f32 v152, -v172, v196, v188
	v_fmac_f32_e32 v196, v152, v180
	v_fma_f32 v188, -v172, v196, v188
	v_div_fmas_f32 v188, v188, v180, v196
	v_div_fixup_f32 v152, v188, v160, 1.0
	v_div_scale_f32 v189, vcc, 1.0, v161, 1.0
	v_mul_f32_e32 v197, v189, v181
	v_fma_f32 v153, -v173, v197, v189
	v_fmac_f32_e32 v197, v153, v181
	v_fma_f32 v189, -v173, v197, v189
	v_div_fmas_f32 v189, v189, v181, v197
	v_div_fixup_f32 v153, v189, v161, 1.0
	v_div_scale_f32 v190, vcc, 1.0, v162, 1.0
	v_mul_f32_e32 v198, v190, v182
	v_fma_f32 v154, -v174, v198, v190
	v_fmac_f32_e32 v198, v154, v182
	v_fma_f32 v190, -v174, v198, v190
	v_div_fmas_f32 v190, v190, v182, v198
	v_div_fixup_f32 v154, v190, v162, 1.0
	v_div_scale_f32 v191, vcc, 1.0, v163, 1.0
	v_mul_f32_e32 v199, v191, v183
	v_fma_f32 v155, -v175, v199, v191
	v_fmac_f32_e32 v199, v155, v183
	v_fma_f32 v191, -v175, v199, v191
	v_div_fmas_f32 v191, v191, v183, v199
	v_div_fixup_f32 v155, v191, v163, 1.0
	v_cvt_pk_bf16_f32 v200, v148, v149
	v_cvt_pk_bf16_f32 v201, v150, v151
	v_cvt_pk_bf16_f32 v202, v152, v153
	v_cvt_pk_bf16_f32 v203, v154, v155
	global_store_dwordx4 v243, v[200:203], s[84:85]
	s_add_u32 s84, s84, 0x1000
	s_addc_u32 s85, s85, 0
	v_add_f32_e32 v148, v56, v136
	v_add_f32_e32 v149, v57, v137
	v_add_f32_e32 v150, v58, v138
	v_add_f32_e32 v151, v59, v139
	v_add_f32_e32 v152, v60, v140
	v_add_f32_e32 v153, v61, v141
	v_add_f32_e32 v154, v62, v142
	v_add_f32_e32 v155, v63, v143
	v_mul_f32_e32 v148, 0xbfb8aa3b, v148
	v_mul_f32_e32 v149, 0xbfb8aa3b, v149
	v_mul_f32_e32 v150, 0xbfb8aa3b, v150
	v_mul_f32_e32 v151, 0xbfb8aa3b, v151
	v_mul_f32_e32 v152, 0xbfb8aa3b, v152
	v_mul_f32_e32 v153, 0xbfb8aa3b, v153
	v_mul_f32_e32 v154, 0xbfb8aa3b, v154
	v_mul_f32_e32 v155, 0xbfb8aa3b, v155
	v_exp_f32_e32 v156, v148
	v_exp_f32_e32 v157, v149
	v_exp_f32_e32 v158, v150
	v_exp_f32_e32 v159, v151
	v_exp_f32_e32 v160, v152
	v_exp_f32_e32 v161, v153
	v_exp_f32_e32 v162, v154
	v_exp_f32_e32 v163, v155
	v_add_f32_e32 v156, 1.0, v156
	v_add_f32_e32 v157, 1.0, v157
	v_add_f32_e32 v158, 1.0, v158
	v_add_f32_e32 v159, 1.0, v159
	v_add_f32_e32 v160, 1.0, v160
	v_add_f32_e32 v161, 1.0, v161
	v_add_f32_e32 v162, 1.0, v162
	v_add_f32_e32 v163, 1.0, v163
	v_div_scale_f32 v164, s[76:77], v156, v156, 1.0
	v_div_scale_f32 v165, s[76:77], v157, v157, 1.0
	v_div_scale_f32 v166, s[76:77], v158, v158, 1.0
	v_div_scale_f32 v167, s[76:77], v159, v159, 1.0
	v_div_scale_f32 v172, s[76:77], v160, v160, 1.0
	v_div_scale_f32 v173, s[76:77], v161, v161, 1.0
	v_div_scale_f32 v174, s[76:77], v162, v162, 1.0
	v_div_scale_f32 v175, s[76:77], v163, v163, 1.0
	v_rcp_f32_e32 v176, v164
	v_rcp_f32_e32 v177, v165
	v_rcp_f32_e32 v178, v166
	v_rcp_f32_e32 v179, v167
	v_rcp_f32_e32 v180, v172
	v_rcp_f32_e32 v181, v173
	v_rcp_f32_e32 v182, v174
	v_rcp_f32_e32 v183, v175
	v_fma_f32 v148, -v164, v176, 1.0
	v_fma_f32 v149, -v165, v177, 1.0
	v_fma_f32 v150, -v166, v178, 1.0
	v_fma_f32 v151, -v167, v179, 1.0
	v_fma_f32 v152, -v172, v180, 1.0
	v_fma_f32 v153, -v173, v181, 1.0
	v_fma_f32 v154, -v174, v182, 1.0
	v_fma_f32 v155, -v175, v183, 1.0
	v_fmac_f32_e32 v176, v148, v176
	v_fmac_f32_e32 v177, v149, v177
	v_fmac_f32_e32 v178, v150, v178
	v_fmac_f32_e32 v179, v151, v179
	v_fmac_f32_e32 v180, v152, v180
	v_fmac_f32_e32 v181, v153, v181
	v_fmac_f32_e32 v182, v154, v182
	v_fmac_f32_e32 v183, v155, v183
	v_div_scale_f32 v184, vcc, 1.0, v156, 1.0
	v_mul_f32_e32 v192, v184, v176
	v_fma_f32 v148, -v164, v192, v184
	v_fmac_f32_e32 v192, v148, v176
	v_fma_f32 v184, -v164, v192, v184
	v_div_fmas_f32 v184, v184, v176, v192
	v_div_fixup_f32 v148, v184, v156, 1.0
	v_div_scale_f32 v185, vcc, 1.0, v157, 1.0
	v_mul_f32_e32 v193, v185, v177
	v_fma_f32 v149, -v165, v193, v185
	v_fmac_f32_e32 v193, v149, v177
	v_fma_f32 v185, -v165, v193, v185
	v_div_fmas_f32 v185, v185, v177, v193
	v_div_fixup_f32 v149, v185, v157, 1.0
	v_div_scale_f32 v186, vcc, 1.0, v158, 1.0
	v_mul_f32_e32 v194, v186, v178
	v_fma_f32 v150, -v166, v194, v186
	v_fmac_f32_e32 v194, v150, v178
	v_fma_f32 v186, -v166, v194, v186
	v_div_fmas_f32 v186, v186, v178, v194
	v_div_fixup_f32 v150, v186, v158, 1.0
	v_div_scale_f32 v187, vcc, 1.0, v159, 1.0
	v_mul_f32_e32 v195, v187, v179
	v_fma_f32 v151, -v167, v195, v187
	v_fmac_f32_e32 v195, v151, v179
	v_fma_f32 v187, -v167, v195, v187
	v_div_fmas_f32 v187, v187, v179, v195
	v_div_fixup_f32 v151, v187, v159, 1.0
	v_div_scale_f32 v188, vcc, 1.0, v160, 1.0
	v_mul_f32_e32 v196, v188, v180
	v_fma_f32 v152, -v172, v196, v188
	v_fmac_f32_e32 v196, v152, v180
	v_fma_f32 v188, -v172, v196, v188
	v_div_fmas_f32 v188, v188, v180, v196
	v_div_fixup_f32 v152, v188, v160, 1.0
	v_div_scale_f32 v189, vcc, 1.0, v161, 1.0
	v_mul_f32_e32 v197, v189, v181
	v_fma_f32 v153, -v173, v197, v189
	v_fmac_f32_e32 v197, v153, v181
	v_fma_f32 v189, -v173, v197, v189
	v_div_fmas_f32 v189, v189, v181, v197
	v_div_fixup_f32 v153, v189, v161, 1.0
	v_div_scale_f32 v190, vcc, 1.0, v162, 1.0
	v_mul_f32_e32 v198, v190, v182
	v_fma_f32 v154, -v174, v198, v190
	v_fmac_f32_e32 v198, v154, v182
	v_fma_f32 v190, -v174, v198, v190
	v_div_fmas_f32 v190, v190, v182, v198
	v_div_fixup_f32 v154, v190, v162, 1.0
	v_div_scale_f32 v191, vcc, 1.0, v163, 1.0
	v_mul_f32_e32 v199, v191, v183
	v_fma_f32 v155, -v175, v199, v191
	v_fmac_f32_e32 v199, v155, v183
	v_fma_f32 v191, -v175, v199, v191
	v_div_fmas_f32 v191, v191, v183, v199
	v_div_fixup_f32 v155, v191, v163, 1.0
	v_cvt_pk_bf16_f32 v204, v148, v149
	v_cvt_pk_bf16_f32 v205, v150, v151
	v_cvt_pk_bf16_f32 v206, v152, v153
	v_cvt_pk_bf16_f32 v207, v154, v155
	global_store_dwordx4 v243, v[204:207], s[84:85]
	s_add_u32 s84, s84, 0x1000
	s_addc_u32 s85, s85, 0
	s_cmp_eq_u32 s83, 1
	s_cbranch_scc1 .Lp5ga_epdone
	s_cmp_eq_u32 s95, 1
	s_cbranch_scc0 .Lp5ga_epdone
	v_mov_b32_e32 v0, v64
	v_mov_b32_e32 v1, v65
	v_mov_b32_e32 v2, v66
	v_mov_b32_e32 v3, v67
	v_mov_b32_e32 v4, v68
	v_mov_b32_e32 v5, v69
	v_mov_b32_e32 v6, v70
	v_mov_b32_e32 v7, v71
	v_mov_b32_e32 v8, v72
	v_mov_b32_e32 v9, v73
	v_mov_b32_e32 v10, v74
	v_mov_b32_e32 v11, v75
	v_mov_b32_e32 v12, v76
	v_mov_b32_e32 v13, v77
	v_mov_b32_e32 v14, v78
	v_mov_b32_e32 v15, v79
	v_mov_b32_e32 v16, v80
	v_mov_b32_e32 v17, v81
	v_mov_b32_e32 v18, v82
	v_mov_b32_e32 v19, v83
	v_mov_b32_e32 v20, v84
	v_mov_b32_e32 v21, v85
	v_mov_b32_e32 v22, v86
	v_mov_b32_e32 v23, v87
	v_mov_b32_e32 v24, v88
	v_mov_b32_e32 v25, v89
	v_mov_b32_e32 v26, v90
	v_mov_b32_e32 v27, v91
	v_mov_b32_e32 v28, v92
	v_mov_b32_e32 v29, v93
	v_mov_b32_e32 v30, v94
	v_mov_b32_e32 v31, v95
	v_mov_b32_e32 v32, v96
	v_mov_b32_e32 v33, v97
	v_mov_b32_e32 v34, v98
	v_mov_b32_e32 v35, v99
	v_mov_b32_e32 v36, v100
	v_mov_b32_e32 v37, v101
	v_mov_b32_e32 v38, v102
	v_mov_b32_e32 v39, v103
	v_mov_b32_e32 v40, v104
	v_mov_b32_e32 v41, v105
	v_mov_b32_e32 v42, v106
	v_mov_b32_e32 v43, v107
	v_mov_b32_e32 v44, v108
	v_mov_b32_e32 v45, v109
	v_mov_b32_e32 v46, v110
	v_mov_b32_e32 v47, v111
	v_mov_b32_e32 v48, v112
	v_mov_b32_e32 v49, v113
	v_mov_b32_e32 v50, v114
	v_mov_b32_e32 v51, v115
	v_mov_b32_e32 v52, v116
	v_mov_b32_e32 v53, v117
	v_mov_b32_e32 v54, v118
	v_mov_b32_e32 v55, v119
	v_mov_b32_e32 v56, v120
	v_mov_b32_e32 v57, v121
	v_mov_b32_e32 v58, v122
	v_mov_b32_e32 v59, v123
	v_mov_b32_e32 v60, v124
	v_mov_b32_e32 v61, v125
	v_mov_b32_e32 v62, v126
	v_mov_b32_e32 v63, v127
	s_mov_b32 s83, 1
	s_branch .Lp5ga_ep
.Lp5ga_epdone:
.Lp5g_site_b:
	v_lshrrev_b32_e32 v236, 3, v168
	v_lshrrev_b32_e32 v237, 4, v168
	v_xor_b32_e32 v237, v237, v168
	v_and_b32_e32 v237, 7, v237
	v_lshlrev_b32_e32 v237, 4, v237
	v_lshl_or_b32 v232, v236, 11, v237
	v_add_u32_e32 v233, 0x10000, v232
	v_add_u32_e32 v234, 0x20000, v232
	v_add_u32_e32 v235, 0x30000, v232
	s_load_dwordx2 s[90:91], s[0:1], 0xa0
	s_load_dwordx2 s[92:93], s[0:1], 0xb0
	v_lshrrev_b32_e32 v237, 6, v168
	s_nop 1
	v_readfirstlane_b32 s97, v237
	s_nop 3
	s_lshl_b32 s96, s97, 10
	s_add_u32 s96, s96, 16
	s_add_u32 s94, s81, s80
	s_cmp_lt_i32 s94, s82
	s_cselect_b32 s95, 1, 0
	s_cmp_lg_u64 s[36:37], 0
	s_cselect_b32 s95, 0, s95
	s_cmp_ge_u32 s94, 0x40
	s_cselect_b32 s97, 1, 0
	s_mul_i32 s100, s97, 0x40
	s_sub_u32 s100, s94, s100
	s_lshr_b32 s101, s100, 3
	s_and_b32 s100, s100, 7
	s_lshl_b32 s97, s97, 3
	s_add_u32 s100, s100, s97
	s_add_u32 s100, s100, s79
	s_cmp_lg_u32 s101, s74
	s_cselect_b32 s95, 0, s95
	s_cmp_eq_u32 s95, 1
	s_cselect_b32 s101, s100, s70
	s_mov_b32 s97, s101
	s_waitcnt lgkmcnt(0)
	s_lshl_b32 s94, s74, 18
	s_add_u32 s98, s92, s94
	s_addc_u32 s99, s93, 0
	s_lshl_b32 s101, s101, 18
	s_add_u32 s101, s101, 0x2000000
	s_add_u32 s92, s90, s101
	s_addc_u32 s93, s91, 0
	s_lshl_b32 s94, s70, 18
	s_add_u32 s94, s94, 0x2000000
	s_add_u32 s90, s90, s94
	s_addc_u32 s91, s91, 0
	s_mov_b64 s[100:101], s[90:91]
	s_mov_b64 s[90:91], s[98:99]
	s_mov_b64 s[98:99], s[92:93]
	s_mov_b64 s[92:93], s[100:101]
	s_waitcnt vmcnt(0)
	s_barrier
	s_add_u32 m0, s96, 0x0
	s_nop 0
	global_load_lds_dwordx4 v232, s[90:91]
	s_add_u32 m0, s96, 0x1000
	s_nop 0
	global_load_lds_dwordx4 v233, s[90:91]
	s_add_u32 m0, s96, 0x2000
	s_nop 0
	global_load_lds_dwordx4 v234, s[90:91]
	s_add_u32 m0, s96, 0x3000
	s_nop 0
	global_load_lds_dwordx4 v235, s[90:91]
	s_add_u32 m0, s96, 0x8000
	s_nop 0
	global_load_lds_dwordx4 v232, s[92:93]
	s_add_u32 m0, s96, 0x9000
	s_nop 0
	global_load_lds_dwordx4 v233, s[92:93]
	s_add_u32 m0, s96, 0xa000
	s_nop 0
	global_load_lds_dwordx4 v234, s[92:93]
	s_add_u32 m0, s96, 0xb000
	s_nop 0
	global_load_lds_dwordx4 v235, s[92:93]
	s_add_u32 m0, s96, 0xc000
	s_nop 0
	global_load_lds_dwordx4 v232, s[98:99]
	s_add_u32 m0, s96, 0xd000
	s_nop 0
	global_load_lds_dwordx4 v233, s[98:99]
	s_add_u32 m0, s96, 0xe000
	s_nop 0
	global_load_lds_dwordx4 v234, s[98:99]
	s_add_u32 m0, s96, 0xf000
	s_nop 0
	global_load_lds_dwordx4 v235, s[98:99]
	s_add_u32 s90, s90, 0x80
	s_addc_u32 s91, s91, 0
	s_add_u32 s92, s92, 0x80
	s_addc_u32 s93, s93, 0
	s_add_u32 s98, s98, 0x80
	s_addc_u32 s99, s99, 0
	v_mov_b32_e32 v0, 0
	v_mov_b32_e32 v1, v0
	v_mov_b32_e32 v2, v0
	v_mov_b32_e32 v3, v0
	v_mov_b32_e32 v4, v0
	v_mov_b32_e32 v5, v0
	v_mov_b32_e32 v6, v0
	v_mov_b32_e32 v7, v0
	v_mov_b32_e32 v8, v0
	v_mov_b32_e32 v9, v0
	v_mov_b32_e32 v10, v0
	v_mov_b32_e32 v11, v0
	v_mov_b32_e32 v12, v0
	v_mov_b32_e32 v13, v0
	v_mov_b32_e32 v14, v0
	v_mov_b32_e32 v15, v0
	v_mov_b32_e32 v16, v0
	v_mov_b32_e32 v17, v0
	v_mov_b32_e32 v18, v0
	v_mov_b32_e32 v19, v0
	v_mov_b32_e32 v20, v0
	v_mov_b32_e32 v21, v0
	v_mov_b32_e32 v22, v0
	v_mov_b32_e32 v23, v0
	v_mov_b32_e32 v24, v0
	v_mov_b32_e32 v25, v0
	v_mov_b32_e32 v26, v0
	v_mov_b32_e32 v27, v0
	v_mov_b32_e32 v28, v0
	v_mov_b32_e32 v29, v0
	v_mov_b32_e32 v30, v0
	v_mov_b32_e32 v31, v0
	v_mov_b32_e32 v32, v0
	v_mov_b32_e32 v33, v0
	v_mov_b32_e32 v34, v0
	v_mov_b32_e32 v35, v0
	v_mov_b32_e32 v36, v0
	v_mov_b32_e32 v37, v0
	v_mov_b32_e32 v38, v0
	v_mov_b32_e32 v39, v0
	v_mov_b32_e32 v40, v0
	v_mov_b32_e32 v41, v0
	v_mov_b32_e32 v42, v0
	v_mov_b32_e32 v43, v0
	v_mov_b32_e32 v44, v0
	v_mov_b32_e32 v45, v0
	v_mov_b32_e32 v46, v0
	v_mov_b32_e32 v47, v0
	v_mov_b32_e32 v48, v0
	v_mov_b32_e32 v49, v0
	v_mov_b32_e32 v50, v0
	v_mov_b32_e32 v51, v0
	v_mov_b32_e32 v52, v0
	v_mov_b32_e32 v53, v0
	v_mov_b32_e32 v54, v0
	v_mov_b32_e32 v55, v0
	v_mov_b32_e32 v56, v0
	v_mov_b32_e32 v57, v0
	v_mov_b32_e32 v58, v0
	v_mov_b32_e32 v59, v0
	v_mov_b32_e32 v60, v0
	v_mov_b32_e32 v61, v0
	v_mov_b32_e32 v62, v0
	v_mov_b32_e32 v63, v0
	v_mov_b32_e32 v64, v0
	v_mov_b32_e32 v65, v0
	v_mov_b32_e32 v66, v0
	v_mov_b32_e32 v67, v0
	v_mov_b32_e32 v68, v0
	v_mov_b32_e32 v69, v0
	v_mov_b32_e32 v70, v0
	v_mov_b32_e32 v71, v0
	v_mov_b32_e32 v72, v0
	v_mov_b32_e32 v73, v0
	v_mov_b32_e32 v74, v0
	v_mov_b32_e32 v75, v0
	v_mov_b32_e32 v76, v0
	v_mov_b32_e32 v77, v0
	v_mov_b32_e32 v78, v0
	v_mov_b32_e32 v79, v0
	v_mov_b32_e32 v80, v0
	v_mov_b32_e32 v81, v0
	v_mov_b32_e32 v82, v0
	v_mov_b32_e32 v83, v0
	v_mov_b32_e32 v84, v0
	v_mov_b32_e32 v85, v0
	v_mov_b32_e32 v86, v0
	v_mov_b32_e32 v87, v0
	v_mov_b32_e32 v88, v0
	v_mov_b32_e32 v89, v0
	v_mov_b32_e32 v90, v0
	v_mov_b32_e32 v91, v0
	v_mov_b32_e32 v92, v0
	v_mov_b32_e32 v93, v0
	v_mov_b32_e32 v94, v0
	v_mov_b32_e32 v95, v0
	v_mov_b32_e32 v96, v0
	v_mov_b32_e32 v97, v0
	v_mov_b32_e32 v98, v0
	v_mov_b32_e32 v99, v0
	v_mov_b32_e32 v100, v0
	v_mov_b32_e32 v101, v0
	v_mov_b32_e32 v102, v0
	v_mov_b32_e32 v103, v0
	v_mov_b32_e32 v104, v0
	v_mov_b32_e32 v105, v0
	v_mov_b32_e32 v106, v0
	v_mov_b32_e32 v107, v0
	v_mov_b32_e32 v108, v0
	v_mov_b32_e32 v109, v0
	v_mov_b32_e32 v110, v0
	v_mov_b32_e32 v111, v0
	v_mov_b32_e32 v112, v0
	v_mov_b32_e32 v113, v0
	v_mov_b32_e32 v114, v0
	v_mov_b32_e32 v115, v0
	v_mov_b32_e32 v116, v0
	v_mov_b32_e32 v117, v0
	v_mov_b32_e32 v118, v0
	v_mov_b32_e32 v119, v0
	v_mov_b32_e32 v120, v0
	v_mov_b32_e32 v121, v0
	v_mov_b32_e32 v122, v0
	v_mov_b32_e32 v123, v0
	v_mov_b32_e32 v124, v0
	v_mov_b32_e32 v125, v0
	v_mov_b32_e32 v126, v0
	v_mov_b32_e32 v127, v0
	s_mov_b32 s94, 0

.Lp5gb_ep:
	s_cmp_eq_u32 s83, 1
	s_cselect_b32 s86, s34, s24
	s_cselect_b32 s87, s35, s25
	s_cmp_eq_u32 s83, 1
	s_cselect_b32 s84, s34, s24
	s_cselect_b32 s85, s35, s25
	global_load_dwordx4 v[128:131], v243, s[86:87]
	s_add_u32 s86, s86, 0x1000
	s_addc_u32 s87, s87, 0
	global_load_dwordx4 v[132:135], v243, s[86:87]
	s_add_u32 s86, s86, 0x1000
	s_addc_u32 s87, s87, 0
	global_load_dwordx4 v[136:139], v243, s[86:87]
	s_add_u32 s86, s86, 0x1000
	s_addc_u32 s87, s87, 0
	global_load_dwordx4 v[140:143], v243, s[86:87]
	s_add_u32 s86, s86, 0x1000
	s_addc_u32 s87, s87, 0
	global_load_dwordx4 v[148:151], v243, s[86:87]
	s_add_u32 s86, s86, 0x1000
	s_addc_u32 s87, s87, 0
	global_load_dwordx4 v[152:155], v243, s[86:87]
	s_add_u32 s86, s86, 0x1000
	s_addc_u32 s87, s87, 0
	global_load_dwordx4 v[156:159], v243, s[86:87]
	s_add_u32 s86, s86, 0x1000
	s_addc_u32 s87, s87, 0
	global_load_dwordx4 v[160:163], v243, s[86:87]
	s_add_u32 s86, s86, 0x1000
	s_addc_u32 s87, s87, 0
	s_waitcnt vmcnt(7)
	v_lshlrev_b32_e32 v164, 16, v128
	v_and_b32_e32 v165, 0xffff0000, v128
	v_lshlrev_b32_e32 v166, 16, v129
	v_and_b32_e32 v167, 0xffff0000, v129
	v_lshlrev_b32_e32 v172, 16, v130
	v_and_b32_e32 v173, 0xffff0000, v130
	v_lshlrev_b32_e32 v174, 16, v131
	v_and_b32_e32 v175, 0xffff0000, v131
	v_mul_f32_e32 v164, v0, v164
	v_mul_f32_e32 v165, v1, v165
	v_mul_f32_e32 v166, v2, v166
	v_mul_f32_e32 v167, v3, v167
	v_mul_f32_e32 v172, v4, v172
	v_mul_f32_e32 v173, v5, v173
	v_mul_f32_e32 v174, v6, v174
	v_mul_f32_e32 v175, v7, v175
	v_cvt_pk_bf16_f32 v184, v164, v165
	v_cvt_pk_bf16_f32 v185, v166, v167
	v_cvt_pk_bf16_f32 v186, v172, v173
	v_cvt_pk_bf16_f32 v187, v174, v175
	global_store_dwordx4 v243, v[184:187], s[84:85]
	s_add_u32 s84, s84, 0x1000
	s_addc_u32 s85, s85, 0
	s_waitcnt vmcnt(7)
	v_lshlrev_b32_e32 v164, 16, v132
	v_and_b32_e32 v165, 0xffff0000, v132
	v_lshlrev_b32_e32 v166, 16, v133
	v_and_b32_e32 v167, 0xffff0000, v133
	v_lshlrev_b32_e32 v172, 16, v134
	v_and_b32_e32 v173, 0xffff0000, v134
	v_lshlrev_b32_e32 v174, 16, v135
	v_and_b32_e32 v175, 0xffff0000, v135
	v_mul_f32_e32 v164, v8, v164
	v_mul_f32_e32 v165, v9, v165
	v_mul_f32_e32 v166, v10, v166
	v_mul_f32_e32 v167, v11, v167
	v_mul_f32_e32 v172, v12, v172
	v_mul_f32_e32 v173, v13, v173
	v_mul_f32_e32 v174, v14, v174
	v_mul_f32_e32 v175, v15, v175
	v_cvt_pk_bf16_f32 v188, v164, v165
	v_cvt_pk_bf16_f32 v189, v166, v167
	v_cvt_pk_bf16_f32 v190, v172, v173
	v_cvt_pk_bf16_f32 v191, v174, v175
	global_store_dwordx4 v243, v[188:191], s[84:85]
	s_add_u32 s84, s84, 0x1000
	s_addc_u32 s85, s85, 0
	s_waitcnt vmcnt(7)
	v_lshlrev_b32_e32 v164, 16, v136
	v_and_b32_e32 v165, 0xffff0000, v136
	v_lshlrev_b32_e32 v166, 16, v137
	v_and_b32_e32 v167, 0xffff0000, v137
	v_lshlrev_b32_e32 v172, 16, v138
	v_and_b32_e32 v173, 0xffff0000, v138
	v_lshlrev_b32_e32 v174, 16, v139
	v_and_b32_e32 v175, 0xffff0000, v139
	v_mul_f32_e32 v164, v16, v164
	v_mul_f32_e32 v165, v17, v165
	v_mul_f32_e32 v166, v18, v166
	v_mul_f32_e32 v167, v19, v167
	v_mul_f32_e32 v172, v20, v172
	v_mul_f32_e32 v173, v21, v173
	v_mul_f32_e32 v174, v22, v174
	v_mul_f32_e32 v175, v23, v175
	v_cvt_pk_bf16_f32 v184, v164, v165
	v_cvt_pk_bf16_f32 v185, v166, v167
	v_cvt_pk_bf16_f32 v186, v172, v173
	v_cvt_pk_bf16_f32 v187, v174, v175
	global_store_dwordx4 v243, v[184:187], s[84:85]
	s_add_u32 s84, s84, 0x1000
	s_addc_u32 s85, s85, 0
	s_waitcnt vmcnt(7)
	v_lshlrev_b32_e32 v164, 16, v140
	v_and_b32_e32 v165, 0xffff0000, v140
	v_lshlrev_b32_e32 v166, 16, v141
	v_and_b32_e32 v167, 0xffff0000, v141
	v_lshlrev_b32_e32 v172, 16, v142
	v_and_b32_e32 v173, 0xffff0000, v142
	v_lshlrev_b32_e32 v174, 16, v143
	v_and_b32_e32 v175, 0xffff0000, v143
	v_mul_f32_e32 v164, v24, v164
	v_mul_f32_e32 v165, v25, v165
	v_mul_f32_e32 v166, v26, v166
	v_mul_f32_e32 v167, v27, v167
	v_mul_f32_e32 v172, v28, v172
	v_mul_f32_e32 v173, v29, v173
	v_mul_f32_e32 v174, v30, v174
	v_mul_f32_e32 v175, v31, v175
	v_cvt_pk_bf16_f32 v188, v164, v165
	v_cvt_pk_bf16_f32 v189, v166, v167
	v_cvt_pk_bf16_f32 v190, v172, v173
	v_cvt_pk_bf16_f32 v191, v174, v175
	global_store_dwordx4 v243, v[188:191], s[84:85]
	s_add_u32 s84, s84, 0x1000
	s_addc_u32 s85, s85, 0
	s_waitcnt vmcnt(7)
	v_lshlrev_b32_e32 v164, 16, v148
	v_and_b32_e32 v165, 0xffff0000, v148
	v_lshlrev_b32_e32 v166, 16, v149
	v_and_b32_e32 v167, 0xffff0000, v149
	v_lshlrev_b32_e32 v172, 16, v150
	v_and_b32_e32 v173, 0xffff0000, v150
	v_lshlrev_b32_e32 v174, 16, v151
	v_and_b32_e32 v175, 0xffff0000, v151
	v_mul_f32_e32 v164, v32, v164
	v_mul_f32_e32 v165, v33, v165
	v_mul_f32_e32 v166, v34, v166
	v_mul_f32_e32 v167, v35, v167
	v_mul_f32_e32 v172, v36, v172
	v_mul_f32_e32 v173, v37, v173
	v_mul_f32_e32 v174, v38, v174
	v_mul_f32_e32 v175, v39, v175
	v_cvt_pk_bf16_f32 v184, v164, v165
	v_cvt_pk_bf16_f32 v185, v166, v167
	v_cvt_pk_bf16_f32 v186, v172, v173
	v_cvt_pk_bf16_f32 v187, v174, v175
	global_store_dwordx4 v243, v[184:187], s[84:85]
	s_add_u32 s84, s84, 0x1000
	s_addc_u32 s85, s85, 0
	s_waitcnt vmcnt(7)
	v_lshlrev_b32_e32 v164, 16, v152
	v_and_b32_e32 v165, 0xffff0000, v152
	v_lshlrev_b32_e32 v166, 16, v153
	v_and_b32_e32 v167, 0xffff0000, v153
	v_lshlrev_b32_e32 v172, 16, v154
	v_and_b32_e32 v173, 0xffff0000, v154
	v_lshlrev_b32_e32 v174, 16, v155
	v_and_b32_e32 v175, 0xffff0000, v155
	v_mul_f32_e32 v164, v40, v164
	v_mul_f32_e32 v165, v41, v165
	v_mul_f32_e32 v166, v42, v166
	v_mul_f32_e32 v167, v43, v167
	v_mul_f32_e32 v172, v44, v172
	v_mul_f32_e32 v173, v45, v173
	v_mul_f32_e32 v174, v46, v174
	v_mul_f32_e32 v175, v47, v175
	v_cvt_pk_bf16_f32 v188, v164, v165
	v_cvt_pk_bf16_f32 v189, v166, v167
	v_cvt_pk_bf16_f32 v190, v172, v173
	v_cvt_pk_bf16_f32 v191, v174, v175
	global_store_dwordx4 v243, v[188:191], s[84:85]
	s_add_u32 s84, s84, 0x1000
	s_addc_u32 s85, s85, 0
	s_waitcnt vmcnt(7)
	v_lshlrev_b32_e32 v164, 16, v156
	v_and_b32_e32 v165, 0xffff0000, v156
	v_lshlrev_b32_e32 v166, 16, v157
	v_and_b32_e32 v167, 0xffff0000, v157
	v_lshlrev_b32_e32 v172, 16, v158
	v_and_b32_e32 v173, 0xffff0000, v158
	v_lshlrev_b32_e32 v174, 16, v159
	v_and_b32_e32 v175, 0xffff0000, v159
	v_mul_f32_e32 v164, v48, v164
	v_mul_f32_e32 v165, v49, v165
	v_mul_f32_e32 v166, v50, v166
	v_mul_f32_e32 v167, v51, v167
	v_mul_f32_e32 v172, v52, v172
	v_mul_f32_e32 v173, v53, v173
	v_mul_f32_e32 v174, v54, v174
	v_mul_f32_e32 v175, v55, v175
	v_cvt_pk_bf16_f32 v184, v164, v165
	v_cvt_pk_bf16_f32 v185, v166, v167
	v_cvt_pk_bf16_f32 v186, v172, v173
	v_cvt_pk_bf16_f32 v187, v174, v175
	global_store_dwordx4 v243, v[184:187], s[84:85]
	s_add_u32 s84, s84, 0x1000
	s_addc_u32 s85, s85, 0
	s_waitcnt vmcnt(7)
	v_lshlrev_b32_e32 v164, 16, v160
	v_and_b32_e32 v165, 0xffff0000, v160
	v_lshlrev_b32_e32 v166, 16, v161
	v_and_b32_e32 v167, 0xffff0000, v161
	v_lshlrev_b32_e32 v172, 16, v162
	v_and_b32_e32 v173, 0xffff0000, v162
	v_lshlrev_b32_e32 v174, 16, v163
	v_and_b32_e32 v175, 0xffff0000, v163
	v_mul_f32_e32 v164, v56, v164
	v_mul_f32_e32 v165, v57, v165
	v_mul_f32_e32 v166, v58, v166
	v_mul_f32_e32 v167, v59, v167
	v_mul_f32_e32 v172, v60, v172
	v_mul_f32_e32 v173, v61, v173
	v_mul_f32_e32 v174, v62, v174
	v_mul_f32_e32 v175, v63, v175
	v_cvt_pk_bf16_f32 v188, v164, v165
	v_cvt_pk_bf16_f32 v189, v166, v167
	v_cvt_pk_bf16_f32 v190, v172, v173
	v_cvt_pk_bf16_f32 v191, v174, v175
	global_store_dwordx4 v243, v[188:191], s[84:85]
	s_add_u32 s84, s84, 0x1000
	s_addc_u32 s85, s85, 0
	s_cmp_eq_u32 s83, 1
	s_cbranch_scc1 .Lp5gb_epdone
	s_cmp_eq_u32 s95, 1
	s_cbranch_scc0 .Lp5gb_epdone
	v_mov_b32_e32 v0, v64
	v_mov_b32_e32 v1, v65
	v_mov_b32_e32 v2, v66
	v_mov_b32_e32 v3, v67
	v_mov_b32_e32 v4, v68
	v_mov_b32_e32 v5, v69
	v_mov_b32_e32 v6, v70
	v_mov_b32_e32 v7, v71
	v_mov_b32_e32 v8, v72
	v_mov_b32_e32 v9, v73
	v_mov_b32_e32 v10, v74
	v_mov_b32_e32 v11, v75
	v_mov_b32_e32 v12, v76
	v_mov_b32_e32 v13, v77
	v_mov_b32_e32 v14, v78
	v_mov_b32_e32 v15, v79
	v_mov_b32_e32 v16, v80
	v_mov_b32_e32 v17, v81
	v_mov_b32_e32 v18, v82
	v_mov_b32_e32 v19, v83
	v_mov_b32_e32 v20, v84
	v_mov_b32_e32 v21, v85
	v_mov_b32_e32 v22, v86
	v_mov_b32_e32 v23, v87
	v_mov_b32_e32 v24, v88
	v_mov_b32_e32 v25, v89
	v_mov_b32_e32 v26, v90
	v_mov_b32_e32 v27, v91
	v_mov_b32_e32 v28, v92
	v_mov_b32_e32 v29, v93
	v_mov_b32_e32 v30, v94
	v_mov_b32_e32 v31, v95
	v_mov_b32_e32 v32, v96
	v_mov_b32_e32 v33, v97
	v_mov_b32_e32 v34, v98
	v_mov_b32_e32 v35, v99
	v_mov_b32_e32 v36, v100
	v_mov_b32_e32 v37, v101
	v_mov_b32_e32 v38, v102
	v_mov_b32_e32 v39, v103
	v_mov_b32_e32 v40, v104
	v_mov_b32_e32 v41, v105
	v_mov_b32_e32 v42, v106
	v_mov_b32_e32 v43, v107
	v_mov_b32_e32 v44, v108
	v_mov_b32_e32 v45, v109
	v_mov_b32_e32 v46, v110
	v_mov_b32_e32 v47, v111
	v_mov_b32_e32 v48, v112
	v_mov_b32_e32 v49, v113
	v_mov_b32_e32 v50, v114
	v_mov_b32_e32 v51, v115
	v_mov_b32_e32 v52, v116
	v_mov_b32_e32 v53, v117
	v_mov_b32_e32 v54, v118
	v_mov_b32_e32 v55, v119
	v_mov_b32_e32 v56, v120
	v_mov_b32_e32 v57, v121
	v_mov_b32_e32 v58, v122
	v_mov_b32_e32 v59, v123
	v_mov_b32_e32 v60, v124
	v_mov_b32_e32 v61, v125
	v_mov_b32_e32 v62, v126
	v_mov_b32_e32 v63, v127
	s_mov_b32 s83, 1
	s_branch .Lp5gb_ep

.Lp5_gemm_end:
	s_cmp_lt_u32 s2, 0x100
	s_cbranch_scc0 .Lp5_body
.Lp5_done:
	s_cmp_lt_u32 s55, 7
	s_cbranch_scc1 .LBB0_449
	s_waitcnt vmcnt(0)
	s_waitcnt vmcnt(0)
	s_barrier
	s_and_saveexec_b64 s[6:7], s[4:5]
	s_cbranch_execz .LBB0_448
	v_mov_b32_e32 v16, 0
	s_waitcnt vmcnt(0) expcnt(0) lgkmcnt(0)
	ds_read_b32 v2, v16
	ds_read_b32 v0, v16 offset:4
	s_waitcnt lgkmcnt(1)
	v_cmp_ne_u32_e32 vcc, 0, v2
	s_cbranch_vccnz .LBB0_412
	s_add_u32 s8, s46, 0x1000
	s_addc_u32 s9, s47, 0
	s_add_u32 s10, s46, 0x1100
	s_addc_u32 s11, s47, 0
	s_add_u32 s12, s46, 0x1200
	s_addc_u32 s13, s47, 0
	s_mul_i32 s3, s53, s78
	s_add_u32 s14, s46, 0x1300
	s_mul_i32 s3, s3, s52
	s_addc_u32 s15, s47, 0
	s_mov_b32 s22, 1
	s_branch .LBB0_400

.Lp6_dec:
	s_load_dwordx2 s[22:23], s[0:1], 0x60
	s_load_dwordx2 s[24:25], s[0:1], 0xf0
	s_load_dwordx2 s[34:35], s[0:1], 0x108
	s_load_dwordx2 s[26:27], s[0:1], 0xd8
	s_mov_b32 s3, 0x7fff
	v_mov_b32_e32 v242, 1
	v_lshlrev_b32_e32 v243, 4, v168
	v_bfe_u32 v249, v168, 6, 1
	v_bfe_u32 v250, v168, 4, 2
	v_lshlrev_b32_e32 v250, 4, v250
	v_lshl_or_b32 v244, v249, 8, v250
	s_lshl_b32 s71, s74, 9
	s_and_b32 s72, s2, 7
	s_lshl_b32 s72, s72, 22
	s_lshr_b32 s73, s2, 3
	s_lshl_b32 s73, s73, 16
	s_add_u32 s72, s72, s73
	s_lshl_b32 s73, s2, 16
	s_waitcnt lgkmcnt(0)
	s_add_u32 s22, s22, s71
	s_addc_u32 s23, s23, 0
	s_add_u32 s24, s24, s72
	s_addc_u32 s25, s25, 0
	s_add_u32 s34, s34, s73
	s_addc_u32 s35, s35, 0
	s_cmp_eq_u32 s52, 0x200
	s_cbranch_scc1 .Lp6_site_c
.Lp6_site_a:
	v_and_b32_e32 v236, 15, v168
	v_lshrrev_b32_e32 v237, 1, v236
	v_bfe_u32 v238, v168, 4, 2
	v_xor_b32_e32 v237, v237, v238
	v_lshlrev_b32_e32 v237, 4, v237
	v_lshl_or_b32 v236, v236, 7, v237
	v_xor_b32_e32 v237, 64, v236
	v_add_u32_e32 v236, 16, v236
	v_add_u32_e32 v237, 16, v237
	v_bfe_u32 v238, v168, 7, 1
	v_lshl_add_u32 v240, v238, 13, v237
	v_lshl_add_u32 v238, v238, 13, v236
	v_bfe_u32 v239, v168, 6, 1
	v_lshl_add_u32 v241, v239, 13, v237
	v_lshl_add_u32 v239, v239, 13, v236
	v_lshrrev_b32_e32 v236, 3, v168
	v_lshrrev_b32_e32 v237, 4, v168
	v_xor_b32_e32 v237, v237, v168
	v_and_b32_e32 v237, 7, v237
	v_lshlrev_b32_e32 v237, 4, v237
	v_lshl_or_b32 v232, v236, 11, v237
	v_add_u32_e32 v233, 0x10000, v232
	v_add_u32_e32 v234, 0x20000, v232
	v_add_u32_e32 v235, 0x30000, v232
	s_load_dwordx2 s[90:91], s[0:1], 0xa0
	s_load_dwordx2 s[92:93], s[0:1], 0xa8
	v_lshrrev_b32_e32 v237, 6, v168
	s_nop 1
	v_readfirstlane_b32 s97, v237
	s_nop 3
	s_lshl_b32 s96, s97, 10
	s_add_u32 s96, s96, 16
	s_add_u32 s94, s81, s80
	s_cmp_lt_i32 s94, s82
	s_cselect_b32 s95, 1, 0
	s_cmp_lg_u64 s[20:21], 0
	s_cselect_b32 s95, 0, s95
	s_cmp_ge_u32 s94, 0x40
	s_cselect_b32 s97, 1, 0
	s_mul_i32 s100, s97, 0x40
	s_sub_u32 s100, s94, s100
	s_lshr_b32 s101, s100, 3
	s_and_b32 s100, s100, 7
	s_lshl_b32 s97, s97, 3
	s_add_u32 s100, s100, s97
	s_add_u32 s100, s100, s79
	s_cmp_lg_u32 s101, s74
	s_cselect_b32 s95, 0, s95
	s_cmp_eq_u32 s95, 1
	s_cselect_b32 s101, s100, s70
	s_mov_b32 s97, s101
	s_waitcnt lgkmcnt(0)
	s_lshl_b32 s94, s74, 18
	s_add_u32 s94, s94, 0xc40000
	s_add_u32 s98, s92, s94
	s_addc_u32 s99, s93, 0
	s_lshl_b32 s101, s101, 18
	s_add_u32 s92, s90, s101
	s_addc_u32 s93, s91, 0
	s_lshl_b32 s94, s70, 18
	s_add_u32 s90, s90, s94
	s_addc_u32 s91, s91, 0
	s_mov_b64 s[100:101], s[90:91]
	s_mov_b64 s[90:91], s[98:99]
	s_mov_b64 s[98:99], s[92:93]
	s_mov_b64 s[92:93], s[100:101]
	s_waitcnt vmcnt(0)
	s_barrier
	s_add_u32 m0, s96, 0x0
	s_nop 0
	global_load_lds_dwordx4 v232, s[90:91]
	s_add_u32 m0, s96, 0x1000
	s_nop 0
	global_load_lds_dwordx4 v233, s[90:91]
	s_add_u32 m0, s96, 0x2000
	s_nop 0
	global_load_lds_dwordx4 v234, s[90:91]
	s_add_u32 m0, s96, 0x3000
	s_nop 0
	global_load_lds_dwordx4 v235, s[90:91]
	s_add_u32 m0, s96, 0x8000
	s_nop 0
	global_load_lds_dwordx4 v232, s[92:93]
	s_add_u32 m0, s96, 0x9000
	s_nop 0
	global_load_lds_dwordx4 v233, s[92:93]
	s_add_u32 m0, s96, 0xa000
	s_nop 0
	global_load_lds_dwordx4 v234, s[92:93]
	s_add_u32 m0, s96, 0xb000
	s_nop 0
	global_load_lds_dwordx4 v235, s[92:93]
	s_add_u32 m0, s96, 0xc000
	s_nop 0
	global_load_lds_dwordx4 v232, s[98:99]
	s_add_u32 m0, s96, 0xd000
	s_nop 0
	global_load_lds_dwordx4 v233, s[98:99]
	s_add_u32 m0, s96, 0xe000
	s_nop 0
	global_load_lds_dwordx4 v234, s[98:99]
	s_add_u32 m0, s96, 0xf000
	s_nop 0
	global_load_lds_dwordx4 v235, s[98:99]
	s_add_u32 s90, s90, 0x80
	s_addc_u32 s91, s91, 0
	s_add_u32 s92, s92, 0x80
	s_addc_u32 s93, s93, 0
	s_add_u32 s98, s98, 0x80
	s_addc_u32 s99, s99, 0
	v_mov_b32_e32 v0, 0
	v_mov_b32_e32 v1, v0
	v_mov_b32_e32 v2, v0
	v_mov_b32_e32 v3, v0
	v_mov_b32_e32 v4, v0
	v_mov_b32_e32 v5, v0
	v_mov_b32_e32 v6, v0
	v_mov_b32_e32 v7, v0
	v_mov_b32_e32 v8, v0
	v_mov_b32_e32 v9, v0
	v_mov_b32_e32 v10, v0
	v_mov_b32_e32 v11, v0
	v_mov_b32_e32 v12, v0
	v_mov_b32_e32 v13, v0
	v_mov_b32_e32 v14, v0
	v_mov_b32_e32 v15, v0
	v_mov_b32_e32 v16, v0
	v_mov_b32_e32 v17, v0
	v_mov_b32_e32 v18, v0
	v_mov_b32_e32 v19, v0
	v_mov_b32_e32 v20, v0
	v_mov_b32_e32 v21, v0
	v_mov_b32_e32 v22, v0
	v_mov_b32_e32 v23, v0
	v_mov_b32_e32 v24, v0
	v_mov_b32_e32 v25, v0
	v_mov_b32_e32 v26, v0
	v_mov_b32_e32 v27, v0
	v_mov_b32_e32 v28, v0
	v_mov_b32_e32 v29, v0
	v_mov_b32_e32 v30, v0
	v_mov_b32_e32 v31, v0
	v_mov_b32_e32 v32, v0
	v_mov_b32_e32 v33, v0
	v_mov_b32_e32 v34, v0
	v_mov_b32_e32 v35, v0
	v_mov_b32_e32 v36, v0
	v_mov_b32_e32 v37, v0
	v_mov_b32_e32 v38, v0
	v_mov_b32_e32 v39, v0
	v_mov_b32_e32 v40, v0
	v_mov_b32_e32 v41, v0
	v_mov_b32_e32 v42, v0
	v_mov_b32_e32 v43, v0
	v_mov_b32_e32 v44, v0
	v_mov_b32_e32 v45, v0
	v_mov_b32_e32 v46, v0
	v_mov_b32_e32 v47, v0
	v_mov_b32_e32 v48, v0
	v_mov_b32_e32 v49, v0
	v_mov_b32_e32 v50, v0
	v_mov_b32_e32 v51, v0
	v_mov_b32_e32 v52, v0
	v_mov_b32_e32 v53, v0
	v_mov_b32_e32 v54, v0
	v_mov_b32_e32 v55, v0
	v_mov_b32_e32 v56, v0
	v_mov_b32_e32 v57, v0
	v_mov_b32_e32 v58, v0
	v_mov_b32_e32 v59, v0
	v_mov_b32_e32 v60, v0
	v_mov_b32_e32 v61, v0
	v_mov_b32_e32 v62, v0
	v_mov_b32_e32 v63, v0
	v_mov_b32_e32 v64, v0
	v_mov_b32_e32 v65, v0
	v_mov_b32_e32 v66, v0
	v_mov_b32_e32 v67, v0
	v_mov_b32_e32 v68, v0
	v_mov_b32_e32 v69, v0
	v_mov_b32_e32 v70, v0
	v_mov_b32_e32 v71, v0
	v_mov_b32_e32 v72, v0
	v_mov_b32_e32 v73, v0
	v_mov_b32_e32 v74, v0
	v_mov_b32_e32 v75, v0
	v_mov_b32_e32 v76, v0
	v_mov_b32_e32 v77, v0
	v_mov_b32_e32 v78, v0
	v_mov_b32_e32 v79, v0
	v_mov_b32_e32 v80, v0
	v_mov_b32_e32 v81, v0
	v_mov_b32_e32 v82, v0
	v_mov_b32_e32 v83, v0
	v_mov_b32_e32 v84, v0
	v_mov_b32_e32 v85, v0
	v_mov_b32_e32 v86, v0
	v_mov_b32_e32 v87, v0
	v_mov_b32_e32 v88, v0
	v_mov_b32_e32 v89, v0
	v_mov_b32_e32 v90, v0
	v_mov_b32_e32 v91, v0
	v_mov_b32_e32 v92, v0
	v_mov_b32_e32 v93, v0
	v_mov_b32_e32 v94, v0
	v_mov_b32_e32 v95, v0
	v_mov_b32_e32 v96, v0
	v_mov_b32_e32 v97, v0
	v_mov_b32_e32 v98, v0
	v_mov_b32_e32 v99, v0
	v_mov_b32_e32 v100, v0
	v_mov_b32_e32 v101, v0
	v_mov_b32_e32 v102, v0
	v_mov_b32_e32 v103, v0
	v_mov_b32_e32 v104, v0
	v_mov_b32_e32 v105, v0
	v_mov_b32_e32 v106, v0
	v_mov_b32_e32 v107, v0
	v_mov_b32_e32 v108, v0
	v_mov_b32_e32 v109, v0
	v_mov_b32_e32 v110, v0
	v_mov_b32_e32 v111, v0
	v_mov_b32_e32 v112, v0
	v_mov_b32_e32 v113, v0
	v_mov_b32_e32 v114, v0
	v_mov_b32_e32 v115, v0
	v_mov_b32_e32 v116, v0
	v_mov_b32_e32 v117, v0
	v_mov_b32_e32 v118, v0
	v_mov_b32_e32 v119, v0
	v_mov_b32_e32 v120, v0
	v_mov_b32_e32 v121, v0
	v_mov_b32_e32 v122, v0
	v_mov_b32_e32 v123, v0
	v_mov_b32_e32 v124, v0
	v_mov_b32_e32 v125, v0
	v_mov_b32_e32 v126, v0
	v_mov_b32_e32 v127, v0
	s_mov_b32 s94, 0

.Lp6a_epdone:
.Lp6_site_b:
	v_lshrrev_b32_e32 v236, 3, v168
	v_lshrrev_b32_e32 v237, 4, v168
	v_xor_b32_e32 v237, v237, v168
	v_and_b32_e32 v237, 7, v237
	v_lshlrev_b32_e32 v237, 4, v237
	v_lshl_or_b32 v232, v236, 11, v237
	v_add_u32_e32 v233, 0x10000, v232
	v_add_u32_e32 v234, 0x20000, v232
	v_add_u32_e32 v235, 0x30000, v232
	s_load_dwordx2 s[90:91], s[0:1], 0xa0
	s_load_dwordx2 s[92:93], s[0:1], 0xb0
	v_lshrrev_b32_e32 v237, 6, v168
	s_nop 1
	v_readfirstlane_b32 s97, v237
	s_nop 3
	s_lshl_b32 s96, s97, 10
	s_add_u32 s96, s96, 16
	s_add_u32 s94, s81, s80
	s_cmp_lt_i32 s94, s82
	s_cselect_b32 s95, 1, 0
	s_cmp_lg_u64 s[20:21], 0
	s_cselect_b32 s95, 0, s95
	s_cmp_ge_u32 s94, 0x40
	s_cselect_b32 s97, 1, 0
	s_mul_i32 s100, s97, 0x40
	s_sub_u32 s100, s94, s100
	s_lshr_b32 s101, s100, 3
	s_and_b32 s100, s100, 7
	s_lshl_b32 s97, s97, 3
	s_add_u32 s100, s100, s97
	s_add_u32 s100, s100, s79
	s_cmp_lg_u32 s101, s74
	s_cselect_b32 s95, 0, s95
	s_cmp_eq_u32 s95, 1
	s_cselect_b32 s101, s100, s70
	s_mov_b32 s97, s101
	s_waitcnt lgkmcnt(0)
	s_lshl_b32 s94, s74, 18
	s_add_u32 s98, s92, s94
	s_addc_u32 s99, s93, 0
	s_lshl_b32 s101, s101, 18
	s_add_u32 s101, s101, 0x2000000
	s_add_u32 s92, s90, s101
	s_addc_u32 s93, s91, 0
	s_lshl_b32 s94, s70, 18
	s_add_u32 s94, s94, 0x2000000
	s_add_u32 s90, s90, s94
	s_addc_u32 s91, s91, 0
	s_mov_b64 s[100:101], s[90:91]
	s_mov_b64 s[90:91], s[98:99]
	s_mov_b64 s[98:99], s[92:93]
	s_mov_b64 s[92:93], s[100:101]
	s_waitcnt vmcnt(0)
	s_barrier
	s_add_u32 m0, s96, 0x0
	s_nop 0
	global_load_lds_dwordx4 v232, s[90:91]
	s_add_u32 m0, s96, 0x1000
	s_nop 0
	global_load_lds_dwordx4 v233, s[90:91]
	s_add_u32 m0, s96, 0x2000
	s_nop 0
	global_load_lds_dwordx4 v234, s[90:91]
	s_add_u32 m0, s96, 0x3000
	s_nop 0
	global_load_lds_dwordx4 v235, s[90:91]
	s_add_u32 m0, s96, 0x8000
	s_nop 0
	global_load_lds_dwordx4 v232, s[92:93]
	s_add_u32 m0, s96, 0x9000
	s_nop 0
	global_load_lds_dwordx4 v233, s[92:93]
	s_add_u32 m0, s96, 0xa000
	s_nop 0
	global_load_lds_dwordx4 v234, s[92:93]
	s_add_u32 m0, s96, 0xb000
	s_nop 0
	global_load_lds_dwordx4 v235, s[92:93]
	s_add_u32 m0, s96, 0xc000
	s_nop 0
	global_load_lds_dwordx4 v232, s[98:99]
	s_add_u32 m0, s96, 0xd000
	s_nop 0
	global_load_lds_dwordx4 v233, s[98:99]
	s_add_u32 m0, s96, 0xe000
	s_nop 0
	global_load_lds_dwordx4 v234, s[98:99]
	s_add_u32 m0, s96, 0xf000
	s_nop 0
	global_load_lds_dwordx4 v235, s[98:99]
	s_add_u32 s90, s90, 0x80
	s_addc_u32 s91, s91, 0
	s_add_u32 s92, s92, 0x80
	s_addc_u32 s93, s93, 0
	s_add_u32 s98, s98, 0x80
	s_addc_u32 s99, s99, 0
	v_mov_b32_e32 v0, 0
	v_mov_b32_e32 v1, v0
	v_mov_b32_e32 v2, v0
	v_mov_b32_e32 v3, v0
	v_mov_b32_e32 v4, v0
	v_mov_b32_e32 v5, v0
	v_mov_b32_e32 v6, v0
	v_mov_b32_e32 v7, v0
	v_mov_b32_e32 v8, v0
	v_mov_b32_e32 v9, v0
	v_mov_b32_e32 v10, v0
	v_mov_b32_e32 v11, v0
	v_mov_b32_e32 v12, v0
	v_mov_b32_e32 v13, v0
	v_mov_b32_e32 v14, v0
	v_mov_b32_e32 v15, v0
	v_mov_b32_e32 v16, v0
	v_mov_b32_e32 v17, v0
	v_mov_b32_e32 v18, v0
	v_mov_b32_e32 v19, v0
	v_mov_b32_e32 v20, v0
	v_mov_b32_e32 v21, v0
	v_mov_b32_e32 v22, v0
	v_mov_b32_e32 v23, v0
	v_mov_b32_e32 v24, v0
	v_mov_b32_e32 v25, v0
	v_mov_b32_e32 v26, v0
	v_mov_b32_e32 v27, v0
	v_mov_b32_e32 v28, v0
	v_mov_b32_e32 v29, v0
	v_mov_b32_e32 v30, v0
	v_mov_b32_e32 v31, v0
	v_mov_b32_e32 v32, v0
	v_mov_b32_e32 v33, v0
	v_mov_b32_e32 v34, v0
	v_mov_b32_e32 v35, v0
	v_mov_b32_e32 v36, v0
	v_mov_b32_e32 v37, v0
	v_mov_b32_e32 v38, v0
	v_mov_b32_e32 v39, v0
	v_mov_b32_e32 v40, v0
	v_mov_b32_e32 v41, v0
	v_mov_b32_e32 v42, v0
	v_mov_b32_e32 v43, v0
	v_mov_b32_e32 v44, v0
	v_mov_b32_e32 v45, v0
	v_mov_b32_e32 v46, v0
	v_mov_b32_e32 v47, v0
	v_mov_b32_e32 v48, v0
	v_mov_b32_e32 v49, v0
	v_mov_b32_e32 v50, v0
	v_mov_b32_e32 v51, v0
	v_mov_b32_e32 v52, v0
	v_mov_b32_e32 v53, v0
	v_mov_b32_e32 v54, v0
	v_mov_b32_e32 v55, v0
	v_mov_b32_e32 v56, v0
	v_mov_b32_e32 v57, v0
	v_mov_b32_e32 v58, v0
	v_mov_b32_e32 v59, v0
	v_mov_b32_e32 v60, v0
	v_mov_b32_e32 v61, v0
	v_mov_b32_e32 v62, v0
	v_mov_b32_e32 v63, v0
	v_mov_b32_e32 v64, v0
	v_mov_b32_e32 v65, v0
	v_mov_b32_e32 v66, v0
	v_mov_b32_e32 v67, v0
	v_mov_b32_e32 v68, v0
	v_mov_b32_e32 v69, v0
	v_mov_b32_e32 v70, v0
	v_mov_b32_e32 v71, v0
	v_mov_b32_e32 v72, v0
	v_mov_b32_e32 v73, v0
	v_mov_b32_e32 v74, v0
	v_mov_b32_e32 v75, v0
	v_mov_b32_e32 v76, v0
	v_mov_b32_e32 v77, v0
	v_mov_b32_e32 v78, v0
	v_mov_b32_e32 v79, v0
	v_mov_b32_e32 v80, v0
	v_mov_b32_e32 v81, v0
	v_mov_b32_e32 v82, v0
	v_mov_b32_e32 v83, v0
	v_mov_b32_e32 v84, v0
	v_mov_b32_e32 v85, v0
	v_mov_b32_e32 v86, v0
	v_mov_b32_e32 v87, v0
	v_mov_b32_e32 v88, v0
	v_mov_b32_e32 v89, v0
	v_mov_b32_e32 v90, v0
	v_mov_b32_e32 v91, v0
	v_mov_b32_e32 v92, v0
	v_mov_b32_e32 v93, v0
	v_mov_b32_e32 v94, v0
	v_mov_b32_e32 v95, v0
	v_mov_b32_e32 v96, v0
	v_mov_b32_e32 v97, v0
	v_mov_b32_e32 v98, v0
	v_mov_b32_e32 v99, v0
	v_mov_b32_e32 v100, v0
	v_mov_b32_e32 v101, v0
	v_mov_b32_e32 v102, v0
	v_mov_b32_e32 v103, v0
	v_mov_b32_e32 v104, v0
	v_mov_b32_e32 v105, v0
	v_mov_b32_e32 v106, v0
	v_mov_b32_e32 v107, v0
	v_mov_b32_e32 v108, v0
	v_mov_b32_e32 v109, v0
	v_mov_b32_e32 v110, v0
	v_mov_b32_e32 v111, v0
	v_mov_b32_e32 v112, v0
	v_mov_b32_e32 v113, v0
	v_mov_b32_e32 v114, v0
	v_mov_b32_e32 v115, v0
	v_mov_b32_e32 v116, v0
	v_mov_b32_e32 v117, v0
	v_mov_b32_e32 v118, v0
	v_mov_b32_e32 v119, v0
	v_mov_b32_e32 v120, v0
	v_mov_b32_e32 v121, v0
	v_mov_b32_e32 v122, v0
	v_mov_b32_e32 v123, v0
	v_mov_b32_e32 v124, v0
	v_mov_b32_e32 v125, v0
	v_mov_b32_e32 v126, v0
	v_mov_b32_e32 v127, v0
	s_mov_b32 s94, 0

.Lp6b_epdone:
.Lp6_site_c:
	v_and_b32_e32 v236, 15, v168
	v_lshrrev_b32_e32 v237, 1, v236
	v_bfe_u32 v238, v168, 4, 2
	v_xor_b32_e32 v237, v237, v238
	v_lshlrev_b32_e32 v237, 4, v237
	v_lshl_or_b32 v236, v236, 7, v237
	v_xor_b32_e32 v237, 64, v236
	v_add_u32_e32 v236, 16, v236
	v_add_u32_e32 v237, 16, v237
	v_bfe_u32 v238, v168, 7, 1
	v_lshl_add_u32 v240, v238, 13, v237
	v_lshl_add_u32 v238, v238, 13, v236
	v_bfe_u32 v239, v168, 6, 1
	v_lshl_add_u32 v241, v239, 13, v237
	v_lshl_add_u32 v239, v239, 13, v236
	v_lshrrev_b32_e32 v236, 3, v168
	v_lshrrev_b32_e32 v237, 4, v168
	v_xor_b32_e32 v237, v237, v168
	v_and_b32_e32 v237, 7, v237
	v_lshlrev_b32_e32 v237, 4, v237
	v_lshl_or_b32 v232, v236, 11, v237
	v_add_u32_e32 v233, 0x10000, v232
	v_add_u32_e32 v234, 0x20000, v232
	v_add_u32_e32 v235, 0x30000, v232
	s_load_dwordx2 s[90:91], s[0:1], 0x100
	s_load_dwordx2 s[92:93], s[0:1], 0xb8
	v_lshrrev_b32_e32 v237, 6, v168
	s_nop 1
	v_readfirstlane_b32 s97, v237
	s_nop 3
	s_lshl_b32 s96, s97, 10
	s_add_u32 s96, s96, 16
	s_add_u32 s94, s81, s80
	s_cmp_lt_i32 s94, s82
	s_cselect_b32 s95, 1, 0
	s_cmp_lg_u64 s[20:21], 0
	s_cselect_b32 s95, 0, s95
	s_cmp_ge_u32 s94, 0x40
	s_cselect_b32 s97, 1, 0
	s_mul_i32 s100, s97, 0x40
	s_sub_u32 s100, s94, s100
	s_lshr_b32 s101, s100, 3
	s_and_b32 s100, s100, 7
	s_lshl_b32 s97, s97, 3
	s_add_u32 s100, s100, s97
	s_add_u32 s100, s100, s79
	s_cmp_lg_u32 s101, s74
	s_cselect_b32 s95, 0, s95
	s_cmp_eq_u32 s95, 1
	s_cselect_b32 s101, s100, s70
	s_mov_b32 s97, s101
	s_waitcnt lgkmcnt(0)
	s_lshl_b32 s94, s74, 18
	s_add_u32 s98, s92, s94
	s_addc_u32 s99, s93, 0
	s_lshl_b32 s101, s101, 18
	s_add_u32 s92, s90, s101
	s_addc_u32 s93, s91, 0
	s_lshl_b32 s94, s70, 18
	s_add_u32 s90, s90, s94
	s_addc_u32 s91, s91, 0
	s_mov_b64 s[100:101], s[90:91]
	s_mov_b64 s[90:91], s[98:99]
	s_mov_b64 s[98:99], s[92:93]
	s_mov_b64 s[92:93], s[100:101]
	s_waitcnt vmcnt(0)
	s_barrier
	s_add_u32 m0, s96, 0x0
	s_nop 0
	global_load_lds_dwordx4 v232, s[90:91]
	s_add_u32 m0, s96, 0x1000
	s_nop 0
	global_load_lds_dwordx4 v233, s[90:91]
	s_add_u32 m0, s96, 0x2000
	s_nop 0
	global_load_lds_dwordx4 v234, s[90:91]
	s_add_u32 m0, s96, 0x3000
	s_nop 0
	global_load_lds_dwordx4 v235, s[90:91]
	s_add_u32 m0, s96, 0x8000
	s_nop 0
	global_load_lds_dwordx4 v232, s[92:93]
	s_add_u32 m0, s96, 0x9000
	s_nop 0
	global_load_lds_dwordx4 v233, s[92:93]
	s_add_u32 m0, s96, 0xa000
	s_nop 0
	global_load_lds_dwordx4 v234, s[92:93]
	s_add_u32 m0, s96, 0xb000
	s_nop 0
	global_load_lds_dwordx4 v235, s[92:93]
	s_add_u32 m0, s96, 0xc000
	s_nop 0
	global_load_lds_dwordx4 v232, s[98:99]
	s_add_u32 m0, s96, 0xd000
	s_nop 0
	global_load_lds_dwordx4 v233, s[98:99]
	s_add_u32 m0, s96, 0xe000
	s_nop 0
	global_load_lds_dwordx4 v234, s[98:99]
	s_add_u32 m0, s96, 0xf000
	s_nop 0
	global_load_lds_dwordx4 v235, s[98:99]
	s_add_u32 s90, s90, 0x80
	s_addc_u32 s91, s91, 0
	s_add_u32 s92, s92, 0x80
	s_addc_u32 s93, s93, 0
	s_add_u32 s98, s98, 0x80
	s_addc_u32 s99, s99, 0
	v_mov_b32_e32 v0, 0
	v_mov_b32_e32 v1, v0
	v_mov_b32_e32 v2, v0
	v_mov_b32_e32 v3, v0
	v_mov_b32_e32 v4, v0
	v_mov_b32_e32 v5, v0
	v_mov_b32_e32 v6, v0
	v_mov_b32_e32 v7, v0
	v_mov_b32_e32 v8, v0
	v_mov_b32_e32 v9, v0
	v_mov_b32_e32 v10, v0
	v_mov_b32_e32 v11, v0
	v_mov_b32_e32 v12, v0
	v_mov_b32_e32 v13, v0
	v_mov_b32_e32 v14, v0
	v_mov_b32_e32 v15, v0
	v_mov_b32_e32 v16, v0
	v_mov_b32_e32 v17, v0
	v_mov_b32_e32 v18, v0
	v_mov_b32_e32 v19, v0
	v_mov_b32_e32 v20, v0
	v_mov_b32_e32 v21, v0
	v_mov_b32_e32 v22, v0
	v_mov_b32_e32 v23, v0
	v_mov_b32_e32 v24, v0
	v_mov_b32_e32 v25, v0
	v_mov_b32_e32 v26, v0
	v_mov_b32_e32 v27, v0
	v_mov_b32_e32 v28, v0
	v_mov_b32_e32 v29, v0
	v_mov_b32_e32 v30, v0
	v_mov_b32_e32 v31, v0
	v_mov_b32_e32 v32, v0
	v_mov_b32_e32 v33, v0
	v_mov_b32_e32 v34, v0
	v_mov_b32_e32 v35, v0
	v_mov_b32_e32 v36, v0
	v_mov_b32_e32 v37, v0
	v_mov_b32_e32 v38, v0
	v_mov_b32_e32 v39, v0
	v_mov_b32_e32 v40, v0
	v_mov_b32_e32 v41, v0
	v_mov_b32_e32 v42, v0
	v_mov_b32_e32 v43, v0
	v_mov_b32_e32 v44, v0
	v_mov_b32_e32 v45, v0
	v_mov_b32_e32 v46, v0
	v_mov_b32_e32 v47, v0
	v_mov_b32_e32 v48, v0
	v_mov_b32_e32 v49, v0
	v_mov_b32_e32 v50, v0
	v_mov_b32_e32 v51, v0
	v_mov_b32_e32 v52, v0
	v_mov_b32_e32 v53, v0
	v_mov_b32_e32 v54, v0
	v_mov_b32_e32 v55, v0
	v_mov_b32_e32 v56, v0
	v_mov_b32_e32 v57, v0
	v_mov_b32_e32 v58, v0
	v_mov_b32_e32 v59, v0
	v_mov_b32_e32 v60, v0
	v_mov_b32_e32 v61, v0
	v_mov_b32_e32 v62, v0
	v_mov_b32_e32 v63, v0
	v_mov_b32_e32 v64, v0
	v_mov_b32_e32 v65, v0
	v_mov_b32_e32 v66, v0
	v_mov_b32_e32 v67, v0
	v_mov_b32_e32 v68, v0
	v_mov_b32_e32 v69, v0
	v_mov_b32_e32 v70, v0
	v_mov_b32_e32 v71, v0
	v_mov_b32_e32 v72, v0
	v_mov_b32_e32 v73, v0
	v_mov_b32_e32 v74, v0
	v_mov_b32_e32 v75, v0
	v_mov_b32_e32 v76, v0
	v_mov_b32_e32 v77, v0
	v_mov_b32_e32 v78, v0
	v_mov_b32_e32 v79, v0
	v_mov_b32_e32 v80, v0
	v_mov_b32_e32 v81, v0
	v_mov_b32_e32 v82, v0
	v_mov_b32_e32 v83, v0
	v_mov_b32_e32 v84, v0
	v_mov_b32_e32 v85, v0
	v_mov_b32_e32 v86, v0
	v_mov_b32_e32 v87, v0
	v_mov_b32_e32 v88, v0
	v_mov_b32_e32 v89, v0
	v_mov_b32_e32 v90, v0
	v_mov_b32_e32 v91, v0
	v_mov_b32_e32 v92, v0
	v_mov_b32_e32 v93, v0
	v_mov_b32_e32 v94, v0
	v_mov_b32_e32 v95, v0
	v_mov_b32_e32 v96, v0
	v_mov_b32_e32 v97, v0
	v_mov_b32_e32 v98, v0
	v_mov_b32_e32 v99, v0
	v_mov_b32_e32 v100, v0
	v_mov_b32_e32 v101, v0
	v_mov_b32_e32 v102, v0
	v_mov_b32_e32 v103, v0
	v_mov_b32_e32 v104, v0
	v_mov_b32_e32 v105, v0
	v_mov_b32_e32 v106, v0
	v_mov_b32_e32 v107, v0
	v_mov_b32_e32 v108, v0
	v_mov_b32_e32 v109, v0
	v_mov_b32_e32 v110, v0
	v_mov_b32_e32 v111, v0
	v_mov_b32_e32 v112, v0
	v_mov_b32_e32 v113, v0
	v_mov_b32_e32 v114, v0
	v_mov_b32_e32 v115, v0
	v_mov_b32_e32 v116, v0
	v_mov_b32_e32 v117, v0
	v_mov_b32_e32 v118, v0
	v_mov_b32_e32 v119, v0
	v_mov_b32_e32 v120, v0
	v_mov_b32_e32 v121, v0
	v_mov_b32_e32 v122, v0
	v_mov_b32_e32 v123, v0
	v_mov_b32_e32 v124, v0
	v_mov_b32_e32 v125, v0
	v_mov_b32_e32 v126, v0
	v_mov_b32_e32 v127, v0
	s_mov_b32 s94, 0

.Lp6c_ep:
	s_cmp_eq_u32 s83, 1
	s_cselect_b32 s84, s34, s24
	s_cselect_b32 s85, s35, s25
	s_add_u32 s84, s84, 0x8000
	s_addc_u32 s85, s85, 0
	v_cvt_pk_bf16_f32 v136, v0, v1
	v_cvt_pk_bf16_f32 v137, v2, v3
	v_cvt_pk_bf16_f32 v138, v4, v5
	v_cvt_pk_bf16_f32 v139, v6, v7
	global_store_dwordx4 v243, v[136:139], s[84:85]
	s_add_u32 s84, s84, 0x1000
	s_addc_u32 s85, s85, 0
	v_cvt_pk_bf16_f32 v140, v8, v9
	v_cvt_pk_bf16_f32 v141, v10, v11
	v_cvt_pk_bf16_f32 v142, v12, v13
	v_cvt_pk_bf16_f32 v143, v14, v15
	global_store_dwordx4 v243, v[140:143], s[84:85]
	s_add_u32 s84, s84, 0x1000
	s_addc_u32 s85, s85, 0
	v_cvt_pk_bf16_f32 v136, v16, v17
	v_cvt_pk_bf16_f32 v137, v18, v19
	v_cvt_pk_bf16_f32 v138, v20, v21
	v_cvt_pk_bf16_f32 v139, v22, v23
	global_store_dwordx4 v243, v[136:139], s[84:85]
	s_add_u32 s84, s84, 0x1000
	s_addc_u32 s85, s85, 0
	v_cvt_pk_bf16_f32 v140, v24, v25
	v_cvt_pk_bf16_f32 v141, v26, v27
	v_cvt_pk_bf16_f32 v142, v28, v29
	v_cvt_pk_bf16_f32 v143, v30, v31
	global_store_dwordx4 v243, v[140:143], s[84:85]
	s_add_u32 s84, s84, 0x1000
	s_addc_u32 s85, s85, 0
	v_cvt_pk_bf16_f32 v136, v32, v33
	v_cvt_pk_bf16_f32 v137, v34, v35
	v_cvt_pk_bf16_f32 v138, v36, v37
	v_cvt_pk_bf16_f32 v139, v38, v39
	global_store_dwordx4 v243, v[136:139], s[84:85]
	s_add_u32 s84, s84, 0x1000
	s_addc_u32 s85, s85, 0
	v_cvt_pk_bf16_f32 v140, v40, v41
	v_cvt_pk_bf16_f32 v141, v42, v43
	v_cvt_pk_bf16_f32 v142, v44, v45
	v_cvt_pk_bf16_f32 v143, v46, v47
	global_store_dwordx4 v243, v[140:143], s[84:85]
	s_add_u32 s84, s84, 0x1000
	s_addc_u32 s85, s85, 0
	v_cvt_pk_bf16_f32 v136, v48, v49
	v_cvt_pk_bf16_f32 v137, v50, v51
	v_cvt_pk_bf16_f32 v138, v52, v53
	v_cvt_pk_bf16_f32 v139, v54, v55
	global_store_dwordx4 v243, v[136:139], s[84:85]
	s_add_u32 s84, s84, 0x1000
	s_addc_u32 s85, s85, 0
	v_cvt_pk_bf16_f32 v140, v56, v57
	v_cvt_pk_bf16_f32 v141, v58, v59
	v_cvt_pk_bf16_f32 v142, v60, v61
	v_cvt_pk_bf16_f32 v143, v62, v63
	global_store_dwordx4 v243, v[140:143], s[84:85]
	s_add_u32 s84, s84, 0x1000
	s_addc_u32 s85, s85, 0
	s_cmp_eq_u32 s83, 1
	s_cbranch_scc1 .Lp6c_epdone
	s_cmp_eq_u32 s95, 1
	s_cbranch_scc0 .Lp6c_epdone
	v_mov_b32_e32 v0, v64
	v_mov_b32_e32 v1, v65
	v_mov_b32_e32 v2, v66
	v_mov_b32_e32 v3, v67
	v_mov_b32_e32 v4, v68
	v_mov_b32_e32 v5, v69
	v_mov_b32_e32 v6, v70
	v_mov_b32_e32 v7, v71
	v_mov_b32_e32 v8, v72
	v_mov_b32_e32 v9, v73
	v_mov_b32_e32 v10, v74
	v_mov_b32_e32 v11, v75
	v_mov_b32_e32 v12, v76
	v_mov_b32_e32 v13, v77
	v_mov_b32_e32 v14, v78
	v_mov_b32_e32 v15, v79
	v_mov_b32_e32 v16, v80
	v_mov_b32_e32 v17, v81
	v_mov_b32_e32 v18, v82
	v_mov_b32_e32 v19, v83
	v_mov_b32_e32 v20, v84
	v_mov_b32_e32 v21, v85
	v_mov_b32_e32 v22, v86
	v_mov_b32_e32 v23, v87
	v_mov_b32_e32 v24, v88
	v_mov_b32_e32 v25, v89
	v_mov_b32_e32 v26, v90
	v_mov_b32_e32 v27, v91
	v_mov_b32_e32 v28, v92
	v_mov_b32_e32 v29, v93
	v_mov_b32_e32 v30, v94
	v_mov_b32_e32 v31, v95
	v_mov_b32_e32 v32, v96
	v_mov_b32_e32 v33, v97
	v_mov_b32_e32 v34, v98
	v_mov_b32_e32 v35, v99
	v_mov_b32_e32 v36, v100
	v_mov_b32_e32 v37, v101
	v_mov_b32_e32 v38, v102
	v_mov_b32_e32 v39, v103
	v_mov_b32_e32 v40, v104
	v_mov_b32_e32 v41, v105
	v_mov_b32_e32 v42, v106
	v_mov_b32_e32 v43, v107
	v_mov_b32_e32 v44, v108
	v_mov_b32_e32 v45, v109
	v_mov_b32_e32 v46, v110
	v_mov_b32_e32 v47, v111
	v_mov_b32_e32 v48, v112
	v_mov_b32_e32 v49, v113
	v_mov_b32_e32 v50, v114
	v_mov_b32_e32 v51, v115
	v_mov_b32_e32 v52, v116
	v_mov_b32_e32 v53, v117
	v_mov_b32_e32 v54, v118
	v_mov_b32_e32 v55, v119
	v_mov_b32_e32 v56, v120
	v_mov_b32_e32 v57, v121
	v_mov_b32_e32 v58, v122
	v_mov_b32_e32 v59, v123
	v_mov_b32_e32 v60, v124
	v_mov_b32_e32 v61, v125
	v_mov_b32_e32 v62, v126
	v_mov_b32_e32 v63, v127
	s_mov_b32 s83, 1
	s_branch .Lp6c_ep
.Lp6c_epdone:
.Lp6_site_d:
	v_lshrrev_b32_e32 v236, 3, v168
	v_lshrrev_b32_e32 v237, 4, v168
	v_xor_b32_e32 v237, v237, v168
	v_and_b32_e32 v237, 7, v237
	v_lshlrev_b32_e32 v237, 4, v237
	v_lshl_or_b32 v232, v236, 11, v237
	v_add_u32_e32 v233, 0x10000, v232
	v_add_u32_e32 v234, 0x20000, v232
	v_add_u32_e32 v235, 0x30000, v232
	s_load_dwordx2 s[90:91], s[0:1], 0xa0
	s_load_dwordx2 s[92:93], s[0:1], 0xa8
	v_lshrrev_b32_e32 v237, 6, v168
	s_nop 1
	v_readfirstlane_b32 s97, v237
	s_nop 3
	s_lshl_b32 s96, s97, 10
	s_add_u32 s96, s96, 16
	s_add_u32 s94, s81, s80
	s_cmp_lt_i32 s94, s82
	s_cselect_b32 s95, 1, 0
	s_cmp_lg_u64 s[20:21], 0
	s_cselect_b32 s95, 0, s95
	s_cmp_ge_u32 s94, 0x40
	s_cselect_b32 s97, 1, 0
	s_mul_i32 s100, s97, 0x40
	s_sub_u32 s100, s94, s100
	s_lshr_b32 s101, s100, 3
	s_and_b32 s100, s100, 7
	s_lshl_b32 s97, s97, 3
	s_add_u32 s100, s100, s97
	s_add_u32 s100, s100, s79
	s_cmp_lg_u32 s101, s74
	s_cselect_b32 s95, 0, s95
	s_cmp_eq_u32 s95, 1
	s_cselect_b32 s101, s100, s70
	s_mov_b32 s97, s101
	s_waitcnt lgkmcnt(0)
	s_lshl_b32 s94, s74, 18
	s_add_u32 s94, s94, 0xe40000
	s_add_u32 s98, s92, s94
	s_addc_u32 s99, s93, 0
	s_lshl_b32 s101, s101, 18
	s_add_u32 s92, s90, s101
	s_addc_u32 s93, s91, 0
	s_lshl_b32 s94, s70, 18
	s_add_u32 s90, s90, s94
	s_addc_u32 s91, s91, 0
	s_mov_b64 s[100:101], s[90:91]
	s_mov_b64 s[90:91], s[98:99]
	s_mov_b64 s[98:99], s[92:93]
	s_mov_b64 s[92:93], s[100:101]
	s_waitcnt vmcnt(0)
	s_barrier
	s_add_u32 m0, s96, 0x0
	s_nop 0
	global_load_lds_dwordx4 v232, s[90:91]
	s_add_u32 m0, s96, 0x1000
	s_nop 0
	global_load_lds_dwordx4 v233, s[90:91]
	s_add_u32 m0, s96, 0x2000
	s_nop 0
	global_load_lds_dwordx4 v234, s[90:91]
	s_add_u32 m0, s96, 0x3000
	s_nop 0
	global_load_lds_dwordx4 v235, s[90:91]
	s_add_u32 m0, s96, 0x8000
	s_nop 0
	global_load_lds_dwordx4 v232, s[92:93]
	s_add_u32 m0, s96, 0x9000
	s_nop 0
	global_load_lds_dwordx4 v233, s[92:93]
	s_add_u32 m0, s96, 0xa000
	s_nop 0
	global_load_lds_dwordx4 v234, s[92:93]
	s_add_u32 m0, s96, 0xb000
	s_nop 0
	global_load_lds_dwordx4 v235, s[92:93]
	s_add_u32 m0, s96, 0xc000
	s_nop 0
	global_load_lds_dwordx4 v232, s[98:99]
	s_add_u32 m0, s96, 0xd000
	s_nop 0
	global_load_lds_dwordx4 v233, s[98:99]
	s_add_u32 m0, s96, 0xe000
	s_nop 0
	global_load_lds_dwordx4 v234, s[98:99]
	s_add_u32 m0, s96, 0xf000
	s_nop 0
	global_load_lds_dwordx4 v235, s[98:99]
	s_add_u32 s90, s90, 0x80
	s_addc_u32 s91, s91, 0
	s_add_u32 s92, s92, 0x80
	s_addc_u32 s93, s93, 0
	s_add_u32 s98, s98, 0x80
	s_addc_u32 s99, s99, 0
	v_mov_b32_e32 v0, 0
	v_mov_b32_e32 v1, v0
	v_mov_b32_e32 v2, v0
	v_mov_b32_e32 v3, v0
	v_mov_b32_e32 v4, v0
	v_mov_b32_e32 v5, v0
	v_mov_b32_e32 v6, v0
	v_mov_b32_e32 v7, v0
	v_mov_b32_e32 v8, v0
	v_mov_b32_e32 v9, v0
	v_mov_b32_e32 v10, v0
	v_mov_b32_e32 v11, v0
	v_mov_b32_e32 v12, v0
	v_mov_b32_e32 v13, v0
	v_mov_b32_e32 v14, v0
	v_mov_b32_e32 v15, v0
	v_mov_b32_e32 v16, v0
	v_mov_b32_e32 v17, v0
	v_mov_b32_e32 v18, v0
	v_mov_b32_e32 v19, v0
	v_mov_b32_e32 v20, v0
	v_mov_b32_e32 v21, v0
	v_mov_b32_e32 v22, v0
	v_mov_b32_e32 v23, v0
	v_mov_b32_e32 v24, v0
	v_mov_b32_e32 v25, v0
	v_mov_b32_e32 v26, v0
	v_mov_b32_e32 v27, v0
	v_mov_b32_e32 v28, v0
	v_mov_b32_e32 v29, v0
	v_mov_b32_e32 v30, v0
	v_mov_b32_e32 v31, v0
	v_mov_b32_e32 v32, v0
	v_mov_b32_e32 v33, v0
	v_mov_b32_e32 v34, v0
	v_mov_b32_e32 v35, v0
	v_mov_b32_e32 v36, v0
	v_mov_b32_e32 v37, v0
	v_mov_b32_e32 v38, v0
	v_mov_b32_e32 v39, v0
	v_mov_b32_e32 v40, v0
	v_mov_b32_e32 v41, v0
	v_mov_b32_e32 v42, v0
	v_mov_b32_e32 v43, v0
	v_mov_b32_e32 v44, v0
	v_mov_b32_e32 v45, v0
	v_mov_b32_e32 v46, v0
	v_mov_b32_e32 v47, v0
	v_mov_b32_e32 v48, v0
	v_mov_b32_e32 v49, v0
	v_mov_b32_e32 v50, v0
	v_mov_b32_e32 v51, v0
	v_mov_b32_e32 v52, v0
	v_mov_b32_e32 v53, v0
	v_mov_b32_e32 v54, v0
	v_mov_b32_e32 v55, v0
	v_mov_b32_e32 v56, v0
	v_mov_b32_e32 v57, v0
	v_mov_b32_e32 v58, v0
	v_mov_b32_e32 v59, v0
	v_mov_b32_e32 v60, v0
	v_mov_b32_e32 v61, v0
	v_mov_b32_e32 v62, v0
	v_mov_b32_e32 v63, v0
	v_mov_b32_e32 v64, v0
	v_mov_b32_e32 v65, v0
	v_mov_b32_e32 v66, v0
	v_mov_b32_e32 v67, v0
	v_mov_b32_e32 v68, v0
	v_mov_b32_e32 v69, v0
	v_mov_b32_e32 v70, v0
	v_mov_b32_e32 v71, v0
	v_mov_b32_e32 v72, v0
	v_mov_b32_e32 v73, v0
	v_mov_b32_e32 v74, v0
	v_mov_b32_e32 v75, v0
	v_mov_b32_e32 v76, v0
	v_mov_b32_e32 v77, v0
	v_mov_b32_e32 v78, v0
	v_mov_b32_e32 v79, v0
	v_mov_b32_e32 v80, v0
	v_mov_b32_e32 v81, v0
	v_mov_b32_e32 v82, v0
	v_mov_b32_e32 v83, v0
	v_mov_b32_e32 v84, v0
	v_mov_b32_e32 v85, v0
	v_mov_b32_e32 v86, v0
	v_mov_b32_e32 v87, v0
	v_mov_b32_e32 v88, v0
	v_mov_b32_e32 v89, v0
	v_mov_b32_e32 v90, v0
	v_mov_b32_e32 v91, v0
	v_mov_b32_e32 v92, v0
	v_mov_b32_e32 v93, v0
	v_mov_b32_e32 v94, v0
	v_mov_b32_e32 v95, v0
	v_mov_b32_e32 v96, v0
	v_mov_b32_e32 v97, v0
	v_mov_b32_e32 v98, v0
	v_mov_b32_e32 v99, v0
	v_mov_b32_e32 v100, v0
	v_mov_b32_e32 v101, v0
	v_mov_b32_e32 v102, v0
	v_mov_b32_e32 v103, v0
	v_mov_b32_e32 v104, v0
	v_mov_b32_e32 v105, v0
	v_mov_b32_e32 v106, v0
	v_mov_b32_e32 v107, v0
	v_mov_b32_e32 v108, v0
	v_mov_b32_e32 v109, v0
	v_mov_b32_e32 v110, v0
	v_mov_b32_e32 v111, v0
	v_mov_b32_e32 v112, v0
	v_mov_b32_e32 v113, v0
	v_mov_b32_e32 v114, v0
	v_mov_b32_e32 v115, v0
	v_mov_b32_e32 v116, v0
	v_mov_b32_e32 v117, v0
	v_mov_b32_e32 v118, v0
	v_mov_b32_e32 v119, v0
	v_mov_b32_e32 v120, v0
	v_mov_b32_e32 v121, v0
	v_mov_b32_e32 v122, v0
	v_mov_b32_e32 v123, v0
	v_mov_b32_e32 v124, v0
	v_mov_b32_e32 v125, v0
	v_mov_b32_e32 v126, v0
	v_mov_b32_e32 v127, v0
	s_mov_b32 s94, 0

.Lp6d_ep:
	s_add_u32 s28, s22, 0x1000
	s_addc_u32 s29, s23, 0
	global_load_dwordx4 v[128:131], v244, s[28:29]
	global_load_dwordx4 v[132:135], v244, s[28:29] offset:64
	global_load_dwordx4 v[136:139], v244, s[28:29] offset:128
	global_load_dwordx4 v[140:143], v244, s[28:29] offset:192
	s_cmp_eq_u32 s83, 1
	s_cselect_b32 s75, s97, s70
	v_lshrrev_b32_e32 v249, 1, v168
	v_and_b32_e32 v249, 0x1c0, v249
	v_and_b32_e32 v250, 15, v168
	v_or_b32_e32 v249, v249, v250
	v_lshl_add_u32 v249, s75, 7, v249
	v_lshlrev_b32_e32 v249, 11, v249
	v_bfe_u32 v250, v168, 4, 2
	v_lshlrev_b32_e32 v246, 3, v250
	v_and_b32_e32 v250, 1, v250
	v_mul_u32_u24_e32 v250, 24, v250
	v_add3_u32 v249, v249, v250, v246
	v_bfe_u32 v250, v168, 6, 1
	s_lshl_b32 s71, s74, 8
	v_lshl_add_u32 v245, v250, 7, v249
	v_add_u32_e32 v245, s71, v245
	v_add_u32_e32 v246, 0x8000, v245
	v_add_u32_e32 v247, 0x10000, v245
	v_add_u32_e32 v248, 0x18000, v245
	s_cmp_eq_u32 s83, 1
	s_cselect_b32 s86, s34, s24
	s_cselect_b32 s87, s35, s25
	s_cmp_eq_u32 s83, 1
	s_cselect_b32 s88, s34, s24
	s_cselect_b32 s89, s35, s25
	s_add_u32 s88, s88, 0x8000
	s_addc_u32 s89, s89, 0
	global_load_dwordx4 v[148:151], v243, s[86:87]
	s_add_u32 s86, s86, 0x1000
	s_addc_u32 s87, s87, 0
	global_load_dwordx4 v[164:167], v243, s[88:89]
	s_add_u32 s88, s88, 0x1000
	s_addc_u32 s89, s89, 0
	global_load_dwordx4 v[152:155], v243, s[86:87]
	s_add_u32 s86, s86, 0x1000
	s_addc_u32 s87, s87, 0
	global_load_dwordx4 v[172:175], v243, s[88:89]
	s_add_u32 s88, s88, 0x1000
	s_addc_u32 s89, s89, 0
	global_load_dwordx4 v[156:159], v243, s[86:87]
	s_add_u32 s86, s86, 0x1000
	s_addc_u32 s87, s87, 0
	global_load_dwordx4 v[176:179], v243, s[88:89]
	s_add_u32 s88, s88, 0x1000
	s_addc_u32 s89, s89, 0
	global_load_dwordx4 v[160:163], v243, s[86:87]
	s_add_u32 s86, s86, 0x1000
	s_addc_u32 s87, s87, 0
	global_load_dwordx4 v[180:183], v243, s[88:89]
	s_add_u32 s88, s88, 0x1000
	s_addc_u32 s89, s89, 0
	s_waitcnt vmcnt(6)
	v_add_f32_e32 v184, v0, v128
	v_add_f32_e32 v185, v1, v129
	v_add_f32_e32 v186, v2, v130
	v_add_f32_e32 v187, v3, v131
	v_add_f32_e32 v188, v4, v132
	v_add_f32_e32 v189, v5, v133
	v_add_f32_e32 v190, v6, v134
	v_add_f32_e32 v191, v7, v135
	v_mul_f32_e32 v184, 0xbfb8aa3b, v184
	v_mul_f32_e32 v185, 0xbfb8aa3b, v185
	v_mul_f32_e32 v186, 0xbfb8aa3b, v186
	v_mul_f32_e32 v187, 0xbfb8aa3b, v187
	v_mul_f32_e32 v188, 0xbfb8aa3b, v188
	v_mul_f32_e32 v189, 0xbfb8aa3b, v189
	v_mul_f32_e32 v190, 0xbfb8aa3b, v190
	v_mul_f32_e32 v191, 0xbfb8aa3b, v191
	v_exp_f32_e32 v192, v184
	v_exp_f32_e32 v193, v185
	v_exp_f32_e32 v194, v186
	v_exp_f32_e32 v195, v187
	v_exp_f32_e32 v196, v188
	v_exp_f32_e32 v197, v189
	v_exp_f32_e32 v198, v190
	v_exp_f32_e32 v199, v191
	v_add_f32_e32 v192, 1.0, v192
	v_add_f32_e32 v193, 1.0, v193
	v_add_f32_e32 v194, 1.0, v194
	v_add_f32_e32 v195, 1.0, v195
	v_add_f32_e32 v196, 1.0, v196
	v_add_f32_e32 v197, 1.0, v197
	v_add_f32_e32 v198, 1.0, v198
	v_add_f32_e32 v199, 1.0, v199
	v_div_scale_f32 v200, s[76:77], v192, v192, 1.0
	v_div_scale_f32 v201, s[76:77], v193, v193, 1.0
	v_div_scale_f32 v202, s[76:77], v194, v194, 1.0
	v_div_scale_f32 v203, s[76:77], v195, v195, 1.0
	v_div_scale_f32 v204, s[76:77], v196, v196, 1.0
	v_div_scale_f32 v205, s[76:77], v197, v197, 1.0
	v_div_scale_f32 v206, s[76:77], v198, v198, 1.0
	v_div_scale_f32 v207, s[76:77], v199, v199, 1.0
	v_rcp_f32_e32 v208, v200
	v_rcp_f32_e32 v209, v201
	v_rcp_f32_e32 v210, v202
	v_rcp_f32_e32 v211, v203
	v_rcp_f32_e32 v212, v204
	v_rcp_f32_e32 v213, v205
	v_rcp_f32_e32 v214, v206
	v_rcp_f32_e32 v215, v207
	v_fma_f32 v184, -v200, v208, 1.0
	v_fma_f32 v185, -v201, v209, 1.0
	v_fma_f32 v186, -v202, v210, 1.0
	v_fma_f32 v187, -v203, v211, 1.0
	v_fma_f32 v188, -v204, v212, 1.0
	v_fma_f32 v189, -v205, v213, 1.0
	v_fma_f32 v190, -v206, v214, 1.0
	v_fma_f32 v191, -v207, v215, 1.0
	v_fmac_f32_e32 v208, v184, v208
	v_fmac_f32_e32 v209, v185, v209
	v_fmac_f32_e32 v210, v186, v210
	v_fmac_f32_e32 v211, v187, v211
	v_fmac_f32_e32 v212, v188, v212
	v_fmac_f32_e32 v213, v189, v213
	v_fmac_f32_e32 v214, v190, v214
	v_fmac_f32_e32 v215, v191, v215
	v_div_scale_f32 v216, vcc, 1.0, v192, 1.0
	v_mul_f32_e32 v224, v216, v208
	v_fma_f32 v184, -v200, v224, v216
	v_fmac_f32_e32 v224, v184, v208
	v_fma_f32 v216, -v200, v224, v216
	v_div_fmas_f32 v216, v216, v208, v224
	v_div_fixup_f32 v184, v216, v192, 1.0
	v_div_scale_f32 v217, vcc, 1.0, v193, 1.0
	v_mul_f32_e32 v225, v217, v209
	v_fma_f32 v185, -v201, v225, v217
	v_fmac_f32_e32 v225, v185, v209
	v_fma_f32 v217, -v201, v225, v217
	v_div_fmas_f32 v217, v217, v209, v225
	v_div_fixup_f32 v185, v217, v193, 1.0
	v_div_scale_f32 v218, vcc, 1.0, v194, 1.0
	v_mul_f32_e32 v226, v218, v210
	v_fma_f32 v186, -v202, v226, v218
	v_fmac_f32_e32 v226, v186, v210
	v_fma_f32 v218, -v202, v226, v218
	v_div_fmas_f32 v218, v218, v210, v226
	v_div_fixup_f32 v186, v218, v194, 1.0
	v_div_scale_f32 v219, vcc, 1.0, v195, 1.0
	v_mul_f32_e32 v227, v219, v211
	v_fma_f32 v187, -v203, v227, v219
	v_fmac_f32_e32 v227, v187, v211
	v_fma_f32 v219, -v203, v227, v219
	v_div_fmas_f32 v219, v219, v211, v227
	v_div_fixup_f32 v187, v219, v195, 1.0
	v_div_scale_f32 v220, vcc, 1.0, v196, 1.0
	v_mul_f32_e32 v228, v220, v212
	v_fma_f32 v188, -v204, v228, v220
	v_fmac_f32_e32 v228, v188, v212
	v_fma_f32 v220, -v204, v228, v220
	v_div_fmas_f32 v220, v220, v212, v228
	v_div_fixup_f32 v188, v220, v196, 1.0
	v_div_scale_f32 v221, vcc, 1.0, v197, 1.0
	v_mul_f32_e32 v229, v221, v213
	v_fma_f32 v189, -v205, v229, v221
	v_fmac_f32_e32 v229, v189, v213
	v_fma_f32 v221, -v205, v229, v221
	v_div_fmas_f32 v221, v221, v213, v229
	v_div_fixup_f32 v189, v221, v197, 1.0
	v_div_scale_f32 v222, vcc, 1.0, v198, 1.0
	v_mul_f32_e32 v230, v222, v214
	v_fma_f32 v190, -v206, v230, v222
	v_fmac_f32_e32 v230, v190, v214
	v_fma_f32 v222, -v206, v230, v222
	v_div_fmas_f32 v222, v222, v214, v230
	v_div_fixup_f32 v190, v222, v198, 1.0
	v_div_scale_f32 v223, vcc, 1.0, v199, 1.0
	v_mul_f32_e32 v231, v223, v215
	v_fma_f32 v191, -v207, v231, v223
	v_fmac_f32_e32 v231, v191, v215
	v_fma_f32 v223, -v207, v231, v223
	v_div_fmas_f32 v223, v223, v215, v231
	v_div_fixup_f32 v191, v223, v199, 1.0
	v_lshlrev_b32_e32 v192, 16, v148
	v_and_b32_e32 v193, 0xffff0000, v148
	v_lshlrev_b32_e32 v200, 16, v164
	v_and_b32_e32 v201, 0xffff0000, v164
	v_lshlrev_b32_e32 v194, 16, v149
	v_and_b32_e32 v195, 0xffff0000, v149
	v_lshlrev_b32_e32 v202, 16, v165
	v_and_b32_e32 v203, 0xffff0000, v165
	v_lshlrev_b32_e32 v196, 16, v150
	v_and_b32_e32 v197, 0xffff0000, v150
	v_lshlrev_b32_e32 v204, 16, v166
	v_and_b32_e32 v205, 0xffff0000, v166
	v_lshlrev_b32_e32 v198, 16, v151
	v_and_b32_e32 v199, 0xffff0000, v151
	v_lshlrev_b32_e32 v206, 16, v167
	v_and_b32_e32 v207, 0xffff0000, v167
	v_fma_f32 v184, v184, v200, v192
	v_fma_f32 v185, v185, v201, v193
	v_fma_f32 v186, v186, v202, v194
	v_fma_f32 v187, v187, v203, v195
	v_fma_f32 v188, v188, v204, v196
	v_fma_f32 v189, v189, v205, v197
	v_fma_f32 v190, v190, v206, v198
	v_fma_f32 v191, v191, v207, v199
	v_cvt_pk_bf16_f32 v216, v184, v185
	v_cvt_pk_bf16_f32 v217, v186, v187
	v_cvt_pk_bf16_f32 v218, v188, v189
	v_cvt_pk_bf16_f32 v219, v190, v191
	s_nop 1
	v_permlane16_swap_b32_e32 v216, v218
	v_permlane16_swap_b32_e32 v217, v219
	global_store_dwordx4 v245, v[216:219], s[26:27]
	s_waitcnt vmcnt(5)
	v_add_f32_e32 v184, v8, v136
	v_add_f32_e32 v185, v9, v137
	v_add_f32_e32 v186, v10, v138
	v_add_f32_e32 v187, v11, v139
	v_add_f32_e32 v188, v12, v140
	v_add_f32_e32 v189, v13, v141
	v_add_f32_e32 v190, v14, v142
	v_add_f32_e32 v191, v15, v143
	v_mul_f32_e32 v184, 0xbfb8aa3b, v184
	v_mul_f32_e32 v185, 0xbfb8aa3b, v185
	v_mul_f32_e32 v186, 0xbfb8aa3b, v186
	v_mul_f32_e32 v187, 0xbfb8aa3b, v187
	v_mul_f32_e32 v188, 0xbfb8aa3b, v188
	v_mul_f32_e32 v189, 0xbfb8aa3b, v189
	v_mul_f32_e32 v190, 0xbfb8aa3b, v190
	v_mul_f32_e32 v191, 0xbfb8aa3b, v191
	v_exp_f32_e32 v192, v184
	v_exp_f32_e32 v193, v185
	v_exp_f32_e32 v194, v186
	v_exp_f32_e32 v195, v187
	v_exp_f32_e32 v196, v188
	v_exp_f32_e32 v197, v189
	v_exp_f32_e32 v198, v190
	v_exp_f32_e32 v199, v191
	v_add_f32_e32 v192, 1.0, v192
	v_add_f32_e32 v193, 1.0, v193
	v_add_f32_e32 v194, 1.0, v194
	v_add_f32_e32 v195, 1.0, v195
	v_add_f32_e32 v196, 1.0, v196
	v_add_f32_e32 v197, 1.0, v197
	v_add_f32_e32 v198, 1.0, v198
	v_add_f32_e32 v199, 1.0, v199
	v_div_scale_f32 v200, s[76:77], v192, v192, 1.0
	v_div_scale_f32 v201, s[76:77], v193, v193, 1.0
	v_div_scale_f32 v202, s[76:77], v194, v194, 1.0
	v_div_scale_f32 v203, s[76:77], v195, v195, 1.0
	v_div_scale_f32 v204, s[76:77], v196, v196, 1.0
	v_div_scale_f32 v205, s[76:77], v197, v197, 1.0
	v_div_scale_f32 v206, s[76:77], v198, v198, 1.0
	v_div_scale_f32 v207, s[76:77], v199, v199, 1.0
	v_rcp_f32_e32 v208, v200
	v_rcp_f32_e32 v209, v201
	v_rcp_f32_e32 v210, v202
	v_rcp_f32_e32 v211, v203
	v_rcp_f32_e32 v212, v204
	v_rcp_f32_e32 v213, v205
	v_rcp_f32_e32 v214, v206
	v_rcp_f32_e32 v215, v207
	v_fma_f32 v184, -v200, v208, 1.0
	v_fma_f32 v185, -v201, v209, 1.0
	v_fma_f32 v186, -v202, v210, 1.0
	v_fma_f32 v187, -v203, v211, 1.0
	v_fma_f32 v188, -v204, v212, 1.0
	v_fma_f32 v189, -v205, v213, 1.0
	v_fma_f32 v190, -v206, v214, 1.0
	v_fma_f32 v191, -v207, v215, 1.0
	v_fmac_f32_e32 v208, v184, v208
	v_fmac_f32_e32 v209, v185, v209
	v_fmac_f32_e32 v210, v186, v210
	v_fmac_f32_e32 v211, v187, v211
	v_fmac_f32_e32 v212, v188, v212
	v_fmac_f32_e32 v213, v189, v213
	v_fmac_f32_e32 v214, v190, v214
	v_fmac_f32_e32 v215, v191, v215
	v_div_scale_f32 v216, vcc, 1.0, v192, 1.0
	v_mul_f32_e32 v224, v216, v208
	v_fma_f32 v184, -v200, v224, v216
	v_fmac_f32_e32 v224, v184, v208
	v_fma_f32 v216, -v200, v224, v216
	v_div_fmas_f32 v216, v216, v208, v224
	v_div_fixup_f32 v184, v216, v192, 1.0
	v_div_scale_f32 v217, vcc, 1.0, v193, 1.0
	v_mul_f32_e32 v225, v217, v209
	v_fma_f32 v185, -v201, v225, v217
	v_fmac_f32_e32 v225, v185, v209
	v_fma_f32 v217, -v201, v225, v217
	v_div_fmas_f32 v217, v217, v209, v225
	v_div_fixup_f32 v185, v217, v193, 1.0
	v_div_scale_f32 v218, vcc, 1.0, v194, 1.0
	v_mul_f32_e32 v226, v218, v210
	v_fma_f32 v186, -v202, v226, v218
	v_fmac_f32_e32 v226, v186, v210
	v_fma_f32 v218, -v202, v226, v218
	v_div_fmas_f32 v218, v218, v210, v226
	v_div_fixup_f32 v186, v218, v194, 1.0
	v_div_scale_f32 v219, vcc, 1.0, v195, 1.0
	v_mul_f32_e32 v227, v219, v211
	v_fma_f32 v187, -v203, v227, v219
	v_fmac_f32_e32 v227, v187, v211
	v_fma_f32 v219, -v203, v227, v219
	v_div_fmas_f32 v219, v219, v211, v227
	v_div_fixup_f32 v187, v219, v195, 1.0
	v_div_scale_f32 v220, vcc, 1.0, v196, 1.0
	v_mul_f32_e32 v228, v220, v212
	v_fma_f32 v188, -v204, v228, v220
	v_fmac_f32_e32 v228, v188, v212
	v_fma_f32 v220, -v204, v228, v220
	v_div_fmas_f32 v220, v220, v212, v228
	v_div_fixup_f32 v188, v220, v196, 1.0
	v_div_scale_f32 v221, vcc, 1.0, v197, 1.0
	v_mul_f32_e32 v229, v221, v213
	v_fma_f32 v189, -v205, v229, v221
	v_fmac_f32_e32 v229, v189, v213
	v_fma_f32 v221, -v205, v229, v221
	v_div_fmas_f32 v221, v221, v213, v229
	v_div_fixup_f32 v189, v221, v197, 1.0
	v_div_scale_f32 v222, vcc, 1.0, v198, 1.0
	v_mul_f32_e32 v230, v222, v214
	v_fma_f32 v190, -v206, v230, v222
	v_fmac_f32_e32 v230, v190, v214
	v_fma_f32 v222, -v206, v230, v222
	v_div_fmas_f32 v222, v222, v214, v230
	v_div_fixup_f32 v190, v222, v198, 1.0
	v_div_scale_f32 v223, vcc, 1.0, v199, 1.0
	v_mul_f32_e32 v231, v223, v215
	v_fma_f32 v191, -v207, v231, v223
	v_fmac_f32_e32 v231, v191, v215
	v_fma_f32 v223, -v207, v231, v223
	v_div_fmas_f32 v223, v223, v215, v231
	v_div_fixup_f32 v191, v223, v199, 1.0
	v_lshlrev_b32_e32 v192, 16, v152
	v_and_b32_e32 v193, 0xffff0000, v152
	v_lshlrev_b32_e32 v200, 16, v172
	v_and_b32_e32 v201, 0xffff0000, v172
	v_lshlrev_b32_e32 v194, 16, v153
	v_and_b32_e32 v195, 0xffff0000, v153
	v_lshlrev_b32_e32 v202, 16, v173
	v_and_b32_e32 v203, 0xffff0000, v173
	v_lshlrev_b32_e32 v196, 16, v154
	v_and_b32_e32 v197, 0xffff0000, v154
	v_lshlrev_b32_e32 v204, 16, v174
	v_and_b32_e32 v205, 0xffff0000, v174
	v_lshlrev_b32_e32 v198, 16, v155
	v_and_b32_e32 v199, 0xffff0000, v155
	v_lshlrev_b32_e32 v206, 16, v175
	v_and_b32_e32 v207, 0xffff0000, v175
	v_fma_f32 v184, v184, v200, v192
	v_fma_f32 v185, v185, v201, v193
	v_fma_f32 v186, v186, v202, v194
	v_fma_f32 v187, v187, v203, v195
	v_fma_f32 v188, v188, v204, v196
	v_fma_f32 v189, v189, v205, v197
	v_fma_f32 v190, v190, v206, v198
	v_fma_f32 v191, v191, v207, v199
	v_cvt_pk_bf16_f32 v220, v184, v185
	v_cvt_pk_bf16_f32 v221, v186, v187
	v_cvt_pk_bf16_f32 v222, v188, v189
	v_cvt_pk_bf16_f32 v223, v190, v191
	s_nop 1
	v_permlane16_swap_b32_e32 v220, v222
	v_permlane16_swap_b32_e32 v221, v223
	global_store_dwordx4 v245, v[220:223], s[26:27] offset:64
	s_waitcnt vmcnt(4)
	v_add_f32_e32 v184, v16, v128
	v_add_f32_e32 v185, v17, v129
	v_add_f32_e32 v186, v18, v130
	v_add_f32_e32 v187, v19, v131
	v_add_f32_e32 v188, v20, v132
	v_add_f32_e32 v189, v21, v133
	v_add_f32_e32 v190, v22, v134
	v_add_f32_e32 v191, v23, v135
	v_mul_f32_e32 v184, 0xbfb8aa3b, v184
	v_mul_f32_e32 v185, 0xbfb8aa3b, v185
	v_mul_f32_e32 v186, 0xbfb8aa3b, v186
	v_mul_f32_e32 v187, 0xbfb8aa3b, v187
	v_mul_f32_e32 v188, 0xbfb8aa3b, v188
	v_mul_f32_e32 v189, 0xbfb8aa3b, v189
	v_mul_f32_e32 v190, 0xbfb8aa3b, v190
	v_mul_f32_e32 v191, 0xbfb8aa3b, v191
	v_exp_f32_e32 v192, v184
	v_exp_f32_e32 v193, v185
	v_exp_f32_e32 v194, v186
	v_exp_f32_e32 v195, v187
	v_exp_f32_e32 v196, v188
	v_exp_f32_e32 v197, v189
	v_exp_f32_e32 v198, v190
	v_exp_f32_e32 v199, v191
	v_add_f32_e32 v192, 1.0, v192
	v_add_f32_e32 v193, 1.0, v193
	v_add_f32_e32 v194, 1.0, v194
	v_add_f32_e32 v195, 1.0, v195
	v_add_f32_e32 v196, 1.0, v196
	v_add_f32_e32 v197, 1.0, v197
	v_add_f32_e32 v198, 1.0, v198
	v_add_f32_e32 v199, 1.0, v199
	v_div_scale_f32 v200, s[76:77], v192, v192, 1.0
	v_div_scale_f32 v201, s[76:77], v193, v193, 1.0
	v_div_scale_f32 v202, s[76:77], v194, v194, 1.0
	v_div_scale_f32 v203, s[76:77], v195, v195, 1.0
	v_div_scale_f32 v204, s[76:77], v196, v196, 1.0
	v_div_scale_f32 v205, s[76:77], v197, v197, 1.0
	v_div_scale_f32 v206, s[76:77], v198, v198, 1.0
	v_div_scale_f32 v207, s[76:77], v199, v199, 1.0
	v_rcp_f32_e32 v208, v200
	v_rcp_f32_e32 v209, v201
	v_rcp_f32_e32 v210, v202
	v_rcp_f32_e32 v211, v203
	v_rcp_f32_e32 v212, v204
	v_rcp_f32_e32 v213, v205
	v_rcp_f32_e32 v214, v206
	v_rcp_f32_e32 v215, v207
	v_fma_f32 v184, -v200, v208, 1.0
	v_fma_f32 v185, -v201, v209, 1.0
	v_fma_f32 v186, -v202, v210, 1.0
	v_fma_f32 v187, -v203, v211, 1.0
	v_fma_f32 v188, -v204, v212, 1.0
	v_fma_f32 v189, -v205, v213, 1.0
	v_fma_f32 v190, -v206, v214, 1.0
	v_fma_f32 v191, -v207, v215, 1.0
	v_fmac_f32_e32 v208, v184, v208
	v_fmac_f32_e32 v209, v185, v209
	v_fmac_f32_e32 v210, v186, v210
	v_fmac_f32_e32 v211, v187, v211
	v_fmac_f32_e32 v212, v188, v212
	v_fmac_f32_e32 v213, v189, v213
	v_fmac_f32_e32 v214, v190, v214
	v_fmac_f32_e32 v215, v191, v215
	v_div_scale_f32 v216, vcc, 1.0, v192, 1.0
	v_mul_f32_e32 v224, v216, v208
	v_fma_f32 v184, -v200, v224, v216
	v_fmac_f32_e32 v224, v184, v208
	v_fma_f32 v216, -v200, v224, v216
	v_div_fmas_f32 v216, v216, v208, v224
	v_div_fixup_f32 v184, v216, v192, 1.0
	v_div_scale_f32 v217, vcc, 1.0, v193, 1.0
	v_mul_f32_e32 v225, v217, v209
	v_fma_f32 v185, -v201, v225, v217
	v_fmac_f32_e32 v225, v185, v209
	v_fma_f32 v217, -v201, v225, v217
	v_div_fmas_f32 v217, v217, v209, v225
	v_div_fixup_f32 v185, v217, v193, 1.0
	v_div_scale_f32 v218, vcc, 1.0, v194, 1.0
	v_mul_f32_e32 v226, v218, v210
	v_fma_f32 v186, -v202, v226, v218
	v_fmac_f32_e32 v226, v186, v210
	v_fma_f32 v218, -v202, v226, v218
	v_div_fmas_f32 v218, v218, v210, v226
	v_div_fixup_f32 v186, v218, v194, 1.0
	v_div_scale_f32 v219, vcc, 1.0, v195, 1.0
	v_mul_f32_e32 v227, v219, v211
	v_fma_f32 v187, -v203, v227, v219
	v_fmac_f32_e32 v227, v187, v211
	v_fma_f32 v219, -v203, v227, v219
	v_div_fmas_f32 v219, v219, v211, v227
	v_div_fixup_f32 v187, v219, v195, 1.0
	v_div_scale_f32 v220, vcc, 1.0, v196, 1.0
	v_mul_f32_e32 v228, v220, v212
	v_fma_f32 v188, -v204, v228, v220
	v_fmac_f32_e32 v228, v188, v212
	v_fma_f32 v220, -v204, v228, v220
	v_div_fmas_f32 v220, v220, v212, v228
	v_div_fixup_f32 v188, v220, v196, 1.0
	v_div_scale_f32 v221, vcc, 1.0, v197, 1.0
	v_mul_f32_e32 v229, v221, v213
	v_fma_f32 v189, -v205, v229, v221
	v_fmac_f32_e32 v229, v189, v213
	v_fma_f32 v221, -v205, v229, v221
	v_div_fmas_f32 v221, v221, v213, v229
	v_div_fixup_f32 v189, v221, v197, 1.0
	v_div_scale_f32 v222, vcc, 1.0, v198, 1.0
	v_mul_f32_e32 v230, v222, v214
	v_fma_f32 v190, -v206, v230, v222
	v_fmac_f32_e32 v230, v190, v214
	v_fma_f32 v222, -v206, v230, v222
	v_div_fmas_f32 v222, v222, v214, v230
	v_div_fixup_f32 v190, v222, v198, 1.0
	v_div_scale_f32 v223, vcc, 1.0, v199, 1.0
	v_mul_f32_e32 v231, v223, v215
	v_fma_f32 v191, -v207, v231, v223
	v_fmac_f32_e32 v231, v191, v215
	v_fma_f32 v223, -v207, v231, v223
	v_div_fmas_f32 v223, v223, v215, v231
	v_div_fixup_f32 v191, v223, v199, 1.0
	v_lshlrev_b32_e32 v192, 16, v156
	v_and_b32_e32 v193, 0xffff0000, v156
	v_lshlrev_b32_e32 v200, 16, v176
	v_and_b32_e32 v201, 0xffff0000, v176
	v_lshlrev_b32_e32 v194, 16, v157
	v_and_b32_e32 v195, 0xffff0000, v157
	v_lshlrev_b32_e32 v202, 16, v177
	v_and_b32_e32 v203, 0xffff0000, v177
	v_lshlrev_b32_e32 v196, 16, v158
	v_and_b32_e32 v197, 0xffff0000, v158
	v_lshlrev_b32_e32 v204, 16, v178
	v_and_b32_e32 v205, 0xffff0000, v178
	v_lshlrev_b32_e32 v198, 16, v159
	v_and_b32_e32 v199, 0xffff0000, v159
	v_lshlrev_b32_e32 v206, 16, v179
	v_and_b32_e32 v207, 0xffff0000, v179
	v_fma_f32 v184, v184, v200, v192
	v_fma_f32 v185, v185, v201, v193
	v_fma_f32 v186, v186, v202, v194
	v_fma_f32 v187, v187, v203, v195
	v_fma_f32 v188, v188, v204, v196
	v_fma_f32 v189, v189, v205, v197
	v_fma_f32 v190, v190, v206, v198
	v_fma_f32 v191, v191, v207, v199
	v_cvt_pk_bf16_f32 v216, v184, v185
	v_cvt_pk_bf16_f32 v217, v186, v187
	v_cvt_pk_bf16_f32 v218, v188, v189
	v_cvt_pk_bf16_f32 v219, v190, v191
	s_nop 1
	v_permlane16_swap_b32_e32 v216, v218
	v_permlane16_swap_b32_e32 v217, v219
	global_store_dwordx4 v246, v[216:219], s[26:27]
	s_waitcnt vmcnt(3)
	v_add_f32_e32 v184, v24, v136
	v_add_f32_e32 v185, v25, v137
	v_add_f32_e32 v186, v26, v138
	v_add_f32_e32 v187, v27, v139
	v_add_f32_e32 v188, v28, v140
	v_add_f32_e32 v189, v29, v141
	v_add_f32_e32 v190, v30, v142
	v_add_f32_e32 v191, v31, v143
	v_mul_f32_e32 v184, 0xbfb8aa3b, v184
	v_mul_f32_e32 v185, 0xbfb8aa3b, v185
	v_mul_f32_e32 v186, 0xbfb8aa3b, v186
	v_mul_f32_e32 v187, 0xbfb8aa3b, v187
	v_mul_f32_e32 v188, 0xbfb8aa3b, v188
	v_mul_f32_e32 v189, 0xbfb8aa3b, v189
	v_mul_f32_e32 v190, 0xbfb8aa3b, v190
	v_mul_f32_e32 v191, 0xbfb8aa3b, v191
	v_exp_f32_e32 v192, v184
	v_exp_f32_e32 v193, v185
	v_exp_f32_e32 v194, v186
	v_exp_f32_e32 v195, v187
	v_exp_f32_e32 v196, v188
	v_exp_f32_e32 v197, v189
	v_exp_f32_e32 v198, v190
	v_exp_f32_e32 v199, v191
	v_add_f32_e32 v192, 1.0, v192
	v_add_f32_e32 v193, 1.0, v193
	v_add_f32_e32 v194, 1.0, v194
	v_add_f32_e32 v195, 1.0, v195
	v_add_f32_e32 v196, 1.0, v196
	v_add_f32_e32 v197, 1.0, v197
	v_add_f32_e32 v198, 1.0, v198
	v_add_f32_e32 v199, 1.0, v199
	v_div_scale_f32 v200, s[76:77], v192, v192, 1.0
	v_div_scale_f32 v201, s[76:77], v193, v193, 1.0
	v_div_scale_f32 v202, s[76:77], v194, v194, 1.0
	v_div_scale_f32 v203, s[76:77], v195, v195, 1.0
	v_div_scale_f32 v204, s[76:77], v196, v196, 1.0
	v_div_scale_f32 v205, s[76:77], v197, v197, 1.0
	v_div_scale_f32 v206, s[76:77], v198, v198, 1.0
	v_div_scale_f32 v207, s[76:77], v199, v199, 1.0
	v_rcp_f32_e32 v208, v200
	v_rcp_f32_e32 v209, v201
	v_rcp_f32_e32 v210, v202
	v_rcp_f32_e32 v211, v203
	v_rcp_f32_e32 v212, v204
	v_rcp_f32_e32 v213, v205
	v_rcp_f32_e32 v214, v206
	v_rcp_f32_e32 v215, v207
	v_fma_f32 v184, -v200, v208, 1.0
	v_fma_f32 v185, -v201, v209, 1.0
	v_fma_f32 v186, -v202, v210, 1.0
	v_fma_f32 v187, -v203, v211, 1.0
	v_fma_f32 v188, -v204, v212, 1.0
	v_fma_f32 v189, -v205, v213, 1.0
	v_fma_f32 v190, -v206, v214, 1.0
	v_fma_f32 v191, -v207, v215, 1.0
	v_fmac_f32_e32 v208, v184, v208
	v_fmac_f32_e32 v209, v185, v209
	v_fmac_f32_e32 v210, v186, v210
	v_fmac_f32_e32 v211, v187, v211
	v_fmac_f32_e32 v212, v188, v212
	v_fmac_f32_e32 v213, v189, v213
	v_fmac_f32_e32 v214, v190, v214
	v_fmac_f32_e32 v215, v191, v215
	v_div_scale_f32 v216, vcc, 1.0, v192, 1.0
	v_mul_f32_e32 v224, v216, v208
	v_fma_f32 v184, -v200, v224, v216
	v_fmac_f32_e32 v224, v184, v208
	v_fma_f32 v216, -v200, v224, v216
	v_div_fmas_f32 v216, v216, v208, v224
	v_div_fixup_f32 v184, v216, v192, 1.0
	v_div_scale_f32 v217, vcc, 1.0, v193, 1.0
	v_mul_f32_e32 v225, v217, v209
	v_fma_f32 v185, -v201, v225, v217
	v_fmac_f32_e32 v225, v185, v209
	v_fma_f32 v217, -v201, v225, v217
	v_div_fmas_f32 v217, v217, v209, v225
	v_div_fixup_f32 v185, v217, v193, 1.0
	v_div_scale_f32 v218, vcc, 1.0, v194, 1.0
	v_mul_f32_e32 v226, v218, v210
	v_fma_f32 v186, -v202, v226, v218
	v_fmac_f32_e32 v226, v186, v210
	v_fma_f32 v218, -v202, v226, v218
	v_div_fmas_f32 v218, v218, v210, v226
	v_div_fixup_f32 v186, v218, v194, 1.0
	v_div_scale_f32 v219, vcc, 1.0, v195, 1.0
	v_mul_f32_e32 v227, v219, v211
	v_fma_f32 v187, -v203, v227, v219
	v_fmac_f32_e32 v227, v187, v211
	v_fma_f32 v219, -v203, v227, v219
	v_div_fmas_f32 v219, v219, v211, v227
	v_div_fixup_f32 v187, v219, v195, 1.0
	v_div_scale_f32 v220, vcc, 1.0, v196, 1.0
	v_mul_f32_e32 v228, v220, v212
	v_fma_f32 v188, -v204, v228, v220
	v_fmac_f32_e32 v228, v188, v212
	v_fma_f32 v220, -v204, v228, v220
	v_div_fmas_f32 v220, v220, v212, v228
	v_div_fixup_f32 v188, v220, v196, 1.0
	v_div_scale_f32 v221, vcc, 1.0, v197, 1.0
	v_mul_f32_e32 v229, v221, v213
	v_fma_f32 v189, -v205, v229, v221
	v_fmac_f32_e32 v229, v189, v213
	v_fma_f32 v221, -v205, v229, v221
	v_div_fmas_f32 v221, v221, v213, v229
	v_div_fixup_f32 v189, v221, v197, 1.0
	v_div_scale_f32 v222, vcc, 1.0, v198, 1.0
	v_mul_f32_e32 v230, v222, v214
	v_fma_f32 v190, -v206, v230, v222
	v_fmac_f32_e32 v230, v190, v214
	v_fma_f32 v222, -v206, v230, v222
	v_div_fmas_f32 v222, v222, v214, v230
	v_div_fixup_f32 v190, v222, v198, 1.0
	v_div_scale_f32 v223, vcc, 1.0, v199, 1.0
	v_mul_f32_e32 v231, v223, v215
	v_fma_f32 v191, -v207, v231, v223
	v_fmac_f32_e32 v231, v191, v215
	v_fma_f32 v223, -v207, v231, v223
	v_div_fmas_f32 v223, v223, v215, v231
	v_div_fixup_f32 v191, v223, v199, 1.0
	v_lshlrev_b32_e32 v192, 16, v160
	v_and_b32_e32 v193, 0xffff0000, v160
	v_lshlrev_b32_e32 v200, 16, v180
	v_and_b32_e32 v201, 0xffff0000, v180
	v_lshlrev_b32_e32 v194, 16, v161
	v_and_b32_e32 v195, 0xffff0000, v161
	v_lshlrev_b32_e32 v202, 16, v181
	v_and_b32_e32 v203, 0xffff0000, v181
	v_lshlrev_b32_e32 v196, 16, v162
	v_and_b32_e32 v197, 0xffff0000, v162
	v_lshlrev_b32_e32 v204, 16, v182
	v_and_b32_e32 v205, 0xffff0000, v182
	v_lshlrev_b32_e32 v198, 16, v163
	v_and_b32_e32 v199, 0xffff0000, v163
	v_lshlrev_b32_e32 v206, 16, v183
	v_and_b32_e32 v207, 0xffff0000, v183
	v_fma_f32 v184, v184, v200, v192
	v_fma_f32 v185, v185, v201, v193
	v_fma_f32 v186, v186, v202, v194
	v_fma_f32 v187, v187, v203, v195
	v_fma_f32 v188, v188, v204, v196
	v_fma_f32 v189, v189, v205, v197
	v_fma_f32 v190, v190, v206, v198
	v_fma_f32 v191, v191, v207, v199
	v_cvt_pk_bf16_f32 v220, v184, v185
	v_cvt_pk_bf16_f32 v221, v186, v187
	v_cvt_pk_bf16_f32 v222, v188, v189
	v_cvt_pk_bf16_f32 v223, v190, v191
	s_nop 1
	v_permlane16_swap_b32_e32 v220, v222
	v_permlane16_swap_b32_e32 v221, v223
	global_store_dwordx4 v246, v[220:223], s[26:27] offset:64
	global_load_dwordx4 v[148:151], v243, s[86:87]
	s_add_u32 s86, s86, 0x1000
	s_addc_u32 s87, s87, 0
	global_load_dwordx4 v[164:167], v243, s[88:89]
	s_add_u32 s88, s88, 0x1000
	s_addc_u32 s89, s89, 0
	global_load_dwordx4 v[152:155], v243, s[86:87]
	s_add_u32 s86, s86, 0x1000
	s_addc_u32 s87, s87, 0
	global_load_dwordx4 v[172:175], v243, s[88:89]
	s_add_u32 s88, s88, 0x1000
	s_addc_u32 s89, s89, 0
	global_load_dwordx4 v[156:159], v243, s[86:87]
	s_add_u32 s86, s86, 0x1000
	s_addc_u32 s87, s87, 0
	global_load_dwordx4 v[176:179], v243, s[88:89]
	s_add_u32 s88, s88, 0x1000
	s_addc_u32 s89, s89, 0
	global_load_dwordx4 v[160:163], v243, s[86:87]
	s_add_u32 s86, s86, 0x1000
	s_addc_u32 s87, s87, 0
	global_load_dwordx4 v[180:183], v243, s[88:89]
	s_add_u32 s88, s88, 0x1000
	s_addc_u32 s89, s89, 0
	s_waitcnt vmcnt(6)
	v_add_f32_e32 v184, v32, v128
	v_add_f32_e32 v185, v33, v129
	v_add_f32_e32 v186, v34, v130
	v_add_f32_e32 v187, v35, v131
	v_add_f32_e32 v188, v36, v132
	v_add_f32_e32 v189, v37, v133
	v_add_f32_e32 v190, v38, v134
	v_add_f32_e32 v191, v39, v135
	v_mul_f32_e32 v184, 0xbfb8aa3b, v184
	v_mul_f32_e32 v185, 0xbfb8aa3b, v185
	v_mul_f32_e32 v186, 0xbfb8aa3b, v186
	v_mul_f32_e32 v187, 0xbfb8aa3b, v187
	v_mul_f32_e32 v188, 0xbfb8aa3b, v188
	v_mul_f32_e32 v189, 0xbfb8aa3b, v189
	v_mul_f32_e32 v190, 0xbfb8aa3b, v190
	v_mul_f32_e32 v191, 0xbfb8aa3b, v191
	v_exp_f32_e32 v192, v184
	v_exp_f32_e32 v193, v185
	v_exp_f32_e32 v194, v186
	v_exp_f32_e32 v195, v187
	v_exp_f32_e32 v196, v188
	v_exp_f32_e32 v197, v189
	v_exp_f32_e32 v198, v190
	v_exp_f32_e32 v199, v191
	v_add_f32_e32 v192, 1.0, v192
	v_add_f32_e32 v193, 1.0, v193
	v_add_f32_e32 v194, 1.0, v194
	v_add_f32_e32 v195, 1.0, v195
	v_add_f32_e32 v196, 1.0, v196
	v_add_f32_e32 v197, 1.0, v197
	v_add_f32_e32 v198, 1.0, v198
	v_add_f32_e32 v199, 1.0, v199
	v_div_scale_f32 v200, s[76:77], v192, v192, 1.0
	v_div_scale_f32 v201, s[76:77], v193, v193, 1.0
	v_div_scale_f32 v202, s[76:77], v194, v194, 1.0
	v_div_scale_f32 v203, s[76:77], v195, v195, 1.0
	v_div_scale_f32 v204, s[76:77], v196, v196, 1.0
	v_div_scale_f32 v205, s[76:77], v197, v197, 1.0
	v_div_scale_f32 v206, s[76:77], v198, v198, 1.0
	v_div_scale_f32 v207, s[76:77], v199, v199, 1.0
	v_rcp_f32_e32 v208, v200
	v_rcp_f32_e32 v209, v201
	v_rcp_f32_e32 v210, v202
	v_rcp_f32_e32 v211, v203
	v_rcp_f32_e32 v212, v204
	v_rcp_f32_e32 v213, v205
	v_rcp_f32_e32 v214, v206
	v_rcp_f32_e32 v215, v207
	v_fma_f32 v184, -v200, v208, 1.0
	v_fma_f32 v185, -v201, v209, 1.0
	v_fma_f32 v186, -v202, v210, 1.0
	v_fma_f32 v187, -v203, v211, 1.0
	v_fma_f32 v188, -v204, v212, 1.0
	v_fma_f32 v189, -v205, v213, 1.0
	v_fma_f32 v190, -v206, v214, 1.0
	v_fma_f32 v191, -v207, v215, 1.0
	v_fmac_f32_e32 v208, v184, v208
	v_fmac_f32_e32 v209, v185, v209
	v_fmac_f32_e32 v210, v186, v210
	v_fmac_f32_e32 v211, v187, v211
	v_fmac_f32_e32 v212, v188, v212
	v_fmac_f32_e32 v213, v189, v213
	v_fmac_f32_e32 v214, v190, v214
	v_fmac_f32_e32 v215, v191, v215
	v_div_scale_f32 v216, vcc, 1.0, v192, 1.0
	v_mul_f32_e32 v224, v216, v208
	v_fma_f32 v184, -v200, v224, v216
	v_fmac_f32_e32 v224, v184, v208
	v_fma_f32 v216, -v200, v224, v216
	v_div_fmas_f32 v216, v216, v208, v224
	v_div_fixup_f32 v184, v216, v192, 1.0
	v_div_scale_f32 v217, vcc, 1.0, v193, 1.0
	v_mul_f32_e32 v225, v217, v209
	v_fma_f32 v185, -v201, v225, v217
	v_fmac_f32_e32 v225, v185, v209
	v_fma_f32 v217, -v201, v225, v217
	v_div_fmas_f32 v217, v217, v209, v225
	v_div_fixup_f32 v185, v217, v193, 1.0
	v_div_scale_f32 v218, vcc, 1.0, v194, 1.0
	v_mul_f32_e32 v226, v218, v210
	v_fma_f32 v186, -v202, v226, v218
	v_fmac_f32_e32 v226, v186, v210
	v_fma_f32 v218, -v202, v226, v218
	v_div_fmas_f32 v218, v218, v210, v226
	v_div_fixup_f32 v186, v218, v194, 1.0
	v_div_scale_f32 v219, vcc, 1.0, v195, 1.0
	v_mul_f32_e32 v227, v219, v211
	v_fma_f32 v187, -v203, v227, v219
	v_fmac_f32_e32 v227, v187, v211
	v_fma_f32 v219, -v203, v227, v219
	v_div_fmas_f32 v219, v219, v211, v227
	v_div_fixup_f32 v187, v219, v195, 1.0
	v_div_scale_f32 v220, vcc, 1.0, v196, 1.0
	v_mul_f32_e32 v228, v220, v212
	v_fma_f32 v188, -v204, v228, v220
	v_fmac_f32_e32 v228, v188, v212
	v_fma_f32 v220, -v204, v228, v220
	v_div_fmas_f32 v220, v220, v212, v228
	v_div_fixup_f32 v188, v220, v196, 1.0
	v_div_scale_f32 v221, vcc, 1.0, v197, 1.0
	v_mul_f32_e32 v229, v221, v213
	v_fma_f32 v189, -v205, v229, v221
	v_fmac_f32_e32 v229, v189, v213
	v_fma_f32 v221, -v205, v229, v221
	v_div_fmas_f32 v221, v221, v213, v229
	v_div_fixup_f32 v189, v221, v197, 1.0
	v_div_scale_f32 v222, vcc, 1.0, v198, 1.0
	v_mul_f32_e32 v230, v222, v214
	v_fma_f32 v190, -v206, v230, v222
	v_fmac_f32_e32 v230, v190, v214
	v_fma_f32 v222, -v206, v230, v222
	v_div_fmas_f32 v222, v222, v214, v230
	v_div_fixup_f32 v190, v222, v198, 1.0
	v_div_scale_f32 v223, vcc, 1.0, v199, 1.0
	v_mul_f32_e32 v231, v223, v215
	v_fma_f32 v191, -v207, v231, v223
	v_fmac_f32_e32 v231, v191, v215
	v_fma_f32 v223, -v207, v231, v223
	v_div_fmas_f32 v223, v223, v215, v231
	v_div_fixup_f32 v191, v223, v199, 1.0
	v_lshlrev_b32_e32 v192, 16, v148
	v_and_b32_e32 v193, 0xffff0000, v148
	v_lshlrev_b32_e32 v200, 16, v164
	v_and_b32_e32 v201, 0xffff0000, v164
	v_lshlrev_b32_e32 v194, 16, v149
	v_and_b32_e32 v195, 0xffff0000, v149
	v_lshlrev_b32_e32 v202, 16, v165
	v_and_b32_e32 v203, 0xffff0000, v165
	v_lshlrev_b32_e32 v196, 16, v150
	v_and_b32_e32 v197, 0xffff0000, v150
	v_lshlrev_b32_e32 v204, 16, v166
	v_and_b32_e32 v205, 0xffff0000, v166
	v_lshlrev_b32_e32 v198, 16, v151
	v_and_b32_e32 v199, 0xffff0000, v151
	v_lshlrev_b32_e32 v206, 16, v167
	v_and_b32_e32 v207, 0xffff0000, v167
	v_fma_f32 v184, v184, v200, v192
	v_fma_f32 v185, v185, v201, v193
	v_fma_f32 v186, v186, v202, v194
	v_fma_f32 v187, v187, v203, v195
	v_fma_f32 v188, v188, v204, v196
	v_fma_f32 v189, v189, v205, v197
	v_fma_f32 v190, v190, v206, v198
	v_fma_f32 v191, v191, v207, v199
	v_cvt_pk_bf16_f32 v216, v184, v185
	v_cvt_pk_bf16_f32 v217, v186, v187
	v_cvt_pk_bf16_f32 v218, v188, v189
	v_cvt_pk_bf16_f32 v219, v190, v191
	s_nop 1
	v_permlane16_swap_b32_e32 v216, v218
	v_permlane16_swap_b32_e32 v217, v219
	global_store_dwordx4 v247, v[216:219], s[26:27]
	s_waitcnt vmcnt(5)
	v_add_f32_e32 v184, v40, v136
	v_add_f32_e32 v185, v41, v137
	v_add_f32_e32 v186, v42, v138
	v_add_f32_e32 v187, v43, v139
	v_add_f32_e32 v188, v44, v140
	v_add_f32_e32 v189, v45, v141
	v_add_f32_e32 v190, v46, v142
	v_add_f32_e32 v191, v47, v143
	v_mul_f32_e32 v184, 0xbfb8aa3b, v184
	v_mul_f32_e32 v185, 0xbfb8aa3b, v185
	v_mul_f32_e32 v186, 0xbfb8aa3b, v186
	v_mul_f32_e32 v187, 0xbfb8aa3b, v187
	v_mul_f32_e32 v188, 0xbfb8aa3b, v188
	v_mul_f32_e32 v189, 0xbfb8aa3b, v189
	v_mul_f32_e32 v190, 0xbfb8aa3b, v190
	v_mul_f32_e32 v191, 0xbfb8aa3b, v191
	v_exp_f32_e32 v192, v184
	v_exp_f32_e32 v193, v185
	v_exp_f32_e32 v194, v186
	v_exp_f32_e32 v195, v187
	v_exp_f32_e32 v196, v188
	v_exp_f32_e32 v197, v189
	v_exp_f32_e32 v198, v190
	v_exp_f32_e32 v199, v191
	v_add_f32_e32 v192, 1.0, v192
	v_add_f32_e32 v193, 1.0, v193
	v_add_f32_e32 v194, 1.0, v194
	v_add_f32_e32 v195, 1.0, v195
	v_add_f32_e32 v196, 1.0, v196
	v_add_f32_e32 v197, 1.0, v197
	v_add_f32_e32 v198, 1.0, v198
	v_add_f32_e32 v199, 1.0, v199
	v_div_scale_f32 v200, s[76:77], v192, v192, 1.0
	v_div_scale_f32 v201, s[76:77], v193, v193, 1.0
	v_div_scale_f32 v202, s[76:77], v194, v194, 1.0
	v_div_scale_f32 v203, s[76:77], v195, v195, 1.0
	v_div_scale_f32 v204, s[76:77], v196, v196, 1.0
	v_div_scale_f32 v205, s[76:77], v197, v197, 1.0
	v_div_scale_f32 v206, s[76:77], v198, v198, 1.0
	v_div_scale_f32 v207, s[76:77], v199, v199, 1.0
	v_rcp_f32_e32 v208, v200
	v_rcp_f32_e32 v209, v201
	v_rcp_f32_e32 v210, v202
	v_rcp_f32_e32 v211, v203
	v_rcp_f32_e32 v212, v204
	v_rcp_f32_e32 v213, v205
	v_rcp_f32_e32 v214, v206
	v_rcp_f32_e32 v215, v207
	v_fma_f32 v184, -v200, v208, 1.0
	v_fma_f32 v185, -v201, v209, 1.0
	v_fma_f32 v186, -v202, v210, 1.0
	v_fma_f32 v187, -v203, v211, 1.0
	v_fma_f32 v188, -v204, v212, 1.0
	v_fma_f32 v189, -v205, v213, 1.0
	v_fma_f32 v190, -v206, v214, 1.0
	v_fma_f32 v191, -v207, v215, 1.0
	v_fmac_f32_e32 v208, v184, v208
	v_fmac_f32_e32 v209, v185, v209
	v_fmac_f32_e32 v210, v186, v210
	v_fmac_f32_e32 v211, v187, v211
	v_fmac_f32_e32 v212, v188, v212
	v_fmac_f32_e32 v213, v189, v213
	v_fmac_f32_e32 v214, v190, v214
	v_fmac_f32_e32 v215, v191, v215
	v_div_scale_f32 v216, vcc, 1.0, v192, 1.0
	v_mul_f32_e32 v224, v216, v208
	v_fma_f32 v184, -v200, v224, v216
	v_fmac_f32_e32 v224, v184, v208
	v_fma_f32 v216, -v200, v224, v216
	v_div_fmas_f32 v216, v216, v208, v224
	v_div_fixup_f32 v184, v216, v192, 1.0
	v_div_scale_f32 v217, vcc, 1.0, v193, 1.0
	v_mul_f32_e32 v225, v217, v209
	v_fma_f32 v185, -v201, v225, v217
	v_fmac_f32_e32 v225, v185, v209
	v_fma_f32 v217, -v201, v225, v217
	v_div_fmas_f32 v217, v217, v209, v225
	v_div_fixup_f32 v185, v217, v193, 1.0
	v_div_scale_f32 v218, vcc, 1.0, v194, 1.0
	v_mul_f32_e32 v226, v218, v210
	v_fma_f32 v186, -v202, v226, v218
	v_fmac_f32_e32 v226, v186, v210
	v_fma_f32 v218, -v202, v226, v218
	v_div_fmas_f32 v218, v218, v210, v226
	v_div_fixup_f32 v186, v218, v194, 1.0
	v_div_scale_f32 v219, vcc, 1.0, v195, 1.0
	v_mul_f32_e32 v227, v219, v211
	v_fma_f32 v187, -v203, v227, v219
	v_fmac_f32_e32 v227, v187, v211
	v_fma_f32 v219, -v203, v227, v219
	v_div_fmas_f32 v219, v219, v211, v227
	v_div_fixup_f32 v187, v219, v195, 1.0
	v_div_scale_f32 v220, vcc, 1.0, v196, 1.0
	v_mul_f32_e32 v228, v220, v212
	v_fma_f32 v188, -v204, v228, v220
	v_fmac_f32_e32 v228, v188, v212
	v_fma_f32 v220, -v204, v228, v220
	v_div_fmas_f32 v220, v220, v212, v228
	v_div_fixup_f32 v188, v220, v196, 1.0
	v_div_scale_f32 v221, vcc, 1.0, v197, 1.0
	v_mul_f32_e32 v229, v221, v213
	v_fma_f32 v189, -v205, v229, v221
	v_fmac_f32_e32 v229, v189, v213
	v_fma_f32 v221, -v205, v229, v221
	v_div_fmas_f32 v221, v221, v213, v229
	v_div_fixup_f32 v189, v221, v197, 1.0
	v_div_scale_f32 v222, vcc, 1.0, v198, 1.0
	v_mul_f32_e32 v230, v222, v214
	v_fma_f32 v190, -v206, v230, v222
	v_fmac_f32_e32 v230, v190, v214
	v_fma_f32 v222, -v206, v230, v222
	v_div_fmas_f32 v222, v222, v214, v230
	v_div_fixup_f32 v190, v222, v198, 1.0
	v_div_scale_f32 v223, vcc, 1.0, v199, 1.0
	v_mul_f32_e32 v231, v223, v215
	v_fma_f32 v191, -v207, v231, v223
	v_fmac_f32_e32 v231, v191, v215
	v_fma_f32 v223, -v207, v231, v223
	v_div_fmas_f32 v223, v223, v215, v231
	v_div_fixup_f32 v191, v223, v199, 1.0
	v_lshlrev_b32_e32 v192, 16, v152
	v_and_b32_e32 v193, 0xffff0000, v152
	v_lshlrev_b32_e32 v200, 16, v172
	v_and_b32_e32 v201, 0xffff0000, v172
	v_lshlrev_b32_e32 v194, 16, v153
	v_and_b32_e32 v195, 0xffff0000, v153
	v_lshlrev_b32_e32 v202, 16, v173
	v_and_b32_e32 v203, 0xffff0000, v173
	v_lshlrev_b32_e32 v196, 16, v154
	v_and_b32_e32 v197, 0xffff0000, v154
	v_lshlrev_b32_e32 v204, 16, v174
	v_and_b32_e32 v205, 0xffff0000, v174
	v_lshlrev_b32_e32 v198, 16, v155
	v_and_b32_e32 v199, 0xffff0000, v155
	v_lshlrev_b32_e32 v206, 16, v175
	v_and_b32_e32 v207, 0xffff0000, v175
	v_fma_f32 v184, v184, v200, v192
	v_fma_f32 v185, v185, v201, v193
	v_fma_f32 v186, v186, v202, v194
	v_fma_f32 v187, v187, v203, v195
	v_fma_f32 v188, v188, v204, v196
	v_fma_f32 v189, v189, v205, v197
	v_fma_f32 v190, v190, v206, v198
	v_fma_f32 v191, v191, v207, v199
	v_cvt_pk_bf16_f32 v220, v184, v185
	v_cvt_pk_bf16_f32 v221, v186, v187
	v_cvt_pk_bf16_f32 v222, v188, v189
	v_cvt_pk_bf16_f32 v223, v190, v191
	s_nop 1
	v_permlane16_swap_b32_e32 v220, v222
	v_permlane16_swap_b32_e32 v221, v223
	global_store_dwordx4 v247, v[220:223], s[26:27] offset:64
	s_waitcnt vmcnt(4)
	v_add_f32_e32 v184, v48, v128
	v_add_f32_e32 v185, v49, v129
	v_add_f32_e32 v186, v50, v130
	v_add_f32_e32 v187, v51, v131
	v_add_f32_e32 v188, v52, v132
	v_add_f32_e32 v189, v53, v133
	v_add_f32_e32 v190, v54, v134
	v_add_f32_e32 v191, v55, v135
	v_mul_f32_e32 v184, 0xbfb8aa3b, v184
	v_mul_f32_e32 v185, 0xbfb8aa3b, v185
	v_mul_f32_e32 v186, 0xbfb8aa3b, v186
	v_mul_f32_e32 v187, 0xbfb8aa3b, v187
	v_mul_f32_e32 v188, 0xbfb8aa3b, v188
	v_mul_f32_e32 v189, 0xbfb8aa3b, v189
	v_mul_f32_e32 v190, 0xbfb8aa3b, v190
	v_mul_f32_e32 v191, 0xbfb8aa3b, v191
	v_exp_f32_e32 v192, v184
	v_exp_f32_e32 v193, v185
	v_exp_f32_e32 v194, v186
	v_exp_f32_e32 v195, v187
	v_exp_f32_e32 v196, v188
	v_exp_f32_e32 v197, v189
	v_exp_f32_e32 v198, v190
	v_exp_f32_e32 v199, v191
	v_add_f32_e32 v192, 1.0, v192
	v_add_f32_e32 v193, 1.0, v193
	v_add_f32_e32 v194, 1.0, v194
	v_add_f32_e32 v195, 1.0, v195
	v_add_f32_e32 v196, 1.0, v196
	v_add_f32_e32 v197, 1.0, v197
	v_add_f32_e32 v198, 1.0, v198
	v_add_f32_e32 v199, 1.0, v199
	v_div_scale_f32 v200, s[76:77], v192, v192, 1.0
	v_div_scale_f32 v201, s[76:77], v193, v193, 1.0
	v_div_scale_f32 v202, s[76:77], v194, v194, 1.0
	v_div_scale_f32 v203, s[76:77], v195, v195, 1.0
	v_div_scale_f32 v204, s[76:77], v196, v196, 1.0
	v_div_scale_f32 v205, s[76:77], v197, v197, 1.0
	v_div_scale_f32 v206, s[76:77], v198, v198, 1.0
	v_div_scale_f32 v207, s[76:77], v199, v199, 1.0
	v_rcp_f32_e32 v208, v200
	v_rcp_f32_e32 v209, v201
	v_rcp_f32_e32 v210, v202
	v_rcp_f32_e32 v211, v203
	v_rcp_f32_e32 v212, v204
	v_rcp_f32_e32 v213, v205
	v_rcp_f32_e32 v214, v206
	v_rcp_f32_e32 v215, v207
	v_fma_f32 v184, -v200, v208, 1.0
	v_fma_f32 v185, -v201, v209, 1.0
	v_fma_f32 v186, -v202, v210, 1.0
	v_fma_f32 v187, -v203, v211, 1.0
	v_fma_f32 v188, -v204, v212, 1.0
	v_fma_f32 v189, -v205, v213, 1.0
	v_fma_f32 v190, -v206, v214, 1.0
	v_fma_f32 v191, -v207, v215, 1.0
	v_fmac_f32_e32 v208, v184, v208
	v_fmac_f32_e32 v209, v185, v209
	v_fmac_f32_e32 v210, v186, v210
	v_fmac_f32_e32 v211, v187, v211
	v_fmac_f32_e32 v212, v188, v212
	v_fmac_f32_e32 v213, v189, v213
	v_fmac_f32_e32 v214, v190, v214
	v_fmac_f32_e32 v215, v191, v215
	v_div_scale_f32 v216, vcc, 1.0, v192, 1.0
	v_mul_f32_e32 v224, v216, v208
	v_fma_f32 v184, -v200, v224, v216
	v_fmac_f32_e32 v224, v184, v208
	v_fma_f32 v216, -v200, v224, v216
	v_div_fmas_f32 v216, v216, v208, v224
	v_div_fixup_f32 v184, v216, v192, 1.0
	v_div_scale_f32 v217, vcc, 1.0, v193, 1.0
	v_mul_f32_e32 v225, v217, v209
	v_fma_f32 v185, -v201, v225, v217
	v_fmac_f32_e32 v225, v185, v209
	v_fma_f32 v217, -v201, v225, v217
	v_div_fmas_f32 v217, v217, v209, v225
	v_div_fixup_f32 v185, v217, v193, 1.0
	v_div_scale_f32 v218, vcc, 1.0, v194, 1.0
	v_mul_f32_e32 v226, v218, v210
	v_fma_f32 v186, -v202, v226, v218
	v_fmac_f32_e32 v226, v186, v210
	v_fma_f32 v218, -v202, v226, v218
	v_div_fmas_f32 v218, v218, v210, v226
	v_div_fixup_f32 v186, v218, v194, 1.0
	v_div_scale_f32 v219, vcc, 1.0, v195, 1.0
	v_mul_f32_e32 v227, v219, v211
	v_fma_f32 v187, -v203, v227, v219
	v_fmac_f32_e32 v227, v187, v211
	v_fma_f32 v219, -v203, v227, v219
	v_div_fmas_f32 v219, v219, v211, v227
	v_div_fixup_f32 v187, v219, v195, 1.0
	v_div_scale_f32 v220, vcc, 1.0, v196, 1.0
	v_mul_f32_e32 v228, v220, v212
	v_fma_f32 v188, -v204, v228, v220
	v_fmac_f32_e32 v228, v188, v212
	v_fma_f32 v220, -v204, v228, v220
	v_div_fmas_f32 v220, v220, v212, v228
	v_div_fixup_f32 v188, v220, v196, 1.0
	v_div_scale_f32 v221, vcc, 1.0, v197, 1.0
	v_mul_f32_e32 v229, v221, v213
	v_fma_f32 v189, -v205, v229, v221
	v_fmac_f32_e32 v229, v189, v213
	v_fma_f32 v221, -v205, v229, v221
	v_div_fmas_f32 v221, v221, v213, v229
	v_div_fixup_f32 v189, v221, v197, 1.0
	v_div_scale_f32 v222, vcc, 1.0, v198, 1.0
	v_mul_f32_e32 v230, v222, v214
	v_fma_f32 v190, -v206, v230, v222
	v_fmac_f32_e32 v230, v190, v214
	v_fma_f32 v222, -v206, v230, v222
	v_div_fmas_f32 v222, v222, v214, v230
	v_div_fixup_f32 v190, v222, v198, 1.0
	v_div_scale_f32 v223, vcc, 1.0, v199, 1.0
	v_mul_f32_e32 v231, v223, v215
	v_fma_f32 v191, -v207, v231, v223
	v_fmac_f32_e32 v231, v191, v215
	v_fma_f32 v223, -v207, v231, v223
	v_div_fmas_f32 v223, v223, v215, v231
	v_div_fixup_f32 v191, v223, v199, 1.0
	v_lshlrev_b32_e32 v192, 16, v156
	v_and_b32_e32 v193, 0xffff0000, v156
	v_lshlrev_b32_e32 v200, 16, v176
	v_and_b32_e32 v201, 0xffff0000, v176
	v_lshlrev_b32_e32 v194, 16, v157
	v_and_b32_e32 v195, 0xffff0000, v157
	v_lshlrev_b32_e32 v202, 16, v177
	v_and_b32_e32 v203, 0xffff0000, v177
	v_lshlrev_b32_e32 v196, 16, v158
	v_and_b32_e32 v197, 0xffff0000, v158
	v_lshlrev_b32_e32 v204, 16, v178
	v_and_b32_e32 v205, 0xffff0000, v178
	v_lshlrev_b32_e32 v198, 16, v159
	v_and_b32_e32 v199, 0xffff0000, v159
	v_lshlrev_b32_e32 v206, 16, v179
	v_and_b32_e32 v207, 0xffff0000, v179
	v_fma_f32 v184, v184, v200, v192
	v_fma_f32 v185, v185, v201, v193
	v_fma_f32 v186, v186, v202, v194
	v_fma_f32 v187, v187, v203, v195
	v_fma_f32 v188, v188, v204, v196
	v_fma_f32 v189, v189, v205, v197
	v_fma_f32 v190, v190, v206, v198
	v_fma_f32 v191, v191, v207, v199
	v_cvt_pk_bf16_f32 v216, v184, v185
	v_cvt_pk_bf16_f32 v217, v186, v187
	v_cvt_pk_bf16_f32 v218, v188, v189
	v_cvt_pk_bf16_f32 v219, v190, v191
	s_nop 1
	v_permlane16_swap_b32_e32 v216, v218
	v_permlane16_swap_b32_e32 v217, v219
	global_store_dwordx4 v248, v[216:219], s[26:27]
	s_waitcnt vmcnt(3)
	v_add_f32_e32 v184, v56, v136
	v_add_f32_e32 v185, v57, v137
	v_add_f32_e32 v186, v58, v138
	v_add_f32_e32 v187, v59, v139
	v_add_f32_e32 v188, v60, v140
	v_add_f32_e32 v189, v61, v141
	v_add_f32_e32 v190, v62, v142
	v_add_f32_e32 v191, v63, v143
	v_mul_f32_e32 v184, 0xbfb8aa3b, v184
	v_mul_f32_e32 v185, 0xbfb8aa3b, v185
	v_mul_f32_e32 v186, 0xbfb8aa3b, v186
	v_mul_f32_e32 v187, 0xbfb8aa3b, v187
	v_mul_f32_e32 v188, 0xbfb8aa3b, v188
	v_mul_f32_e32 v189, 0xbfb8aa3b, v189
	v_mul_f32_e32 v190, 0xbfb8aa3b, v190
	v_mul_f32_e32 v191, 0xbfb8aa3b, v191
	v_exp_f32_e32 v192, v184
	v_exp_f32_e32 v193, v185
	v_exp_f32_e32 v194, v186
	v_exp_f32_e32 v195, v187
	v_exp_f32_e32 v196, v188
	v_exp_f32_e32 v197, v189
	v_exp_f32_e32 v198, v190
	v_exp_f32_e32 v199, v191
	v_add_f32_e32 v192, 1.0, v192
	v_add_f32_e32 v193, 1.0, v193
	v_add_f32_e32 v194, 1.0, v194
	v_add_f32_e32 v195, 1.0, v195
	v_add_f32_e32 v196, 1.0, v196
	v_add_f32_e32 v197, 1.0, v197
	v_add_f32_e32 v198, 1.0, v198
	v_add_f32_e32 v199, 1.0, v199
	v_div_scale_f32 v200, s[76:77], v192, v192, 1.0
	v_div_scale_f32 v201, s[76:77], v193, v193, 1.0
	v_div_scale_f32 v202, s[76:77], v194, v194, 1.0
	v_div_scale_f32 v203, s[76:77], v195, v195, 1.0
	v_div_scale_f32 v204, s[76:77], v196, v196, 1.0
	v_div_scale_f32 v205, s[76:77], v197, v197, 1.0
	v_div_scale_f32 v206, s[76:77], v198, v198, 1.0
	v_div_scale_f32 v207, s[76:77], v199, v199, 1.0
	v_rcp_f32_e32 v208, v200
	v_rcp_f32_e32 v209, v201
	v_rcp_f32_e32 v210, v202
	v_rcp_f32_e32 v211, v203
	v_rcp_f32_e32 v212, v204
	v_rcp_f32_e32 v213, v205
	v_rcp_f32_e32 v214, v206
	v_rcp_f32_e32 v215, v207
	v_fma_f32 v184, -v200, v208, 1.0
	v_fma_f32 v185, -v201, v209, 1.0
	v_fma_f32 v186, -v202, v210, 1.0
	v_fma_f32 v187, -v203, v211, 1.0
	v_fma_f32 v188, -v204, v212, 1.0
	v_fma_f32 v189, -v205, v213, 1.0
	v_fma_f32 v190, -v206, v214, 1.0
	v_fma_f32 v191, -v207, v215, 1.0
	v_fmac_f32_e32 v208, v184, v208
	v_fmac_f32_e32 v209, v185, v209
	v_fmac_f32_e32 v210, v186, v210
	v_fmac_f32_e32 v211, v187, v211
	v_fmac_f32_e32 v212, v188, v212
	v_fmac_f32_e32 v213, v189, v213
	v_fmac_f32_e32 v214, v190, v214
	v_fmac_f32_e32 v215, v191, v215
	v_div_scale_f32 v216, vcc, 1.0, v192, 1.0
	v_mul_f32_e32 v224, v216, v208
	v_fma_f32 v184, -v200, v224, v216
	v_fmac_f32_e32 v224, v184, v208
	v_fma_f32 v216, -v200, v224, v216
	v_div_fmas_f32 v216, v216, v208, v224
	v_div_fixup_f32 v184, v216, v192, 1.0
	v_div_scale_f32 v217, vcc, 1.0, v193, 1.0
	v_mul_f32_e32 v225, v217, v209
	v_fma_f32 v185, -v201, v225, v217
	v_fmac_f32_e32 v225, v185, v209
	v_fma_f32 v217, -v201, v225, v217
	v_div_fmas_f32 v217, v217, v209, v225
	v_div_fixup_f32 v185, v217, v193, 1.0
	v_div_scale_f32 v218, vcc, 1.0, v194, 1.0
	v_mul_f32_e32 v226, v218, v210
	v_fma_f32 v186, -v202, v226, v218
	v_fmac_f32_e32 v226, v186, v210
	v_fma_f32 v218, -v202, v226, v218
	v_div_fmas_f32 v218, v218, v210, v226
	v_div_fixup_f32 v186, v218, v194, 1.0
	v_div_scale_f32 v219, vcc, 1.0, v195, 1.0
	v_mul_f32_e32 v227, v219, v211
	v_fma_f32 v187, -v203, v227, v219
	v_fmac_f32_e32 v227, v187, v211
	v_fma_f32 v219, -v203, v227, v219
	v_div_fmas_f32 v219, v219, v211, v227
	v_div_fixup_f32 v187, v219, v195, 1.0
	v_div_scale_f32 v220, vcc, 1.0, v196, 1.0
	v_mul_f32_e32 v228, v220, v212
	v_fma_f32 v188, -v204, v228, v220
	v_fmac_f32_e32 v228, v188, v212
	v_fma_f32 v220, -v204, v228, v220
	v_div_fmas_f32 v220, v220, v212, v228
	v_div_fixup_f32 v188, v220, v196, 1.0
	v_div_scale_f32 v221, vcc, 1.0, v197, 1.0
	v_mul_f32_e32 v229, v221, v213
	v_fma_f32 v189, -v205, v229, v221
	v_fmac_f32_e32 v229, v189, v213
	v_fma_f32 v221, -v205, v229, v221
	v_div_fmas_f32 v221, v221, v213, v229
	v_div_fixup_f32 v189, v221, v197, 1.0
	v_div_scale_f32 v222, vcc, 1.0, v198, 1.0
	v_mul_f32_e32 v230, v222, v214
	v_fma_f32 v190, -v206, v230, v222
	v_fmac_f32_e32 v230, v190, v214
	v_fma_f32 v222, -v206, v230, v222
	v_div_fmas_f32 v222, v222, v214, v230
	v_div_fixup_f32 v190, v222, v198, 1.0
	v_div_scale_f32 v223, vcc, 1.0, v199, 1.0
	v_mul_f32_e32 v231, v223, v215
	v_fma_f32 v191, -v207, v231, v223
	v_fmac_f32_e32 v231, v191, v215
	v_fma_f32 v223, -v207, v231, v223
	v_div_fmas_f32 v223, v223, v215, v231
	v_div_fixup_f32 v191, v223, v199, 1.0
	v_lshlrev_b32_e32 v192, 16, v160
	v_and_b32_e32 v193, 0xffff0000, v160
	v_lshlrev_b32_e32 v200, 16, v180
	v_and_b32_e32 v201, 0xffff0000, v180
	v_lshlrev_b32_e32 v194, 16, v161
	v_and_b32_e32 v195, 0xffff0000, v161
	v_lshlrev_b32_e32 v202, 16, v181
	v_and_b32_e32 v203, 0xffff0000, v181
	v_lshlrev_b32_e32 v196, 16, v162
	v_and_b32_e32 v197, 0xffff0000, v162
	v_lshlrev_b32_e32 v204, 16, v182
	v_and_b32_e32 v205, 0xffff0000, v182
	v_lshlrev_b32_e32 v198, 16, v163
	v_and_b32_e32 v199, 0xffff0000, v163
	v_lshlrev_b32_e32 v206, 16, v183
	v_and_b32_e32 v207, 0xffff0000, v183
	v_fma_f32 v184, v184, v200, v192
	v_fma_f32 v185, v185, v201, v193
	v_fma_f32 v186, v186, v202, v194
	v_fma_f32 v187, v187, v203, v195
	v_fma_f32 v188, v188, v204, v196
	v_fma_f32 v189, v189, v205, v197
	v_fma_f32 v190, v190, v206, v198
	v_fma_f32 v191, v191, v207, v199
	v_cvt_pk_bf16_f32 v220, v184, v185
	v_cvt_pk_bf16_f32 v221, v186, v187
	v_cvt_pk_bf16_f32 v222, v188, v189
	v_cvt_pk_bf16_f32 v223, v190, v191
	s_nop 1
	v_permlane16_swap_b32_e32 v220, v222
	v_permlane16_swap_b32_e32 v221, v223
	global_store_dwordx4 v248, v[220:223], s[26:27] offset:64
	s_cmp_eq_u32 s83, 1
	s_cbranch_scc1 .Lp6d_epdone
	s_cmp_eq_u32 s95, 1
	s_cbranch_scc0 .Lp6d_epdone
	v_mov_b32_e32 v0, v64
	v_mov_b32_e32 v1, v65
	v_mov_b32_e32 v2, v66
	v_mov_b32_e32 v3, v67
	v_mov_b32_e32 v4, v68
	v_mov_b32_e32 v5, v69
	v_mov_b32_e32 v6, v70
	v_mov_b32_e32 v7, v71
	v_mov_b32_e32 v8, v72
	v_mov_b32_e32 v9, v73
	v_mov_b32_e32 v10, v74
	v_mov_b32_e32 v11, v75
	v_mov_b32_e32 v12, v76
	v_mov_b32_e32 v13, v77
	v_mov_b32_e32 v14, v78
	v_mov_b32_e32 v15, v79
	v_mov_b32_e32 v16, v80
	v_mov_b32_e32 v17, v81
	v_mov_b32_e32 v18, v82
	v_mov_b32_e32 v19, v83
	v_mov_b32_e32 v20, v84
	v_mov_b32_e32 v21, v85
	v_mov_b32_e32 v22, v86
	v_mov_b32_e32 v23, v87
	v_mov_b32_e32 v24, v88
	v_mov_b32_e32 v25, v89
	v_mov_b32_e32 v26, v90
	v_mov_b32_e32 v27, v91
	v_mov_b32_e32 v28, v92
	v_mov_b32_e32 v29, v93
	v_mov_b32_e32 v30, v94
	v_mov_b32_e32 v31, v95
	v_mov_b32_e32 v32, v96
	v_mov_b32_e32 v33, v97
	v_mov_b32_e32 v34, v98
	v_mov_b32_e32 v35, v99
	v_mov_b32_e32 v36, v100
	v_mov_b32_e32 v37, v101
	v_mov_b32_e32 v38, v102
	v_mov_b32_e32 v39, v103
	v_mov_b32_e32 v40, v104
	v_mov_b32_e32 v41, v105
	v_mov_b32_e32 v42, v106
	v_mov_b32_e32 v43, v107
	v_mov_b32_e32 v44, v108
	v_mov_b32_e32 v45, v109
	v_mov_b32_e32 v46, v110
	v_mov_b32_e32 v47, v111
	v_mov_b32_e32 v48, v112
	v_mov_b32_e32 v49, v113
	v_mov_b32_e32 v50, v114
	v_mov_b32_e32 v51, v115
	v_mov_b32_e32 v52, v116
	v_mov_b32_e32 v53, v117
	v_mov_b32_e32 v54, v118
	v_mov_b32_e32 v55, v119
	v_mov_b32_e32 v56, v120
	v_mov_b32_e32 v57, v121
	v_mov_b32_e32 v58, v122
	v_mov_b32_e32 v59, v123
	v_mov_b32_e32 v60, v124
	v_mov_b32_e32 v61, v125
	v_mov_b32_e32 v62, v126
	v_mov_b32_e32 v63, v127
	s_mov_b32 s83, 1
	s_branch .Lp6d_ep
